# o58: o50 + back-edge SALU hoisted 8 MFMAs before the trip-end barrier (o54 used 4)
# baseline (speedup 1.0000x reference)
;     __device__ float mid(int row) const { return rg(row) / ra(row); }
;     __device__ __forceinline__ bool next(int i, Unit& u) const { return map(rank + i * nloc, u); }
;     __device__ __forceinline__ bool next(int i, Unit& u) const { if (i >= __builtin_amdgcn_readfirstlane(tab[0])) return false; u.pm = __builtin_amdgcn_readfirstlane(tab[1 + 2 * i]); u.pn = __builtin_amdgcn_readfirstlane(tab[2 + 2 * i]); return true; }
; #define PG8_LDA(dst, b, h) do { _Pragma("unroll") for (int m = 0; m < 4; ++m) _Pragma("unroll") for (int k = 0; k < 2; ++k) dst[m][k] = *(const PG8_LAS bf16x8*)(lds + PG8_SA(b, h) + aoff + m * 2048 + k * 1024); } while (0)
; #define PG8_WAIT_V(n) asm volatile("s_waitcnt vmcnt(" #n ")" ::: "memory")
; template <class Epi, class Sched, bool ALIGN_EPI = false, bool SP2 = false>
; __device__ __forceinline__ void gemm_phase(PG8_LAS unsigned char* lds, const Gemm g, const Sched& S, const Epi& E, int wid0) {
;     ...
;         const bool has_next = S.next(ui + 1, nxt); nxt.ui = ui + 1;
;         if constexpr (Epi::HAS_PRE) E.pre_finish(lds, cur, tid, pq0, pq1, pq2);
;         const char* nA = has_next ? (const char*)g.A + (size_t)nxt.pm * tstepA : cA; const char* nB = has_next ? (const char*)g.Bt + (size_t)nxt.pn * tstep : cB;
; #pragma nounroll
;         for (int t = 0; t < nt; t += 2) {
;             const bool last = (t == nt - 2);
;             const char* a1 = cA + (size_t)(t + 1) * kstep;
;             const char* a2 = last ? nA : cA + (size_t)(t + 2) * kstep; const char* b2 = last ? nB : cB + (size_t)(t + 2) * kstep;
;             const char* a3 = a2 + kstep; const char* b3 = b2 + kstep;
;             if (last && has_next) S.a_ready(nxt);
;             if constexpr (Epi::HAS_MID) { if (t == Epi::MID_T) E.mid(acc, cur, wr, fr); }
;             unsigned vA_[2] = {voffA[0], voffA[1]}, vB_[2] = {voffB[0], voffB[1]};
;             asm volatile("" : "+v"(vA_[0]), "+v"(vA_[1]), "+v"(vB_[0]), "+v"(vB_[1]));
;             if constexpr (SP2) {
;             PG8_LDB(B0, 0, 0); PG8_LDB(B1, 0, 1); PG8_SCHED; PG8_LDA(At, 0, 0); PG8_STAGE(PG8_SA(1, 1), a1 + hstepA, vA_);
;             PG8_WAIT_V(8); PG8_WAIT_L(0); PG8_BAR; PG8_MMA(0, 0, At, B0); PG8_MMA(0, 1, At, B1); PG8_BAR; PG8_SCHED;
;             PG8_LDA(At, 0, 1); PG8_STAGE(PG8_SB(0, 0), b2, vB_); PG8_STAGE(PG8_SB(0, 1), b2 + hstep, vB_); PG8_STAGE(PG8_SA(0, 0), a2, vA_);
.LBB13_358:
	v_mov_b32_e32 v8, v174
	v_mov_b32_e32 v220, v200
	v_mov_b32_e32 v221, v176
	v_mov_b32_e32 v222, v178
	ds_read_b128 v[82:85], v201
	ds_read_b128 v[90:93], v201 offset:1024
	ds_read_b128 v[94:97], v201 offset:2048
	ds_read_b128 v[102:105], v201 offset:3072
	ds_read_b128 v[158:161], v202
	ds_read_b128 v[162:165], v202 offset:1024
	ds_read_b128 v[166:169], v202 offset:2048
	ds_read_b128 v[170:173], v202 offset:3072
	s_add_u32 s8, s2, 0x100
	s_addc_u32 s9, s3, 0
	s_cmp_eq_u32 s82, 12
	s_cselect_b32 s58, s78, s8
	s_cselect_b32 s59, s47, s9
	s_cselect_b32 s12, s79, s80
	s_cselect_b32 s13, s49, s81
	s_add_u32 s10, s58, 0x80
	s_addc_u32 s11, s59, 0
	s_add_u32 s2, s2, 0x40080
	s_addc_u32 s3, s3, 0
	s_add_i32 m0, s57, 0xc000
	ds_read_b128 v[180:183], v203
	ds_read_b128 v[184:187], v203 offset:1024
	ds_read_b128 v[188:191], v203 offset:2048
	ds_read_b128 v[192:195], v203 offset:3072
	ds_read_b128 v[204:207], v203 offset:4096
	ds_read_b128 v[208:211], v203 offset:5120
	ds_read_b128 v[212:215], v203 offset:6144
	ds_read_b128 v[216:219], v203 offset:7168
	s_nop 0
	global_load_lds_dwordx4 v8, s[2:3]
	s_add_i32 m0, s57, 0xe000
	s_nop 0
	global_load_lds_dwordx4 v221, s[2:3]
	s_waitcnt vmcnt(8)
	s_waitcnt lgkmcnt(0)
	s_barrier
	s_setprio 1
	s_waitcnt lgkmcnt(0)
	v_mfma_f32_16x16x32_bf16 v[154:157], v[82:85], v[180:183], v[154:157]
	v_mfma_f32_16x16x32_bf16 v[150:153], v[94:97], v[180:183], v[150:153]
	v_mfma_f32_16x16x32_bf16 v[138:141], v[82:85], v[188:191], v[138:141]
	v_mfma_f32_16x16x32_bf16 v[134:137], v[94:97], v[188:191], v[134:137]
	v_mfma_f32_16x16x32_bf16 v[122:125], v[82:85], v[204:207], v[122:125]
	v_mfma_f32_16x16x32_bf16 v[118:121], v[94:97], v[204:207], v[118:121]
	v_mfma_f32_16x16x32_bf16 v[106:109], v[82:85], v[212:215], v[106:109]
	v_mfma_f32_16x16x32_bf16 v[98:101], v[94:97], v[212:215], v[98:101]
	v_mfma_f32_16x16x32_bf16 v[154:157], v[90:93], v[184:187], v[154:157]
	v_mfma_f32_16x16x32_bf16 v[150:153], v[102:105], v[184:187], v[150:153]
	v_mfma_f32_16x16x32_bf16 v[138:141], v[90:93], v[192:195], v[138:141]
	v_mfma_f32_16x16x32_bf16 v[134:137], v[102:105], v[192:195], v[134:137]
	v_mfma_f32_16x16x32_bf16 v[122:125], v[90:93], v[208:211], v[122:125]
	v_mfma_f32_16x16x32_bf16 v[118:121], v[102:105], v[208:211], v[118:121]
	v_mfma_f32_16x16x32_bf16 v[106:109], v[90:93], v[216:219], v[106:109]
	v_mfma_f32_16x16x32_bf16 v[98:101], v[102:105], v[216:219], v[98:101]
	s_setprio 0
	s_setprio 1
	v_mfma_f32_16x16x32_bf16 v[146:149], v[158:161], v[180:183], v[146:149]
	v_mfma_f32_16x16x32_bf16 v[142:145], v[166:169], v[180:183], v[142:145]
	v_mfma_f32_16x16x32_bf16 v[130:133], v[158:161], v[188:191], v[130:133]
	v_mfma_f32_16x16x32_bf16 v[126:129], v[166:169], v[188:191], v[126:129]
	v_mfma_f32_16x16x32_bf16 v[114:117], v[158:161], v[204:207], v[114:117]
	v_mfma_f32_16x16x32_bf16 v[110:113], v[166:169], v[204:207], v[110:113]
	v_mfma_f32_16x16x32_bf16 v[86:89], v[158:161], v[212:215], v[86:89]
	v_mfma_f32_16x16x32_bf16 v[78:81], v[166:169], v[212:215], v[78:81]
	v_mfma_f32_16x16x32_bf16 v[146:149], v[162:165], v[184:187], v[146:149]
	v_mfma_f32_16x16x32_bf16 v[142:145], v[170:173], v[184:187], v[142:145]
	v_mfma_f32_16x16x32_bf16 v[130:133], v[162:165], v[192:195], v[130:133]
	v_mfma_f32_16x16x32_bf16 v[126:129], v[170:173], v[192:195], v[126:129]
	v_mfma_f32_16x16x32_bf16 v[114:117], v[162:165], v[208:211], v[114:117]
	v_mfma_f32_16x16x32_bf16 v[110:113], v[170:173], v[208:211], v[110:113]
	v_mfma_f32_16x16x32_bf16 v[86:89], v[162:165], v[216:219], v[86:89]
	v_mfma_f32_16x16x32_bf16 v[78:81], v[170:173], v[216:219], v[78:81]
	s_setprio 0
	s_barrier
	s_add_i32 s83, s74, s55
	s_mov_b64 s[2:3], s[12:13]
	s_mov_b32 m0, s83
	ds_read_b128 v[180:183], v203 offset:16384
	ds_read_b128 v[184:187], v203 offset:17408
	ds_read_b128 v[188:191], v203 offset:18432
	ds_read_b128 v[192:195], v203 offset:19456
	ds_read_b128 v[204:207], v203 offset:20480
	ds_read_b128 v[208:211], v203 offset:21504
	ds_read_b128 v[212:215], v203 offset:22528
	ds_read_b128 v[216:219], v203 offset:23552
	s_nop 0
	global_load_lds_dwordx4 v220, s[2:3]
	s_add_i32 m0, s83, 0x2000
	s_nop 0
	global_load_lds_dwordx4 v222, s[2:3]
	s_add_u32 s2, s12, 0x40000
	s_addc_u32 s3, s13, 0
	s_add_i32 s83, s75, s55
	s_mov_b32 m0, s83
	s_nop 0
	global_load_lds_dwordx4 v220, s[2:3]
	s_add_i32 m0, s83, 0x2000
	s_nop 0
	global_load_lds_dwordx4 v222, s[2:3]
	s_mov_b64 s[2:3], s[58:59]
	s_mov_b32 m0, s57
	s_nop 0
	global_load_lds_dwordx4 v8, s[2:3]
	s_mov_b32 m0, s63
	s_nop 0
	global_load_lds_dwordx4 v221, s[2:3]
	s_waitcnt vmcnt(8)
	s_waitcnt lgkmcnt(0)
	s_barrier
; #define PG8_STAGE(bufoff, gbase, voff) do { const char* gb_ = (const char*)(gbase); asm volatile("" : "+s"(gb_));     \
;         _Pragma("unroll") for (int _i = 0; _i < 2; ++_i) \
;         __builtin_amdgcn_global_load_lds((const unsigned*)(gb_ + (voff)[_i]), (PG8_LAS unsigned*)(lds + (bufoff) + ldsw + _i * 8192), 16, 0, 0); } while (0)
; #define PG8_LDA(dst, b, h) do { _Pragma("unroll") for (int m = 0; m < 4; ++m) _Pragma("unroll") for (int k = 0; k < 2; ++k) dst[m][k] = *(const PG8_LAS bf16x8*)(lds + PG8_SA(b, h) + aoff + m * 2048 + k * 1024); } while (0)
; #define PG8_LDB(dst, b, h) do { _Pragma("unroll") for (int n = 0; n < 2; ++n) _Pragma("unroll") for (int k = 0; k < 2; ++k) dst[n][k] = *(const PG8_LAS bf16x8*)(lds + PG8_SB(b, h) + boff + n * 2048 + k * 1024); } while (0)
; #define PG8_MMA(ai, bj, At, Bt) do { __builtin_amdgcn_s_setprio(1); _Pragma("unroll") for (int m = 0; m < 4; ++m) _Pragma("unroll") for (int n = 0; n < 2; ++n) _Pragma("unroll") for (int k = 0; k < 2; ++k) \
;         acc[ai][bj][m][n] = __builtin_amdgcn_mfma_f32_16x16x32_bf16(Bt[n][k], At[m][k], acc[ai][bj][m][n], 0, 0, 0); __builtin_amdgcn_s_setprio(0); } while (0)
; #define PG8_WAIT_V(n) asm volatile("s_waitcnt vmcnt(" #n ")" ::: "memory")
; #define PG8_WAIT_L(n) asm volatile("s_waitcnt lgkmcnt(" #n ")" ::: "memory")
; #define PG8_BAR __builtin_amdgcn_s_barrier()
; #define PG8_SCHED __builtin_amdgcn_sched_barrier(0)
; template <class Epi, class Sched, bool ALIGN_EPI = false, bool SP2 = false>
; __device__ __forceinline__ void gemm_phase(PG8_LAS unsigned char* lds, const Gemm g, const Sched& S, const Epi& E, int wid0) {
;     ...
;             PG8_WAIT_V(8); PG8_WAIT_L(0); PG8_BAR; PG8_MMA(0, 0, At, B0); PG8_MMA(0, 1, At, B1); PG8_BAR; PG8_SCHED;
;             PG8_LDA(At, 0, 1); PG8_STAGE(PG8_SB(0, 0), b2, vB_); PG8_STAGE(PG8_SB(0, 1), b2 + hstep, vB_); PG8_STAGE(PG8_SA(0, 0), a2, vA_);
;             PG8_WAIT_V(8); PG8_WAIT_L(0); PG8_BAR; PG8_MMA(1, 0, At, B0); PG8_MMA(1, 1, At, B1); PG8_BAR; PG8_SCHED;
;             PG8_LDB(B0, 1, 0); PG8_LDB(B1, 1, 1); PG8_SCHED; PG8_LDA(At, 1, 0); PG8_STAGE(PG8_SA(0, 1), a2 + hstepA, vA_);
;             PG8_WAIT_V(8); PG8_WAIT_L(0); PG8_BAR; PG8_MMA(0, 0, At, B0); PG8_MMA(0, 1, At, B1); PG8_BAR; PG8_SCHED;
	s_setprio 1
	s_waitcnt lgkmcnt(0)
	v_mfma_f32_16x16x32_bf16 v[74:77], v[82:85], v[180:183], v[74:77]
	v_mfma_f32_16x16x32_bf16 v[70:73], v[94:97], v[180:183], v[70:73]
	v_mfma_f32_16x16x32_bf16 v[58:61], v[82:85], v[188:191], v[58:61]
	v_mfma_f32_16x16x32_bf16 v[54:57], v[94:97], v[188:191], v[54:57]
	v_mfma_f32_16x16x32_bf16 v[42:45], v[82:85], v[204:207], v[42:45]
	v_mfma_f32_16x16x32_bf16 v[38:41], v[94:97], v[204:207], v[38:41]
	v_mfma_f32_16x16x32_bf16 v[26:29], v[82:85], v[212:215], v[26:29]
	v_mfma_f32_16x16x32_bf16 v[22:25], v[94:97], v[212:215], v[22:25]
	v_mfma_f32_16x16x32_bf16 v[74:77], v[90:93], v[184:187], v[74:77]
	v_mfma_f32_16x16x32_bf16 v[70:73], v[102:105], v[184:187], v[70:73]
	v_mfma_f32_16x16x32_bf16 v[58:61], v[90:93], v[192:195], v[58:61]
	v_mfma_f32_16x16x32_bf16 v[54:57], v[102:105], v[192:195], v[54:57]
	v_mfma_f32_16x16x32_bf16 v[42:45], v[90:93], v[208:211], v[42:45]
	v_mfma_f32_16x16x32_bf16 v[38:41], v[102:105], v[208:211], v[38:41]
	v_mfma_f32_16x16x32_bf16 v[26:29], v[90:93], v[216:219], v[26:29]
	v_mfma_f32_16x16x32_bf16 v[22:25], v[102:105], v[216:219], v[22:25]
	s_setprio 0
	s_setprio 1
	v_mfma_f32_16x16x32_bf16 v[66:69], v[158:161], v[180:183], v[66:69]
	v_mfma_f32_16x16x32_bf16 v[62:65], v[166:169], v[180:183], v[62:65]
	v_mfma_f32_16x16x32_bf16 v[50:53], v[158:161], v[188:191], v[50:53]
	v_mfma_f32_16x16x32_bf16 v[46:49], v[166:169], v[188:191], v[46:49]
	v_mfma_f32_16x16x32_bf16 v[34:37], v[158:161], v[204:207], v[34:37]
	v_mfma_f32_16x16x32_bf16 v[30:33], v[166:169], v[204:207], v[30:33]
	v_mfma_f32_16x16x32_bf16 v[18:21], v[158:161], v[212:215], v[18:21]
	v_mfma_f32_16x16x32_bf16 v[14:17], v[166:169], v[212:215], v[14:17]
	v_mfma_f32_16x16x32_bf16 v[66:69], v[162:165], v[184:187], v[66:69]
	v_mfma_f32_16x16x32_bf16 v[62:65], v[170:173], v[184:187], v[62:65]
	v_mfma_f32_16x16x32_bf16 v[50:53], v[162:165], v[192:195], v[50:53]
	v_mfma_f32_16x16x32_bf16 v[46:49], v[170:173], v[192:195], v[46:49]
	v_mfma_f32_16x16x32_bf16 v[34:37], v[162:165], v[208:211], v[34:37]
	v_mfma_f32_16x16x32_bf16 v[30:33], v[170:173], v[208:211], v[30:33]
	v_mfma_f32_16x16x32_bf16 v[18:21], v[162:165], v[216:219], v[18:21]
	v_mfma_f32_16x16x32_bf16 v[14:17], v[170:173], v[216:219], v[14:17]
	s_setprio 0
	s_barrier
	s_add_i32 s83, 0, 0x18000
	s_add_i32 s84, 0, 0x1c000
	v_add_u32_e32 v102, s83, v175
	v_add_u32_e32 v170, s84, v175
	ds_read_b128 v[82:85], v102
	ds_read_b128 v[90:93], v102 offset:1024
	ds_read_b128 v[94:97], v102 offset:2048
	ds_read_b128 v[102:105], v102 offset:3072
	ds_read_b128 v[158:161], v170
	ds_read_b128 v[162:165], v170 offset:1024
	ds_read_b128 v[166:169], v170 offset:2048
	ds_read_b128 v[170:173], v170 offset:3072
	s_add_u32 s2, s58, 0x40000
	s_addc_u32 s3, s59, 0
	s_mov_b32 m0, s64
	ds_read_b128 v[180:183], v203 offset:32768
	ds_read_b128 v[184:187], v203 offset:33792
	ds_read_b128 v[188:191], v203 offset:34816
	ds_read_b128 v[192:195], v203 offset:35840
	ds_read_b128 v[204:207], v203 offset:36864
	ds_read_b128 v[208:211], v203 offset:37888
	ds_read_b128 v[212:215], v203 offset:38912
	ds_read_b128 v[216:219], v203 offset:39936
	s_nop 0
	global_load_lds_dwordx4 v8, s[2:3]
	s_mov_b32 m0, s65
	s_nop 0
	global_load_lds_dwordx4 v221, s[2:3]
	s_waitcnt vmcnt(8)
	s_waitcnt lgkmcnt(0)
	s_barrier
	s_setprio 1
	s_waitcnt lgkmcnt(0)
	v_mfma_f32_16x16x32_bf16 v[154:157], v[82:85], v[180:183], v[154:157]
	v_mfma_f32_16x16x32_bf16 v[150:153], v[94:97], v[180:183], v[150:153]
	v_mfma_f32_16x16x32_bf16 v[138:141], v[82:85], v[188:191], v[138:141]
	v_mfma_f32_16x16x32_bf16 v[134:137], v[94:97], v[188:191], v[134:137]
	v_mfma_f32_16x16x32_bf16 v[122:125], v[82:85], v[204:207], v[122:125]
	v_mfma_f32_16x16x32_bf16 v[118:121], v[94:97], v[204:207], v[118:121]
	v_mfma_f32_16x16x32_bf16 v[106:109], v[82:85], v[212:215], v[106:109]
	v_mfma_f32_16x16x32_bf16 v[98:101], v[94:97], v[212:215], v[98:101]
	v_mfma_f32_16x16x32_bf16 v[154:157], v[90:93], v[184:187], v[154:157]
	v_mfma_f32_16x16x32_bf16 v[150:153], v[102:105], v[184:187], v[150:153]
	v_mfma_f32_16x16x32_bf16 v[138:141], v[90:93], v[192:195], v[138:141]
	v_mfma_f32_16x16x32_bf16 v[134:137], v[102:105], v[192:195], v[134:137]
	v_mfma_f32_16x16x32_bf16 v[122:125], v[90:93], v[208:211], v[122:125]
	v_mfma_f32_16x16x32_bf16 v[118:121], v[102:105], v[208:211], v[118:121]
	v_mfma_f32_16x16x32_bf16 v[106:109], v[90:93], v[216:219], v[106:109]
	v_mfma_f32_16x16x32_bf16 v[98:101], v[102:105], v[216:219], v[98:101]
	s_setprio 0
	s_setprio 1
	v_mfma_f32_16x16x32_bf16 v[146:149], v[158:161], v[180:183], v[146:149]
	v_mfma_f32_16x16x32_bf16 v[142:145], v[166:169], v[180:183], v[142:145]
	v_mfma_f32_16x16x32_bf16 v[130:133], v[158:161], v[188:191], v[130:133]
	v_mfma_f32_16x16x32_bf16 v[126:129], v[166:169], v[188:191], v[126:129]
	v_mfma_f32_16x16x32_bf16 v[114:117], v[158:161], v[204:207], v[114:117]
	v_mfma_f32_16x16x32_bf16 v[110:113], v[166:169], v[204:207], v[110:113]
	v_mfma_f32_16x16x32_bf16 v[86:89], v[158:161], v[212:215], v[86:89]
	v_mfma_f32_16x16x32_bf16 v[78:81], v[166:169], v[212:215], v[78:81]
	v_mfma_f32_16x16x32_bf16 v[146:149], v[162:165], v[184:187], v[146:149]
	v_mfma_f32_16x16x32_bf16 v[142:145], v[170:173], v[184:187], v[142:145]
	v_mfma_f32_16x16x32_bf16 v[130:133], v[162:165], v[192:195], v[130:133]
	v_mfma_f32_16x16x32_bf16 v[126:129], v[170:173], v[192:195], v[126:129]
	v_mfma_f32_16x16x32_bf16 v[114:117], v[162:165], v[208:211], v[114:117]
	v_mfma_f32_16x16x32_bf16 v[110:113], v[170:173], v[208:211], v[110:113]
	v_mfma_f32_16x16x32_bf16 v[86:89], v[162:165], v[216:219], v[86:89]
	v_mfma_f32_16x16x32_bf16 v[78:81], v[170:173], v[216:219], v[78:81]
	s_setprio 0
	s_barrier
;     __device__ float mid(int row) const { return rg(row) / ra(row); }
; #define PG8_STAGE(bufoff, gbase, voff) do { const char* gb_ = (const char*)(gbase); asm volatile("" : "+s"(gb_));     \
;         _Pragma("unroll") for (int _i = 0; _i < 2; ++_i) \
;         __builtin_amdgcn_global_load_lds((const unsigned*)(gb_ + (voff)[_i]), (PG8_LAS unsigned*)(lds + (bufoff) + ldsw + _i * 8192), 16, 0, 0); } while (0)
; #define PG8_BAR __builtin_amdgcn_s_barrier()
; template <class Epi, class Sched, bool ALIGN_EPI = false, bool SP2 = false>
; __device__ __forceinline__ void gemm_phase(PG8_LAS unsigned char* lds, const Gemm g, const Sched& S, const Epi& E, int wid0) {
;     ...
;         for (int t = 0; t < nt; t += 2) {
;             const bool last = (t == nt - 2);
;             const char* a1 = cA + (size_t)(t + 1) * kstep;
;             const char* a2 = last ? nA : cA + (size_t)(t + 2) * kstep; const char* b2 = last ? nB : cB + (size_t)(t + 2) * kstep;
;             const char* a3 = a2 + kstep; const char* b3 = b2 + kstep;
;             if (last && has_next) S.a_ready(nxt);
;             if constexpr (Epi::HAS_MID) { if (t == Epi::MID_T) E.mid(acc, cur, wr, fr); }
;             unsigned vA_[2] = {voffA[0], voffA[1]}, vB_[2] = {voffB[0], voffB[1]};
;             asm volatile("" : "+v"(vA_[0]), "+v"(vA_[1]), "+v"(vB_[0]), "+v"(vB_[1]));
;             if constexpr (SP2) {
;             PG8_LDB(B0, 0, 0); PG8_LDB(B1, 0, 1); PG8_SCHED; PG8_LDA(At, 0, 0); PG8_STAGE(PG8_SA(1, 1), a1 + hstepA, vA_);
;             PG8_WAIT_V(8); PG8_WAIT_L(0); PG8_BAR; PG8_MMA(0, 0, At, B0); PG8_MMA(0, 1, At, B1); PG8_BAR; PG8_SCHED;
;             PG8_LDA(At, 0, 1); PG8_STAGE(PG8_SB(0, 0), b2, vB_); PG8_STAGE(PG8_SB(0, 1), b2 + hstep, vB_); PG8_STAGE(PG8_SA(0, 0), a2, vA_);
;             PG8_WAIT_V(8); PG8_WAIT_L(0); PG8_BAR; PG8_MMA(1, 0, At, B0); PG8_MMA(1, 1, At, B1); PG8_BAR; PG8_SCHED;
;             PG8_LDB(B0, 1, 0); PG8_LDB(B1, 1, 1); PG8_SCHED; PG8_LDA(At, 1, 0); PG8_STAGE(PG8_SA(0, 1), a2 + hstepA, vA_);
;             PG8_WAIT_V(8); PG8_WAIT_L(0); PG8_BAR; PG8_MMA(0, 0, At, B0); PG8_MMA(0, 1, At, B1); PG8_BAR; PG8_SCHED;
;             PG8_LDA(At, 1, 1); PG8_STAGE(PG8_SB(1, 0), b3, vB_); PG8_STAGE(PG8_SB(1, 1), b3 + hstep, vB_); PG8_STAGE(PG8_SA(1, 0), a3, vA_);
;             PG8_WAIT_V(8); PG8_WAIT_L(0); PG8_BAR; PG8_MMA(1, 0, At, B0); PG8_MMA(1, 1, At, B1); PG8_BAR; PG8_SCHED;
	s_add_u32 s2, s12, 0x80
	s_addc_u32 s3, s13, 0
	s_add_i32 s58, s83, s55
	s_mov_b32 m0, s58
	ds_read_b128 v[180:183], v203 offset:49152
	ds_read_b128 v[184:187], v203 offset:50176
	ds_read_b128 v[188:191], v203 offset:51200
	ds_read_b128 v[192:195], v203 offset:52224
	ds_read_b128 v[204:207], v203 offset:53248
	ds_read_b128 v[208:211], v203 offset:54272
	ds_read_b128 v[212:215], v203 offset:55296
	ds_read_b128 v[216:219], v203 offset:56320
	s_nop 0
	global_load_lds_dwordx4 v220, s[2:3]
	s_add_i32 m0, s58, 0x2000
	s_nop 0
	global_load_lds_dwordx4 v222, s[2:3]
	s_add_u32 s2, s12, 0x40080
	s_addc_u32 s3, s13, 0
	s_add_i32 s12, s84, s55
	s_mov_b32 m0, s12
	s_nop 0
	global_load_lds_dwordx4 v220, s[2:3]
	s_add_i32 m0, s12, 0x2000
	s_nop 0
	global_load_lds_dwordx4 v222, s[2:3]
	s_mov_b32 m0, s68
	s_nop 0
	global_load_lds_dwordx4 v8, s[10:11]
	s_mov_b32 m0, s69
	s_nop 0
	global_load_lds_dwordx4 v221, s[10:11]
	s_waitcnt vmcnt(8)
	s_waitcnt lgkmcnt(0)
	s_barrier
	s_setprio 1
	s_waitcnt lgkmcnt(0)
	v_mfma_f32_16x16x32_bf16 v[74:77], v[82:85], v[180:183], v[74:77]
	v_mfma_f32_16x16x32_bf16 v[70:73], v[94:97], v[180:183], v[70:73]
	v_mfma_f32_16x16x32_bf16 v[58:61], v[82:85], v[188:191], v[58:61]
	v_mfma_f32_16x16x32_bf16 v[54:57], v[94:97], v[188:191], v[54:57]
	v_mfma_f32_16x16x32_bf16 v[42:45], v[82:85], v[204:207], v[42:45]
	v_mfma_f32_16x16x32_bf16 v[38:41], v[94:97], v[204:207], v[38:41]
	v_mfma_f32_16x16x32_bf16 v[26:29], v[82:85], v[212:215], v[26:29]
	v_mfma_f32_16x16x32_bf16 v[22:25], v[94:97], v[212:215], v[22:25]
	v_mfma_f32_16x16x32_bf16 v[74:77], v[90:93], v[184:187], v[74:77]
	v_mfma_f32_16x16x32_bf16 v[70:73], v[102:105], v[184:187], v[70:73]
	v_mfma_f32_16x16x32_bf16 v[58:61], v[90:93], v[192:195], v[58:61]
	v_mfma_f32_16x16x32_bf16 v[54:57], v[102:105], v[192:195], v[54:57]
	v_mfma_f32_16x16x32_bf16 v[42:45], v[90:93], v[208:211], v[42:45]
	v_mfma_f32_16x16x32_bf16 v[38:41], v[102:105], v[208:211], v[38:41]
	v_mfma_f32_16x16x32_bf16 v[26:29], v[90:93], v[216:219], v[26:29]
	v_mfma_f32_16x16x32_bf16 v[22:25], v[102:105], v[216:219], v[22:25]
	s_setprio 0
	s_setprio 1
	v_mfma_f32_16x16x32_bf16 v[66:69], v[158:161], v[180:183], v[66:69]
	v_mfma_f32_16x16x32_bf16 v[62:65], v[166:169], v[180:183], v[62:65]
	v_mfma_f32_16x16x32_bf16 v[50:53], v[158:161], v[188:191], v[50:53]
	v_mfma_f32_16x16x32_bf16 v[46:49], v[166:169], v[188:191], v[46:49]
	v_mfma_f32_16x16x32_bf16 v[34:37], v[158:161], v[204:207], v[34:37]
	v_mfma_f32_16x16x32_bf16 v[30:33], v[166:169], v[204:207], v[30:33]
	v_mfma_f32_16x16x32_bf16 v[18:21], v[158:161], v[212:215], v[18:21]
	v_mfma_f32_16x16x32_bf16 v[14:17], v[166:169], v[212:215], v[14:17]
	s_add_i32 s82, s82, 2
	s_add_u32 s80, s80, 0x100
	s_addc_u32 s81, s81, 0
	s_cmp_gt_u32 s82, 13
	s_mov_b64 s[2:3], s[8:9]
	v_mfma_f32_16x16x32_bf16 v[66:69], v[162:165], v[184:187], v[66:69]
	v_mfma_f32_16x16x32_bf16 v[62:65], v[170:173], v[184:187], v[62:65]
	v_mfma_f32_16x16x32_bf16 v[50:53], v[162:165], v[192:195], v[50:53]
	v_mfma_f32_16x16x32_bf16 v[46:49], v[170:173], v[192:195], v[46:49]
	v_mfma_f32_16x16x32_bf16 v[34:37], v[162:165], v[208:211], v[34:37]
	v_mfma_f32_16x16x32_bf16 v[30:33], v[170:173], v[208:211], v[30:33]
	v_mfma_f32_16x16x32_bf16 v[18:21], v[162:165], v[216:219], v[18:21]
	v_mfma_f32_16x16x32_bf16 v[14:17], v[170:173], v[216:219], v[14:17]
	s_setprio 0
	s_barrier
	s_cbranch_scc0 .LBB13_358
	s_and_b64 vcc, exec, s[42:43]
	s_cbranch_vccz .LBB13_361
	s_barrier

;     __device__ float mid(int row) const { return rg(row) / ra(row); }
; #define PG8_STAGE(bufoff, gbase, voff) do { const char* gb_ = (const char*)(gbase); asm volatile("" : "+s"(gb_));     \
;         _Pragma("unroll") for (int _i = 0; _i < 2; ++_i) \
;         __builtin_amdgcn_global_load_lds((const unsigned*)(gb_ + (voff)[_i]), (PG8_LAS unsigned*)(lds + (bufoff) + ldsw + _i * 8192), 16, 0, 0); } while (0)
; #define PG8_LDA(dst, b, h) do { _Pragma("unroll") for (int m = 0; m < 4; ++m) _Pragma("unroll") for (int k = 0; k < 2; ++k) dst[m][k] = *(const PG8_LAS bf16x8*)(lds + PG8_SA(b, h) + aoff + m * 2048 + k * 1024); } while (0)
; #define PG8_LDB(dst, b, h) do { _Pragma("unroll") for (int n = 0; n < 2; ++n) _Pragma("unroll") for (int k = 0; k < 2; ++k) dst[n][k] = *(const PG8_LAS bf16x8*)(lds + PG8_SB(b, h) + boff + n * 2048 + k * 1024); } while (0)
; #define PG8_WAIT_V(n) asm volatile("s_waitcnt vmcnt(" #n ")" ::: "memory")
; template <class Epi, class Sched, bool ALIGN_EPI = false, bool SP2 = false>
; __device__ __forceinline__ void gemm_phase(PG8_LAS unsigned char* lds, const Gemm g, const Sched& S, const Epi& E, int wid0) {
;     ...
;         for (int t = 0; t < nt; t += 2) {
;             const bool last = (t == nt - 2);
;             const char* a1 = cA + (size_t)(t + 1) * kstep;
;             const char* a2 = last ? nA : cA + (size_t)(t + 2) * kstep; const char* b2 = last ? nB : cB + (size_t)(t + 2) * kstep;
;             const char* a3 = a2 + kstep; const char* b3 = b2 + kstep;
;             if (last && has_next) S.a_ready(nxt);
;             if constexpr (Epi::HAS_MID) { if (t == Epi::MID_T) E.mid(acc, cur, wr, fr); }
;             unsigned vA_[2] = {voffA[0], voffA[1]}, vB_[2] = {voffB[0], voffB[1]};
;             asm volatile("" : "+v"(vA_[0]), "+v"(vA_[1]), "+v"(vB_[0]), "+v"(vB_[1]));
;             if constexpr (SP2) {
;             PG8_LDB(B0, 0, 0); PG8_LDB(B1, 0, 1); PG8_SCHED; PG8_LDA(At, 0, 0); PG8_STAGE(PG8_SA(1, 1), a1 + hstepA, vA_);
;             PG8_WAIT_V(8); PG8_WAIT_L(0); PG8_BAR; PG8_MMA(0, 0, At, B0); PG8_MMA(0, 1, At, B1); PG8_BAR; PG8_SCHED;
;             PG8_LDA(At, 0, 1); PG8_STAGE(PG8_SB(0, 0), b2, vB_); PG8_STAGE(PG8_SB(0, 1), b2 + hstep, vB_); PG8_STAGE(PG8_SA(0, 0), a2, vA_);
;             PG8_WAIT_V(8); PG8_WAIT_L(0); PG8_BAR; PG8_MMA(1, 0, At, B0); PG8_MMA(1, 1, At, B1); PG8_BAR; PG8_SCHED;
.LBB13_942:
	v_mov_b32_e32 v9, v160
	v_mov_b32_e32 v154, v162
	v_mov_b32_e32 v155, v156
	v_mov_b32_e32 v166, v158
	v_add_u32_e32 v10, s64, v157
	ds_read_b128 v[142:145], v10
	ds_read_b128 v[146:149], v10 offset:1024
	ds_read_b128 v[150:153], v10 offset:2048
	ds_read_b128 v[168:171], v10 offset:3072
	v_add_u32_e32 v10, s65, v157
	s_add_u32 s6, s42, 0x100
	ds_read_b128 v[172:175], v10
	ds_read_b128 v[176:179], v10 offset:1024
	ds_read_b128 v[180:183], v10 offset:2048
	ds_read_b128 v[184:187], v10 offset:3072
	s_addc_u32 s7, s43, 0
	s_cmp_eq_u32 s70, 12
	s_cselect_b32 s50, s35, s6
	s_cselect_b32 s51, s29, s7
	s_cselect_b32 s45, s31, s69
	s_cselect_b32 s44, s67, s68
	s_add_u32 s46, s50, 0x80
	s_addc_u32 s47, s51, 0
	s_add_u32 s48, s44, 0x80
	s_addc_u32 s49, s45, 0
	s_add_u32 s42, s42, 0x80080
	s_addc_u32 s43, s43, 0
	s_add_i32 m0, s13, 0xc000
	ds_read_b128 v[188:191], v167
	ds_read_b128 v[192:195], v167 offset:1024
	ds_read_b128 v[196:199], v167 offset:2048
	ds_read_b128 v[200:203], v167 offset:3072
	ds_read_b128 v[204:207], v167 offset:4096
	ds_read_b128 v[208:211], v167 offset:5120
	ds_read_b128 v[212:215], v167 offset:6144
	ds_read_b128 v[216:219], v167 offset:7168
	s_nop 0
	global_load_lds_dwordx4 v155, s[42:43]
	s_add_i32 m0, s13, 0xe000
	s_nop 0
	global_load_lds_dwordx4 v9, s[42:43]
	s_waitcnt vmcnt(8)
	s_waitcnt lgkmcnt(0)
	s_barrier
	s_setprio 1
	s_waitcnt lgkmcnt(0)
	v_mfma_f32_16x16x32_bf16 v[136:139], v[142:145], v[188:191], v[136:139]
	v_mfma_f32_16x16x32_bf16 v[132:135], v[150:153], v[188:191], v[132:135]
	v_mfma_f32_16x16x32_bf16 v[128:131], v[142:145], v[196:199], v[128:131]
	v_mfma_f32_16x16x32_bf16 v[124:127], v[150:153], v[196:199], v[124:127]
	v_mfma_f32_16x16x32_bf16 v[120:123], v[142:145], v[204:207], v[120:123]
	v_mfma_f32_16x16x32_bf16 v[116:119], v[150:153], v[204:207], v[116:119]
	v_mfma_f32_16x16x32_bf16 v[112:115], v[142:145], v[212:215], v[112:115]
	v_mfma_f32_16x16x32_bf16 v[108:111], v[150:153], v[212:215], v[108:111]
	v_mfma_f32_16x16x32_bf16 v[136:139], v[146:149], v[192:195], v[136:139]
	v_mfma_f32_16x16x32_bf16 v[132:135], v[168:171], v[192:195], v[132:135]
	v_mfma_f32_16x16x32_bf16 v[128:131], v[146:149], v[200:203], v[128:131]
	v_mfma_f32_16x16x32_bf16 v[124:127], v[168:171], v[200:203], v[124:127]
	v_mfma_f32_16x16x32_bf16 v[120:123], v[146:149], v[208:211], v[120:123]
	v_mfma_f32_16x16x32_bf16 v[116:119], v[168:171], v[208:211], v[116:119]
	v_mfma_f32_16x16x32_bf16 v[112:115], v[146:149], v[216:219], v[112:115]
	v_mfma_f32_16x16x32_bf16 v[108:111], v[168:171], v[216:219], v[108:111]
	s_setprio 0
	s_setprio 1
	v_mfma_f32_16x16x32_bf16 v[72:75], v[172:175], v[188:191], v[72:75]
	v_mfma_f32_16x16x32_bf16 v[68:71], v[180:183], v[188:191], v[68:71]
	v_mfma_f32_16x16x32_bf16 v[64:67], v[172:175], v[196:199], v[64:67]
	v_mfma_f32_16x16x32_bf16 v[60:63], v[180:183], v[196:199], v[60:63]
	v_mfma_f32_16x16x32_bf16 v[56:59], v[172:175], v[204:207], v[56:59]
	v_mfma_f32_16x16x32_bf16 v[52:55], v[180:183], v[204:207], v[52:55]
	v_mfma_f32_16x16x32_bf16 v[48:51], v[172:175], v[212:215], v[48:51]
	v_mfma_f32_16x16x32_bf16 v[44:47], v[180:183], v[212:215], v[44:47]
	v_mfma_f32_16x16x32_bf16 v[72:75], v[176:179], v[192:195], v[72:75]
	v_mfma_f32_16x16x32_bf16 v[68:71], v[184:187], v[192:195], v[68:71]
	v_mfma_f32_16x16x32_bf16 v[64:67], v[176:179], v[200:203], v[64:67]
	v_mfma_f32_16x16x32_bf16 v[60:63], v[184:187], v[200:203], v[60:63]
	v_mfma_f32_16x16x32_bf16 v[56:59], v[176:179], v[208:211], v[56:59]
	v_mfma_f32_16x16x32_bf16 v[52:55], v[184:187], v[208:211], v[52:55]
	v_mfma_f32_16x16x32_bf16 v[48:51], v[176:179], v[216:219], v[48:51]
	v_mfma_f32_16x16x32_bf16 v[44:47], v[184:187], v[216:219], v[44:47]
	s_setprio 0
	s_barrier
	s_add_i32 s71, s64, s27
	s_mov_b64 s[42:43], s[44:45]
	s_mov_b32 m0, s71
	ds_read_b128 v[188:191], v167 offset:16384
	ds_read_b128 v[192:195], v167 offset:17408
	ds_read_b128 v[196:199], v167 offset:18432
	ds_read_b128 v[200:203], v167 offset:19456
	ds_read_b128 v[204:207], v167 offset:20480
	ds_read_b128 v[208:211], v167 offset:21504
	ds_read_b128 v[212:215], v167 offset:22528
	ds_read_b128 v[216:219], v167 offset:23552
	s_nop 0
	global_load_lds_dwordx4 v166, s[42:43]
	s_add_i32 m0, s71, 0x2000
	s_nop 0
	global_load_lds_dwordx4 v154, s[42:43]
	s_add_u32 s42, s44, 0x40000
	s_addc_u32 s43, s45, 0
	s_add_i32 s71, s65, s27
	s_mov_b32 m0, s71
	s_nop 0
	global_load_lds_dwordx4 v166, s[42:43]
	s_add_i32 m0, s71, 0x2000
	s_nop 0
	global_load_lds_dwordx4 v154, s[42:43]
	s_mov_b64 s[42:43], s[50:51]
	s_mov_b32 m0, s13
	s_nop 0
	global_load_lds_dwordx4 v155, s[42:43]
	s_mov_b32 m0, s53
	s_nop 0
	global_load_lds_dwordx4 v9, s[42:43]
	s_waitcnt vmcnt(8)
	s_waitcnt lgkmcnt(0)
	s_barrier
; #define PG8_STAGE(bufoff, gbase, voff) do { const char* gb_ = (const char*)(gbase); asm volatile("" : "+s"(gb_));     \
;         _Pragma("unroll") for (int _i = 0; _i < 2; ++_i) \
;         __builtin_amdgcn_global_load_lds((const unsigned*)(gb_ + (voff)[_i]), (PG8_LAS unsigned*)(lds + (bufoff) + ldsw + _i * 8192), 16, 0, 0); } while (0)
; #define PG8_LDA(dst, b, h) do { _Pragma("unroll") for (int m = 0; m < 4; ++m) _Pragma("unroll") for (int k = 0; k < 2; ++k) dst[m][k] = *(const PG8_LAS bf16x8*)(lds + PG8_SA(b, h) + aoff + m * 2048 + k * 1024); } while (0)
; #define PG8_LDB(dst, b, h) do { _Pragma("unroll") for (int n = 0; n < 2; ++n) _Pragma("unroll") for (int k = 0; k < 2; ++k) dst[n][k] = *(const PG8_LAS bf16x8*)(lds + PG8_SB(b, h) + boff + n * 2048 + k * 1024); } while (0)
; #define PG8_MMA(ai, bj, At, Bt) do { __builtin_amdgcn_s_setprio(1); _Pragma("unroll") for (int m = 0; m < 4; ++m) _Pragma("unroll") for (int n = 0; n < 2; ++n) _Pragma("unroll") for (int k = 0; k < 2; ++k) \
;         acc[ai][bj][m][n] = __builtin_amdgcn_mfma_f32_16x16x32_bf16(Bt[n][k], At[m][k], acc[ai][bj][m][n], 0, 0, 0); __builtin_amdgcn_s_setprio(0); } while (0)
; #define PG8_WAIT_V(n) asm volatile("s_waitcnt vmcnt(" #n ")" ::: "memory")
; #define PG8_WAIT_L(n) asm volatile("s_waitcnt lgkmcnt(" #n ")" ::: "memory")
; #define PG8_BAR __builtin_amdgcn_s_barrier()
; #define PG8_SCHED __builtin_amdgcn_sched_barrier(0)
; template <class Epi, class Sched, bool ALIGN_EPI = false, bool SP2 = false>
; __device__ __forceinline__ void gemm_phase(PG8_LAS unsigned char* lds, const Gemm g, const Sched& S, const Epi& E, int wid0) {
;     ...
;             PG8_WAIT_V(8); PG8_WAIT_L(0); PG8_BAR; PG8_MMA(1, 0, At, B0); PG8_MMA(1, 1, At, B1); PG8_BAR; PG8_SCHED;
;             PG8_LDB(B0, 1, 0); PG8_LDB(B1, 1, 1); PG8_SCHED; PG8_LDA(At, 1, 0); PG8_STAGE(PG8_SA(0, 1), a2 + hstepA, vA_);
;             PG8_WAIT_V(8); PG8_WAIT_L(0); PG8_BAR; PG8_MMA(0, 0, At, B0); PG8_MMA(0, 1, At, B1); PG8_BAR; PG8_SCHED;
	s_setprio 1
	s_waitcnt lgkmcnt(0)
	v_mfma_f32_16x16x32_bf16 v[104:107], v[142:145], v[188:191], v[104:107]
	v_mfma_f32_16x16x32_bf16 v[100:103], v[150:153], v[188:191], v[100:103]
	v_mfma_f32_16x16x32_bf16 v[96:99], v[142:145], v[196:199], v[96:99]
	v_mfma_f32_16x16x32_bf16 v[92:95], v[150:153], v[196:199], v[92:95]
	v_mfma_f32_16x16x32_bf16 v[88:91], v[142:145], v[204:207], v[88:91]
	v_mfma_f32_16x16x32_bf16 v[84:87], v[150:153], v[204:207], v[84:87]
	v_mfma_f32_16x16x32_bf16 v[80:83], v[142:145], v[212:215], v[80:83]
	v_mfma_f32_16x16x32_bf16 v[76:79], v[150:153], v[212:215], v[76:79]
	v_mfma_f32_16x16x32_bf16 v[104:107], v[146:149], v[192:195], v[104:107]
	v_mfma_f32_16x16x32_bf16 v[100:103], v[168:171], v[192:195], v[100:103]
	v_mfma_f32_16x16x32_bf16 v[96:99], v[146:149], v[200:203], v[96:99]
	v_mfma_f32_16x16x32_bf16 v[92:95], v[168:171], v[200:203], v[92:95]
	v_mfma_f32_16x16x32_bf16 v[88:91], v[146:149], v[208:211], v[88:91]
	v_mfma_f32_16x16x32_bf16 v[84:87], v[168:171], v[208:211], v[84:87]
	v_mfma_f32_16x16x32_bf16 v[80:83], v[146:149], v[216:219], v[80:83]
	v_mfma_f32_16x16x32_bf16 v[76:79], v[168:171], v[216:219], v[76:79]
	s_setprio 0
	s_setprio 1
	v_mfma_f32_16x16x32_bf16 v[40:43], v[172:175], v[188:191], v[40:43]
	v_mfma_f32_16x16x32_bf16 v[36:39], v[180:183], v[188:191], v[36:39]
	v_mfma_f32_16x16x32_bf16 v[32:35], v[172:175], v[196:199], v[32:35]
	v_mfma_f32_16x16x32_bf16 v[28:31], v[180:183], v[196:199], v[28:31]
	v_mfma_f32_16x16x32_bf16 v[24:27], v[172:175], v[204:207], v[24:27]
	v_mfma_f32_16x16x32_bf16 v[20:23], v[180:183], v[204:207], v[20:23]
	v_mfma_f32_16x16x32_bf16 v[16:19], v[172:175], v[212:215], v[16:19]
	v_mfma_f32_16x16x32_bf16 v[10:13], v[180:183], v[212:215], v[12:15]
	v_mfma_f32_16x16x32_bf16 v[40:43], v[176:179], v[192:195], v[40:43]
	v_mfma_f32_16x16x32_bf16 v[36:39], v[184:187], v[192:195], v[36:39]
	v_mfma_f32_16x16x32_bf16 v[32:35], v[176:179], v[200:203], v[32:35]
	v_mfma_f32_16x16x32_bf16 v[28:31], v[184:187], v[200:203], v[28:31]
	v_mfma_f32_16x16x32_bf16 v[24:27], v[176:179], v[208:211], v[24:27]
	v_mfma_f32_16x16x32_bf16 v[20:23], v[184:187], v[208:211], v[20:23]
	v_mfma_f32_16x16x32_bf16 v[16:19], v[176:179], v[216:219], v[16:19]
	v_mfma_f32_16x16x32_bf16 v[10:13], v[184:187], v[216:219], v[10:13]
	s_setprio 0
	s_barrier
	s_add_i32 s71, 0, 0x18000
	v_add_u32_e32 v14, s71, v157
	s_add_i32 s72, 0, 0x1c000
	ds_read_b128 v[142:145], v14
	ds_read_b128 v[146:149], v14 offset:1024
	ds_read_b128 v[150:153], v14 offset:2048
	ds_read_b128 v[168:171], v14 offset:3072
	v_add_u32_e32 v14, s72, v157
	ds_read_b128 v[172:175], v14
	ds_read_b128 v[176:179], v14 offset:1024
	ds_read_b128 v[180:183], v14 offset:2048
	ds_read_b128 v[184:187], v14 offset:3072
	s_add_u32 s42, s50, 0x80000
	s_addc_u32 s43, s51, 0
	s_mov_b32 m0, s54
	ds_read_b128 v[188:191], v167 offset:32768
	ds_read_b128 v[192:195], v167 offset:33792
	ds_read_b128 v[196:199], v167 offset:34816
	ds_read_b128 v[200:203], v167 offset:35840
	ds_read_b128 v[204:207], v167 offset:36864
	ds_read_b128 v[208:211], v167 offset:37888
	ds_read_b128 v[212:215], v167 offset:38912
	ds_read_b128 v[216:219], v167 offset:39936
	s_nop 0
	global_load_lds_dwordx4 v155, s[42:43]
	s_mov_b32 m0, s55
	s_nop 0
	global_load_lds_dwordx4 v9, s[42:43]
	s_waitcnt vmcnt(8)
	s_waitcnt lgkmcnt(0)
	s_barrier
	s_setprio 1
	s_waitcnt lgkmcnt(0)
	v_mfma_f32_16x16x32_bf16 v[136:139], v[142:145], v[188:191], v[136:139]
	v_mfma_f32_16x16x32_bf16 v[132:135], v[150:153], v[188:191], v[132:135]
	v_mfma_f32_16x16x32_bf16 v[128:131], v[142:145], v[196:199], v[128:131]
	v_mfma_f32_16x16x32_bf16 v[124:127], v[150:153], v[196:199], v[124:127]
	v_mfma_f32_16x16x32_bf16 v[120:123], v[142:145], v[204:207], v[120:123]
	v_mfma_f32_16x16x32_bf16 v[116:119], v[150:153], v[204:207], v[116:119]
	v_mfma_f32_16x16x32_bf16 v[112:115], v[142:145], v[212:215], v[112:115]
	v_mfma_f32_16x16x32_bf16 v[108:111], v[150:153], v[212:215], v[108:111]
	v_mfma_f32_16x16x32_bf16 v[136:139], v[146:149], v[192:195], v[136:139]
	v_mfma_f32_16x16x32_bf16 v[132:135], v[168:171], v[192:195], v[132:135]
	v_mfma_f32_16x16x32_bf16 v[128:131], v[146:149], v[200:203], v[128:131]
	v_mfma_f32_16x16x32_bf16 v[124:127], v[168:171], v[200:203], v[124:127]
	v_mfma_f32_16x16x32_bf16 v[120:123], v[146:149], v[208:211], v[120:123]
	v_mfma_f32_16x16x32_bf16 v[116:119], v[168:171], v[208:211], v[116:119]
	v_mfma_f32_16x16x32_bf16 v[112:115], v[146:149], v[216:219], v[112:115]
	v_mfma_f32_16x16x32_bf16 v[108:111], v[168:171], v[216:219], v[108:111]
	s_setprio 0
	s_setprio 1
	v_mfma_f32_16x16x32_bf16 v[72:75], v[172:175], v[188:191], v[72:75]
	v_mfma_f32_16x16x32_bf16 v[68:71], v[180:183], v[188:191], v[68:71]
	v_mfma_f32_16x16x32_bf16 v[64:67], v[172:175], v[196:199], v[64:67]
	v_mfma_f32_16x16x32_bf16 v[60:63], v[180:183], v[196:199], v[60:63]
	v_mfma_f32_16x16x32_bf16 v[56:59], v[172:175], v[204:207], v[56:59]
	v_mfma_f32_16x16x32_bf16 v[52:55], v[180:183], v[204:207], v[52:55]
	v_mfma_f32_16x16x32_bf16 v[48:51], v[172:175], v[212:215], v[48:51]
	v_mfma_f32_16x16x32_bf16 v[44:47], v[180:183], v[212:215], v[44:47]
	v_mfma_f32_16x16x32_bf16 v[72:75], v[176:179], v[192:195], v[72:75]
	v_mfma_f32_16x16x32_bf16 v[68:71], v[184:187], v[192:195], v[68:71]
	v_mfma_f32_16x16x32_bf16 v[64:67], v[176:179], v[200:203], v[64:67]
	v_mfma_f32_16x16x32_bf16 v[60:63], v[184:187], v[200:203], v[60:63]
	v_mfma_f32_16x16x32_bf16 v[56:59], v[176:179], v[208:211], v[56:59]
	v_mfma_f32_16x16x32_bf16 v[52:55], v[184:187], v[208:211], v[52:55]
	v_mfma_f32_16x16x32_bf16 v[48:51], v[176:179], v[216:219], v[48:51]
	v_mfma_f32_16x16x32_bf16 v[44:47], v[184:187], v[216:219], v[44:47]
	s_setprio 0
	s_barrier
;     __device__ float mid(int row) const { return rg(row) / ra(row); }
; #define PG8_STAGE(bufoff, gbase, voff) do { const char* gb_ = (const char*)(gbase); asm volatile("" : "+s"(gb_));     \
;         _Pragma("unroll") for (int _i = 0; _i < 2; ++_i) \
;         __builtin_amdgcn_global_load_lds((const unsigned*)(gb_ + (voff)[_i]), (PG8_LAS unsigned*)(lds + (bufoff) + ldsw + _i * 8192), 16, 0, 0); } while (0)
; #define PG8_BAR __builtin_amdgcn_s_barrier()
; template <class Epi, class Sched, bool ALIGN_EPI = false, bool SP2 = false>
; __device__ __forceinline__ void gemm_phase(PG8_LAS unsigned char* lds, const Gemm g, const Sched& S, const Epi& E, int wid0) {
;     ...
;         for (int t = 0; t < nt; t += 2) {
;             const bool last = (t == nt - 2);
;             const char* a1 = cA + (size_t)(t + 1) * kstep;
;             const char* a2 = last ? nA : cA + (size_t)(t + 2) * kstep; const char* b2 = last ? nB : cB + (size_t)(t + 2) * kstep;
;             const char* a3 = a2 + kstep; const char* b3 = b2 + kstep;
;             if (last && has_next) S.a_ready(nxt);
;             if constexpr (Epi::HAS_MID) { if (t == Epi::MID_T) E.mid(acc, cur, wr, fr); }
;             unsigned vA_[2] = {voffA[0], voffA[1]}, vB_[2] = {voffB[0], voffB[1]};
;             asm volatile("" : "+v"(vA_[0]), "+v"(vA_[1]), "+v"(vB_[0]), "+v"(vB_[1]));
;             if constexpr (SP2) {
;             PG8_LDB(B0, 0, 0); PG8_LDB(B1, 0, 1); PG8_SCHED; PG8_LDA(At, 0, 0); PG8_STAGE(PG8_SA(1, 1), a1 + hstepA, vA_);
;             PG8_WAIT_V(8); PG8_WAIT_L(0); PG8_BAR; PG8_MMA(0, 0, At, B0); PG8_MMA(0, 1, At, B1); PG8_BAR; PG8_SCHED;
;             PG8_LDA(At, 0, 1); PG8_STAGE(PG8_SB(0, 0), b2, vB_); PG8_STAGE(PG8_SB(0, 1), b2 + hstep, vB_); PG8_STAGE(PG8_SA(0, 0), a2, vA_);
;             PG8_WAIT_V(8); PG8_WAIT_L(0); PG8_BAR; PG8_MMA(1, 0, At, B0); PG8_MMA(1, 1, At, B1); PG8_BAR; PG8_SCHED;
;             PG8_LDB(B0, 1, 0); PG8_LDB(B1, 1, 1); PG8_SCHED; PG8_LDA(At, 1, 0); PG8_STAGE(PG8_SA(0, 1), a2 + hstepA, vA_);
;             PG8_WAIT_V(8); PG8_WAIT_L(0); PG8_BAR; PG8_MMA(0, 0, At, B0); PG8_MMA(0, 1, At, B1); PG8_BAR; PG8_SCHED;
;             PG8_LDA(At, 1, 1); PG8_STAGE(PG8_SB(1, 0), b3, vB_); PG8_STAGE(PG8_SB(1, 1), b3 + hstep, vB_); PG8_STAGE(PG8_SA(1, 0), a3, vA_);
;             PG8_WAIT_V(8); PG8_WAIT_L(0); PG8_BAR; PG8_MMA(1, 0, At, B0); PG8_MMA(1, 1, At, B1); PG8_BAR; PG8_SCHED;
	s_add_i32 s42, s71, s27
	s_mov_b32 m0, s42
	ds_read_b128 v[188:191], v167 offset:49152
	ds_read_b128 v[192:195], v167 offset:50176
	ds_read_b128 v[196:199], v167 offset:51200
	ds_read_b128 v[200:203], v167 offset:52224
	ds_read_b128 v[204:207], v167 offset:53248
	ds_read_b128 v[208:211], v167 offset:54272
	ds_read_b128 v[212:215], v167 offset:55296
	ds_read_b128 v[216:219], v167 offset:56320
	s_nop 0
	global_load_lds_dwordx4 v166, s[48:49]
	s_add_i32 m0, s42, 0x2000
	s_add_u32 s42, s44, 0x40080
	s_addc_u32 s43, s45, 0
	s_add_i32 s44, s72, s27
	global_load_lds_dwordx4 v154, s[48:49]
	s_mov_b32 m0, s44
	s_nop 0
	global_load_lds_dwordx4 v166, s[42:43]
	s_add_i32 m0, s44, 0x2000
	s_nop 0
	global_load_lds_dwordx4 v154, s[42:43]
	s_mov_b32 m0, s59
	s_nop 0
	global_load_lds_dwordx4 v155, s[46:47]
	s_mov_b32 m0, s60
	s_nop 0
	global_load_lds_dwordx4 v9, s[46:47]
	s_waitcnt vmcnt(8)
	s_waitcnt lgkmcnt(0)
	s_barrier
	s_setprio 1
	s_waitcnt lgkmcnt(0)
	v_mfma_f32_16x16x32_bf16 v[104:107], v[142:145], v[188:191], v[104:107]
	v_mfma_f32_16x16x32_bf16 v[100:103], v[150:153], v[188:191], v[100:103]
	v_mfma_f32_16x16x32_bf16 v[96:99], v[142:145], v[196:199], v[96:99]
	v_mfma_f32_16x16x32_bf16 v[92:95], v[150:153], v[196:199], v[92:95]
	v_mfma_f32_16x16x32_bf16 v[88:91], v[142:145], v[204:207], v[88:91]
	v_mfma_f32_16x16x32_bf16 v[84:87], v[150:153], v[204:207], v[84:87]
	v_mfma_f32_16x16x32_bf16 v[80:83], v[142:145], v[212:215], v[80:83]
	v_mfma_f32_16x16x32_bf16 v[76:79], v[150:153], v[212:215], v[76:79]
	v_mfma_f32_16x16x32_bf16 v[104:107], v[146:149], v[192:195], v[104:107]
	v_mfma_f32_16x16x32_bf16 v[100:103], v[168:171], v[192:195], v[100:103]
	v_mfma_f32_16x16x32_bf16 v[96:99], v[146:149], v[200:203], v[96:99]
	v_mfma_f32_16x16x32_bf16 v[92:95], v[168:171], v[200:203], v[92:95]
	v_mfma_f32_16x16x32_bf16 v[88:91], v[146:149], v[208:211], v[88:91]
	v_mfma_f32_16x16x32_bf16 v[84:87], v[168:171], v[208:211], v[84:87]
	v_mfma_f32_16x16x32_bf16 v[80:83], v[146:149], v[216:219], v[80:83]
	v_mfma_f32_16x16x32_bf16 v[76:79], v[168:171], v[216:219], v[76:79]
	s_setprio 0
	s_setprio 1
	v_mfma_f32_16x16x32_bf16 v[40:43], v[172:175], v[188:191], v[40:43]
	v_mfma_f32_16x16x32_bf16 v[36:39], v[180:183], v[188:191], v[36:39]
	v_mfma_f32_16x16x32_bf16 v[32:35], v[172:175], v[196:199], v[32:35]
	v_mfma_f32_16x16x32_bf16 v[28:31], v[180:183], v[196:199], v[28:31]
	v_mfma_f32_16x16x32_bf16 v[24:27], v[172:175], v[204:207], v[24:27]
	v_mfma_f32_16x16x32_bf16 v[20:23], v[180:183], v[204:207], v[20:23]
	v_mfma_f32_16x16x32_bf16 v[14:17], v[172:175], v[212:215], v[16:19]
	v_mfma_f32_16x16x32_bf16 v[10:13], v[180:183], v[212:215], v[10:13]
	s_add_i32 s70, s70, 2
	s_add_u32 s68, s68, 0x100
	s_addc_u32 s69, s69, 0
	s_cmp_gt_u32 s70, 13
	v_mfma_f32_16x16x32_bf16 v[40:43], v[176:179], v[192:195], v[40:43]
	v_mfma_f32_16x16x32_bf16 v[36:39], v[184:187], v[192:195], v[36:39]
	v_mfma_f32_16x16x32_bf16 v[32:35], v[176:179], v[200:203], v[32:35]
	v_mfma_f32_16x16x32_bf16 v[28:31], v[184:187], v[200:203], v[28:31]
	v_mfma_f32_16x16x32_bf16 v[24:27], v[176:179], v[208:211], v[24:27]
	v_mfma_f32_16x16x32_bf16 v[20:23], v[184:187], v[208:211], v[20:23]
	v_mfma_f32_16x16x32_bf16 v[16:19], v[176:179], v[216:219], v[14:17]
	v_mfma_f32_16x16x32_bf16 v[12:15], v[184:187], v[216:219], v[10:13]
	s_setprio 0
	s_barrier
	s_cbranch_scc1 .LBB13_944
	s_mov_b64 s[42:43], s[6:7]
	s_cmp_lg_u32 s70, 6
	s_cbranch_scc0 .LBB13_941
	s_branch .LBB13_942

; #define PG8_STAGE(bufoff, gbase, voff) do { const char* gb_ = (const char*)(gbase); asm volatile("" : "+s"(gb_));     \
;         _Pragma("unroll") for (int _i = 0; _i < 2; ++_i) \
;         __builtin_amdgcn_global_load_lds((const unsigned*)(gb_ + (voff)[_i]), (PG8_LAS unsigned*)(lds + (bufoff) + ldsw + _i * 8192), 16, 0, 0); } while (0)
; #define PG8_LDA(dst, b, h) do { _Pragma("unroll") for (int m = 0; m < 4; ++m) _Pragma("unroll") for (int k = 0; k < 2; ++k) dst[m][k] = *(const PG8_LAS bf16x8*)(lds + PG8_SA(b, h) + aoff + m * 2048 + k * 1024); } while (0)
; #define PG8_LDB(dst, b, h) do { _Pragma("unroll") for (int n = 0; n < 2; ++n) _Pragma("unroll") for (int k = 0; k < 2; ++k) dst[n][k] = *(const PG8_LAS bf16x8*)(lds + PG8_SB(b, h) + boff + n * 2048 + k * 1024); } while (0)
; #define PG8_MMA(ai, bj, At, Bt) do { __builtin_amdgcn_s_setprio(1); _Pragma("unroll") for (int m = 0; m < 4; ++m) _Pragma("unroll") for (int n = 0; n < 2; ++n) _Pragma("unroll") for (int k = 0; k < 2; ++k) \
;         acc[ai][bj][m][n] = __builtin_amdgcn_mfma_f32_16x16x32_bf16(Bt[n][k], At[m][k], acc[ai][bj][m][n], 0, 0, 0); __builtin_amdgcn_s_setprio(0); } while (0)
; #define PG8_WAIT_V(n) asm volatile("s_waitcnt vmcnt(" #n ")" ::: "memory")
; #define PG8_WAIT_L(n) asm volatile("s_waitcnt lgkmcnt(" #n ")" ::: "memory")
; #define PG8_BAR __builtin_amdgcn_s_barrier()
; #define PG8_SCHED __builtin_amdgcn_sched_barrier(0)
; template <class Epi, class Sched, bool ALIGN_EPI = false, bool SP2 = false>
; __device__ __forceinline__ void gemm_phase(PG8_LAS unsigned char* lds, const Gemm g, const Sched& S, const Epi& E, int wid0) {
;     ...
;             PG8_WAIT_V(8); PG8_WAIT_L(0); PG8_BAR; PG8_MMA(1, 0, At, B0); PG8_MMA(1, 1, At, B1); PG8_BAR; PG8_SCHED;
;             PG8_LDB(B0, 1, 0); PG8_LDB(B1, 1, 1); PG8_SCHED; PG8_LDA(At, 1, 0); PG8_STAGE(PG8_SA(0, 1), a2 + hstepA, vA_);
;             PG8_WAIT_V(8); PG8_WAIT_L(0); PG8_BAR; PG8_MMA(0, 0, At, B0); PG8_MMA(0, 1, At, B1); PG8_BAR; PG8_SCHED;
.Lff1a_wd_1:
	s_waitcnt lgkmcnt(0)
	s_barrier
	s_setprio 1
	s_waitcnt lgkmcnt(0)
	v_mfma_f32_16x16x32_bf16 v[74:77], v[142:145], v[186:189], v[74:77]
	v_mfma_f32_16x16x32_bf16 v[70:73], v[150:153], v[186:189], v[70:73]
	v_mfma_f32_16x16x32_bf16 v[58:61], v[142:145], v[194:197], v[58:61]
	v_mfma_f32_16x16x32_bf16 v[54:57], v[150:153], v[194:197], v[54:57]
	v_mfma_f32_16x16x32_bf16 v[42:45], v[142:145], v[202:205], v[42:45]
	v_mfma_f32_16x16x32_bf16 v[38:41], v[150:153], v[202:205], v[38:41]
	v_mfma_f32_16x16x32_bf16 v[26:29], v[142:145], v[210:213], v[26:29]
	v_mfma_f32_16x16x32_bf16 v[22:25], v[150:153], v[210:213], v[22:25]
	v_mfma_f32_16x16x32_bf16 v[74:77], v[146:149], v[190:193], v[74:77]
	v_mfma_f32_16x16x32_bf16 v[70:73], v[154:157], v[190:193], v[70:73]
	v_mfma_f32_16x16x32_bf16 v[58:61], v[146:149], v[198:201], v[58:61]
	v_mfma_f32_16x16x32_bf16 v[54:57], v[154:157], v[198:201], v[54:57]
	v_mfma_f32_16x16x32_bf16 v[42:45], v[146:149], v[206:209], v[42:45]
	v_mfma_f32_16x16x32_bf16 v[38:41], v[154:157], v[206:209], v[38:41]
	v_mfma_f32_16x16x32_bf16 v[26:29], v[146:149], v[214:217], v[26:29]
	v_mfma_f32_16x16x32_bf16 v[22:25], v[154:157], v[214:217], v[22:25]
	s_setprio 0
	s_setprio 1
	v_mfma_f32_16x16x32_bf16 v[66:69], v[164:167], v[186:189], v[66:69]
	v_mfma_f32_16x16x32_bf16 v[62:65], v[178:181], v[186:189], v[62:65]
	v_mfma_f32_16x16x32_bf16 v[50:53], v[164:167], v[194:197], v[50:53]
	v_mfma_f32_16x16x32_bf16 v[46:49], v[178:181], v[194:197], v[46:49]
	v_mfma_f32_16x16x32_bf16 v[34:37], v[164:167], v[202:205], v[34:37]
	v_mfma_f32_16x16x32_bf16 v[30:33], v[178:181], v[202:205], v[30:33]
	v_mfma_f32_16x16x32_bf16 v[18:21], v[164:167], v[210:213], v[18:21]
	v_mfma_f32_16x16x32_bf16 v[14:17], v[178:181], v[210:213], v[14:17]
	v_mfma_f32_16x16x32_bf16 v[66:69], v[174:177], v[190:193], v[66:69]
	v_mfma_f32_16x16x32_bf16 v[62:65], v[182:185], v[190:193], v[62:65]
	v_mfma_f32_16x16x32_bf16 v[50:53], v[174:177], v[198:201], v[50:53]
	v_mfma_f32_16x16x32_bf16 v[46:49], v[182:185], v[198:201], v[46:49]
	v_mfma_f32_16x16x32_bf16 v[34:37], v[174:177], v[206:209], v[34:37]
	v_mfma_f32_16x16x32_bf16 v[30:33], v[182:185], v[206:209], v[30:33]
	v_mfma_f32_16x16x32_bf16 v[18:21], v[174:177], v[214:217], v[18:21]
	v_mfma_f32_16x16x32_bf16 v[14:17], v[182:185], v[214:217], v[14:17]
	s_setprio 0
	s_barrier
	s_add_i32 s62, 0, 0x18000
	s_add_i32 s63, 0, 0x1c000
	v_add_u32_e32 v154, s62, v9
	v_add_u32_e32 v182, s63, v9
	ds_read_b128 v[142:145], v154
	ds_read_b128 v[146:149], v154 offset:1024
	ds_read_b128 v[150:153], v154 offset:2048
	ds_read_b128 v[154:157], v154 offset:3072
	ds_read_b128 v[164:167], v182
	ds_read_b128 v[174:177], v182 offset:1024
	ds_read_b128 v[178:181], v182 offset:2048
	ds_read_b128 v[182:185], v182 offset:3072
	s_add_u32 s8, s40, 0x40000
	s_addc_u32 s9, s41, 0
	s_mov_b32 m0, s46
	ds_read_b128 v[186:189], v173 offset:32768
	ds_read_b128 v[190:193], v173 offset:33792
	ds_read_b128 v[194:197], v173 offset:34816
	ds_read_b128 v[198:201], v173 offset:35840
	ds_read_b128 v[202:205], v173 offset:36864
	ds_read_b128 v[206:209], v173 offset:37888
	ds_read_b128 v[210:213], v173 offset:38912
	ds_read_b128 v[214:217], v173 offset:39936
	s_nop 0
	global_load_lds_dwordx4 v218, s[8:9]
	s_mov_b32 m0, s47
	s_nop 0
	global_load_lds_dwordx4 v220, s[8:9]
	s_waitcnt vmcnt(8)
	s_waitcnt lgkmcnt(0)
	s_barrier
	s_setprio 1
	s_waitcnt lgkmcnt(0)
	v_mfma_f32_16x16x32_bf16 v[138:141], v[142:145], v[186:189], v[138:141]
	v_mfma_f32_16x16x32_bf16 v[134:137], v[150:153], v[186:189], v[134:137]
	v_mfma_f32_16x16x32_bf16 v[122:125], v[142:145], v[194:197], v[122:125]
	v_mfma_f32_16x16x32_bf16 v[118:121], v[150:153], v[194:197], v[118:121]
	v_mfma_f32_16x16x32_bf16 v[106:109], v[142:145], v[202:205], v[106:109]
	v_mfma_f32_16x16x32_bf16 v[102:105], v[150:153], v[202:205], v[102:105]
	v_mfma_f32_16x16x32_bf16 v[90:93], v[142:145], v[210:213], v[90:93]
	v_mfma_f32_16x16x32_bf16 v[86:89], v[150:153], v[210:213], v[86:89]
	v_mfma_f32_16x16x32_bf16 v[138:141], v[146:149], v[190:193], v[138:141]
	v_mfma_f32_16x16x32_bf16 v[134:137], v[154:157], v[190:193], v[134:137]
	v_mfma_f32_16x16x32_bf16 v[122:125], v[146:149], v[198:201], v[122:125]
	v_mfma_f32_16x16x32_bf16 v[118:121], v[154:157], v[198:201], v[118:121]
	v_mfma_f32_16x16x32_bf16 v[106:109], v[146:149], v[206:209], v[106:109]
	v_mfma_f32_16x16x32_bf16 v[102:105], v[154:157], v[206:209], v[102:105]
	v_mfma_f32_16x16x32_bf16 v[90:93], v[146:149], v[214:217], v[90:93]
	v_mfma_f32_16x16x32_bf16 v[86:89], v[154:157], v[214:217], v[86:89]
	s_setprio 0
	s_setprio 1
	v_mfma_f32_16x16x32_bf16 v[130:133], v[164:167], v[186:189], v[130:133]
	v_mfma_f32_16x16x32_bf16 v[126:129], v[178:181], v[186:189], v[126:129]
	v_mfma_f32_16x16x32_bf16 v[114:117], v[164:167], v[194:197], v[114:117]
	v_mfma_f32_16x16x32_bf16 v[110:113], v[178:181], v[194:197], v[110:113]
	v_mfma_f32_16x16x32_bf16 v[98:101], v[164:167], v[202:205], v[98:101]
	v_mfma_f32_16x16x32_bf16 v[94:97], v[178:181], v[202:205], v[94:97]
	v_mfma_f32_16x16x32_bf16 v[82:85], v[164:167], v[210:213], v[82:85]
	v_mfma_f32_16x16x32_bf16 v[78:81], v[178:181], v[210:213], v[78:81]
	v_mfma_f32_16x16x32_bf16 v[130:133], v[174:177], v[190:193], v[130:133]
	v_mfma_f32_16x16x32_bf16 v[126:129], v[182:185], v[190:193], v[126:129]
	v_mfma_f32_16x16x32_bf16 v[114:117], v[174:177], v[198:201], v[114:117]
	v_mfma_f32_16x16x32_bf16 v[110:113], v[182:185], v[198:201], v[110:113]
	v_mfma_f32_16x16x32_bf16 v[98:101], v[174:177], v[206:209], v[98:101]
	v_mfma_f32_16x16x32_bf16 v[94:97], v[182:185], v[206:209], v[94:97]
	v_mfma_f32_16x16x32_bf16 v[82:85], v[174:177], v[214:217], v[82:85]
	v_mfma_f32_16x16x32_bf16 v[78:81], v[182:185], v[214:217], v[78:81]
	s_setprio 0
	s_barrier
;     __device__ float mid(int row) const { return rg(row) / ra(row); }
; #define PG8_STAGE(bufoff, gbase, voff) do { const char* gb_ = (const char*)(gbase); asm volatile("" : "+s"(gb_));     \
;         _Pragma("unroll") for (int _i = 0; _i < 2; ++_i) \
;         __builtin_amdgcn_global_load_lds((const unsigned*)(gb_ + (voff)[_i]), (PG8_LAS unsigned*)(lds + (bufoff) + ldsw + _i * 8192), 16, 0, 0); } while (0)
; #define PG8_BAR __builtin_amdgcn_s_barrier()
; template <class Epi, class Sched, bool ALIGN_EPI = false, bool SP2 = false>
; __device__ __forceinline__ void gemm_phase(PG8_LAS unsigned char* lds, const Gemm g, const Sched& S, const Epi& E, int wid0) {
;     ...
;         for (int t = 0; t < nt; t += 2) {
;             const bool last = (t == nt - 2);
;             const char* a1 = cA + (size_t)(t + 1) * kstep;
;             const char* a2 = last ? nA : cA + (size_t)(t + 2) * kstep; const char* b2 = last ? nB : cB + (size_t)(t + 2) * kstep;
;             const char* a3 = a2 + kstep; const char* b3 = b2 + kstep;
;             if (last && has_next) S.a_ready(nxt);
;             if constexpr (Epi::HAS_MID) { if (t == Epi::MID_T) E.mid(acc, cur, wr, fr); }
;             unsigned vA_[2] = {voffA[0], voffA[1]}, vB_[2] = {voffB[0], voffB[1]};
;             asm volatile("" : "+v"(vA_[0]), "+v"(vA_[1]), "+v"(vB_[0]), "+v"(vB_[1]));
;             if constexpr (SP2) {
;             PG8_LDB(B0, 0, 0); PG8_LDB(B1, 0, 1); PG8_SCHED; PG8_LDA(At, 0, 0); PG8_STAGE(PG8_SA(1, 1), a1 + hstepA, vA_);
;             PG8_WAIT_V(8); PG8_WAIT_L(0); PG8_BAR; PG8_MMA(0, 0, At, B0); PG8_MMA(0, 1, At, B1); PG8_BAR; PG8_SCHED;
;             PG8_LDA(At, 0, 1); PG8_STAGE(PG8_SB(0, 0), b2, vB_); PG8_STAGE(PG8_SB(0, 1), b2 + hstep, vB_); PG8_STAGE(PG8_SA(0, 0), a2, vA_);
;             PG8_WAIT_V(8); PG8_WAIT_L(0); PG8_BAR; PG8_MMA(1, 0, At, B0); PG8_MMA(1, 1, At, B1); PG8_BAR; PG8_SCHED;
;             PG8_LDB(B0, 1, 0); PG8_LDB(B1, 1, 1); PG8_SCHED; PG8_LDA(At, 1, 0); PG8_STAGE(PG8_SA(0, 1), a2 + hstepA, vA_);
;             PG8_WAIT_V(8); PG8_WAIT_L(0); PG8_BAR; PG8_MMA(0, 0, At, B0); PG8_MMA(0, 1, At, B1); PG8_BAR; PG8_SCHED;
;             PG8_LDA(At, 1, 1); PG8_STAGE(PG8_SB(1, 0), b3, vB_); PG8_STAGE(PG8_SB(1, 1), b3 + hstep, vB_); PG8_STAGE(PG8_SA(1, 0), a3, vA_);
;             PG8_WAIT_V(8); PG8_WAIT_L(0); PG8_BAR; PG8_MMA(1, 0, At, B0); PG8_MMA(1, 1, At, B1); PG8_BAR; PG8_SCHED;
	s_add_u32 s8, s38, 0x80
	s_addc_u32 s9, s39, 0
	s_add_i32 s40, s62, s27
	s_mov_b32 m0, s40
	ds_read_b128 v[186:189], v173 offset:49152
	ds_read_b128 v[190:193], v173 offset:50176
	ds_read_b128 v[194:197], v173 offset:51200
	ds_read_b128 v[198:201], v173 offset:52224
	ds_read_b128 v[202:205], v173 offset:53248
	ds_read_b128 v[206:209], v173 offset:54272
	ds_read_b128 v[210:213], v173 offset:55296
	ds_read_b128 v[214:217], v173 offset:56320
	s_nop 0
	global_load_lds_dwordx4 v219, s[8:9]
	s_add_i32 m0, s40, 0x2000
	s_nop 0
	global_load_lds_dwordx4 v221, s[8:9]
	s_add_u32 s8, s38, 0x10080
	s_addc_u32 s9, s39, 0
	s_add_i32 s38, s63, s27
	s_mov_b32 m0, s38
	s_nop 0
	global_load_lds_dwordx4 v219, s[8:9]
	s_add_i32 m0, s38, 0x2000
	s_nop 0
	global_load_lds_dwordx4 v221, s[8:9]
	s_mov_b32 m0, s50
	s_nop 0
	global_load_lds_dwordx4 v218, s[36:37]
	s_mov_b32 m0, s51
	s_nop 0
	global_load_lds_dwordx4 v220, s[36:37]
	s_waitcnt vmcnt(8)
	s_waitcnt lgkmcnt(0)
	s_barrier
	s_setprio 1
	s_waitcnt lgkmcnt(0)
	v_mfma_f32_16x16x32_bf16 v[74:77], v[142:145], v[186:189], v[74:77]
	v_mfma_f32_16x16x32_bf16 v[70:73], v[150:153], v[186:189], v[70:73]
	v_mfma_f32_16x16x32_bf16 v[58:61], v[142:145], v[194:197], v[58:61]
	v_mfma_f32_16x16x32_bf16 v[54:57], v[150:153], v[194:197], v[54:57]
	v_mfma_f32_16x16x32_bf16 v[42:45], v[142:145], v[202:205], v[42:45]
	v_mfma_f32_16x16x32_bf16 v[38:41], v[150:153], v[202:205], v[38:41]
	v_mfma_f32_16x16x32_bf16 v[26:29], v[142:145], v[210:213], v[26:29]
	v_mfma_f32_16x16x32_bf16 v[22:25], v[150:153], v[210:213], v[22:25]
	v_mfma_f32_16x16x32_bf16 v[74:77], v[146:149], v[190:193], v[74:77]
	v_mfma_f32_16x16x32_bf16 v[70:73], v[154:157], v[190:193], v[70:73]
	v_mfma_f32_16x16x32_bf16 v[58:61], v[146:149], v[198:201], v[58:61]
	v_mfma_f32_16x16x32_bf16 v[54:57], v[154:157], v[198:201], v[54:57]
	v_mfma_f32_16x16x32_bf16 v[42:45], v[146:149], v[206:209], v[42:45]
	v_mfma_f32_16x16x32_bf16 v[38:41], v[154:157], v[206:209], v[38:41]
	v_mfma_f32_16x16x32_bf16 v[26:29], v[146:149], v[214:217], v[26:29]
	v_mfma_f32_16x16x32_bf16 v[22:25], v[154:157], v[214:217], v[22:25]
	s_setprio 0
	s_setprio 1
	v_mfma_f32_16x16x32_bf16 v[66:69], v[164:167], v[186:189], v[66:69]
	v_mfma_f32_16x16x32_bf16 v[62:65], v[178:181], v[186:189], v[62:65]
	v_mfma_f32_16x16x32_bf16 v[50:53], v[164:167], v[194:197], v[50:53]
	v_mfma_f32_16x16x32_bf16 v[46:49], v[178:181], v[194:197], v[46:49]
	v_mfma_f32_16x16x32_bf16 v[34:37], v[164:167], v[202:205], v[34:37]
	v_mfma_f32_16x16x32_bf16 v[30:33], v[178:181], v[202:205], v[30:33]
	v_mfma_f32_16x16x32_bf16 v[18:21], v[164:167], v[210:213], v[18:21]
	v_mfma_f32_16x16x32_bf16 v[14:17], v[178:181], v[210:213], v[14:17]
	s_add_i32 s61, s61, 2
	s_add_u32 s59, s59, 0x100
	s_addc_u32 s60, s60, 0
	s_cmp_gt_u32 s61, 13
	s_mov_b64 s[8:9], s[34:35]
	v_mfma_f32_16x16x32_bf16 v[66:69], v[174:177], v[190:193], v[66:69]
	v_mfma_f32_16x16x32_bf16 v[62:65], v[182:185], v[190:193], v[62:65]
	v_mfma_f32_16x16x32_bf16 v[50:53], v[174:177], v[198:201], v[50:53]
	v_mfma_f32_16x16x32_bf16 v[46:49], v[182:185], v[198:201], v[46:49]
	v_mfma_f32_16x16x32_bf16 v[34:37], v[174:177], v[206:209], v[34:37]
	v_mfma_f32_16x16x32_bf16 v[30:33], v[182:185], v[206:209], v[30:33]
	v_mfma_f32_16x16x32_bf16 v[18:21], v[174:177], v[214:217], v[18:21]
	v_mfma_f32_16x16x32_bf16 v[14:17], v[182:185], v[214:217], v[14:17]
	s_setprio 0
	s_barrier
	s_cbranch_scc0 .LBB13_1074
	s_and_b64 vcc, exec, s[16:17]
	s_cbranch_vccz .LBB13_1077
	s_barrier

;     __device__ float mid(int row) const { return rg(row) / ra(row); }
; #define PG8_STAGE(bufoff, gbase, voff) do { const char* gb_ = (const char*)(gbase); asm volatile("" : "+s"(gb_));     \
;         _Pragma("unroll") for (int _i = 0; _i < 2; ++_i) \
;         __builtin_amdgcn_global_load_lds((const unsigned*)(gb_ + (voff)[_i]), (PG8_LAS unsigned*)(lds + (bufoff) + ldsw + _i * 8192), 16, 0, 0); } while (0)
; #define PG8_LDA(dst, b, h) do { _Pragma("unroll") for (int m = 0; m < 4; ++m) _Pragma("unroll") for (int k = 0; k < 2; ++k) dst[m][k] = *(const PG8_LAS bf16x8*)(lds + PG8_SA(b, h) + aoff + m * 2048 + k * 1024); } while (0)
; #define PG8_LDB(dst, b, h) do { _Pragma("unroll") for (int n = 0; n < 2; ++n) _Pragma("unroll") for (int k = 0; k < 2; ++k) dst[n][k] = *(const PG8_LAS bf16x8*)(lds + PG8_SB(b, h) + boff + n * 2048 + k * 1024); } while (0)
; #define PG8_WAIT_V(n) asm volatile("s_waitcnt vmcnt(" #n ")" ::: "memory")
; template <class Epi, class Sched, bool ALIGN_EPI = false, bool SP2 = false>
; __device__ __forceinline__ void gemm_phase(PG8_LAS unsigned char* lds, const Gemm g, const Sched& S, const Epi& E, int wid0) {
;     ...
;         for (int t = 0; t < nt; t += 2) {
;             const bool last = (t == nt - 2);
;             const char* a1 = cA + (size_t)(t + 1) * kstep;
;             const char* a2 = last ? nA : cA + (size_t)(t + 2) * kstep; const char* b2 = last ? nB : cB + (size_t)(t + 2) * kstep;
;             const char* a3 = a2 + kstep; const char* b3 = b2 + kstep;
;             if (last && has_next) S.a_ready(nxt);
;             if constexpr (Epi::HAS_MID) { if (t == Epi::MID_T) E.mid(acc, cur, wr, fr); }
;             unsigned vA_[2] = {voffA[0], voffA[1]}, vB_[2] = {voffB[0], voffB[1]};
;             asm volatile("" : "+v"(vA_[0]), "+v"(vA_[1]), "+v"(vB_[0]), "+v"(vB_[1]));
;             if constexpr (SP2) {
;             PG8_LDB(B0, 0, 0); PG8_LDB(B1, 0, 1); PG8_SCHED; PG8_LDA(At, 0, 0); PG8_STAGE(PG8_SA(1, 1), a1 + hstepA, vA_);
;             PG8_WAIT_V(8); PG8_WAIT_L(0); PG8_BAR; PG8_MMA(0, 0, At, B0); PG8_MMA(0, 1, At, B1); PG8_BAR; PG8_SCHED;
;             PG8_LDA(At, 0, 1); PG8_STAGE(PG8_SB(0, 0), b2, vB_); PG8_STAGE(PG8_SB(0, 1), b2 + hstep, vB_); PG8_STAGE(PG8_SA(0, 0), a2, vA_);
;             PG8_WAIT_V(8); PG8_WAIT_L(0); PG8_BAR; PG8_MMA(1, 0, At, B0); PG8_MMA(1, 1, At, B1); PG8_BAR; PG8_SCHED;
.LBB13_1187:
	v_mov_b32_e32 v181, v162
	v_mov_b32_e32 v202, v156
	v_mov_b32_e32 v203, v158
	v_mov_b32_e32 v204, v160
	ds_read_b128 v[128:131], v161
	ds_read_b128 v[132:135], v161 offset:1024
	ds_read_b128 v[136:139], v161 offset:2048
	ds_read_b128 v[140:143], v161 offset:3072
	ds_read_b128 v[144:147], v163
	ds_read_b128 v[148:151], v163 offset:1024
	ds_read_b128 v[152:155], v163 offset:2048
	ds_read_b128 v[164:167], v163 offset:3072
	s_add_u32 s34, s30, 0x100
	s_addc_u32 s35, s31, 0
	s_cmp_eq_u32 s60, 60
	s_cselect_b32 s40, s27, s34
	s_cselect_b32 s41, s17, s35
	s_cselect_b32 s38, s57, s58
	s_cselect_b32 s39, s19, s59
	s_add_u32 s36, s40, 0x80
	s_addc_u32 s37, s41, 0
	s_add_u32 s30, s30, 0x100080
	s_addc_u32 s31, s31, 0
	s_add_i32 m0, s29, 0xc000
	ds_read_b128 v[168:171], v180
	ds_read_b128 v[172:175], v180 offset:1024
	ds_read_b128 v[176:179], v180 offset:2048
	ds_read_b128 v[182:185], v180 offset:3072
	ds_read_b128 v[186:189], v180 offset:4096
	ds_read_b128 v[190:193], v180 offset:5120
	ds_read_b128 v[194:197], v180 offset:6144
	ds_read_b128 v[198:201], v180 offset:7168
	s_nop 0
	global_load_lds_dwordx4 v202, s[30:31]
	s_add_i32 m0, s29, 0xe000
	s_nop 0
	global_load_lds_dwordx4 v204, s[30:31]
	s_waitcnt vmcnt(8)
	s_waitcnt lgkmcnt(0)
	s_barrier
	s_setprio 1
	s_waitcnt lgkmcnt(0)
	v_mfma_f32_16x16x32_bf16 v[124:127], v[128:131], v[168:171], v[124:127]
	v_mfma_f32_16x16x32_bf16 v[120:123], v[136:139], v[168:171], v[120:123]
	v_mfma_f32_16x16x32_bf16 v[116:119], v[128:131], v[176:179], v[116:119]
	v_mfma_f32_16x16x32_bf16 v[112:115], v[136:139], v[176:179], v[112:115]
	v_mfma_f32_16x16x32_bf16 v[108:111], v[128:131], v[186:189], v[108:111]
	v_mfma_f32_16x16x32_bf16 v[104:107], v[136:139], v[186:189], v[104:107]
	v_mfma_f32_16x16x32_bf16 v[100:103], v[128:131], v[194:197], v[100:103]
	v_mfma_f32_16x16x32_bf16 v[96:99], v[136:139], v[194:197], v[96:99]
	v_mfma_f32_16x16x32_bf16 v[124:127], v[132:135], v[172:175], v[124:127]
	v_mfma_f32_16x16x32_bf16 v[120:123], v[140:143], v[172:175], v[120:123]
	v_mfma_f32_16x16x32_bf16 v[116:119], v[132:135], v[182:185], v[116:119]
	v_mfma_f32_16x16x32_bf16 v[112:115], v[140:143], v[182:185], v[112:115]
	v_mfma_f32_16x16x32_bf16 v[108:111], v[132:135], v[190:193], v[108:111]
	v_mfma_f32_16x16x32_bf16 v[104:107], v[140:143], v[190:193], v[104:107]
	v_mfma_f32_16x16x32_bf16 v[100:103], v[132:135], v[198:201], v[100:103]
	v_mfma_f32_16x16x32_bf16 v[96:99], v[140:143], v[198:201], v[96:99]
	s_setprio 0
	s_setprio 1
	v_mfma_f32_16x16x32_bf16 v[60:63], v[144:147], v[168:171], v[60:63]
	v_mfma_f32_16x16x32_bf16 v[56:59], v[152:155], v[168:171], v[56:59]
	v_mfma_f32_16x16x32_bf16 v[52:55], v[144:147], v[176:179], v[52:55]
	v_mfma_f32_16x16x32_bf16 v[48:51], v[152:155], v[176:179], v[48:51]
	v_mfma_f32_16x16x32_bf16 v[44:47], v[144:147], v[186:189], v[44:47]
	v_mfma_f32_16x16x32_bf16 v[40:43], v[152:155], v[186:189], v[40:43]
	v_mfma_f32_16x16x32_bf16 v[36:39], v[144:147], v[194:197], v[36:39]
	v_mfma_f32_16x16x32_bf16 v[32:35], v[152:155], v[194:197], v[32:35]
	v_mfma_f32_16x16x32_bf16 v[60:63], v[148:151], v[172:175], v[60:63]
	v_mfma_f32_16x16x32_bf16 v[56:59], v[164:167], v[172:175], v[56:59]
	v_mfma_f32_16x16x32_bf16 v[52:55], v[148:151], v[182:185], v[52:55]
	v_mfma_f32_16x16x32_bf16 v[48:51], v[164:167], v[182:185], v[48:51]
	v_mfma_f32_16x16x32_bf16 v[44:47], v[148:151], v[190:193], v[44:47]
	v_mfma_f32_16x16x32_bf16 v[40:43], v[164:167], v[190:193], v[40:43]
	v_mfma_f32_16x16x32_bf16 v[36:39], v[148:151], v[198:201], v[36:39]
	v_mfma_f32_16x16x32_bf16 v[32:35], v[164:167], v[198:201], v[32:35]
	s_setprio 0
	s_barrier
	s_add_i32 s61, s55, s33
	s_mov_b64 s[30:31], s[38:39]
	s_mov_b32 m0, s61
	ds_read_b128 v[168:171], v180 offset:16384
	ds_read_b128 v[172:175], v180 offset:17408
	ds_read_b128 v[176:179], v180 offset:18432
	ds_read_b128 v[182:185], v180 offset:19456
	ds_read_b128 v[186:189], v180 offset:20480
	ds_read_b128 v[190:193], v180 offset:21504
	ds_read_b128 v[194:197], v180 offset:22528
	ds_read_b128 v[198:201], v180 offset:23552
	s_nop 0
	global_load_lds_dwordx4 v203, s[30:31]
	s_add_i32 m0, s61, 0x2000
	s_nop 0
	global_load_lds_dwordx4 v181, s[30:31]
	s_add_u32 s30, s38, 0x100000
	s_addc_u32 s31, s39, 0
	s_add_i32 s61, s56, s33
	s_mov_b32 m0, s61
	s_nop 0
	global_load_lds_dwordx4 v203, s[30:31]
	s_add_i32 m0, s61, 0x2000
	s_nop 0
	global_load_lds_dwordx4 v181, s[30:31]
	s_mov_b64 s[30:31], s[40:41]
	s_mov_b32 m0, s29
	s_nop 0
	global_load_lds_dwordx4 v202, s[30:31]
	s_mov_b32 m0, s46
	s_nop 0
	global_load_lds_dwordx4 v204, s[30:31]
	s_waitcnt vmcnt(8)
	s_waitcnt lgkmcnt(0)
	s_barrier
; #define PG8_STAGE(bufoff, gbase, voff) do { const char* gb_ = (const char*)(gbase); asm volatile("" : "+s"(gb_));     \
;         _Pragma("unroll") for (int _i = 0; _i < 2; ++_i) \
;         __builtin_amdgcn_global_load_lds((const unsigned*)(gb_ + (voff)[_i]), (PG8_LAS unsigned*)(lds + (bufoff) + ldsw + _i * 8192), 16, 0, 0); } while (0)
; #define PG8_LDA(dst, b, h) do { _Pragma("unroll") for (int m = 0; m < 4; ++m) _Pragma("unroll") for (int k = 0; k < 2; ++k) dst[m][k] = *(const PG8_LAS bf16x8*)(lds + PG8_SA(b, h) + aoff + m * 2048 + k * 1024); } while (0)
; #define PG8_LDB(dst, b, h) do { _Pragma("unroll") for (int n = 0; n < 2; ++n) _Pragma("unroll") for (int k = 0; k < 2; ++k) dst[n][k] = *(const PG8_LAS bf16x8*)(lds + PG8_SB(b, h) + boff + n * 2048 + k * 1024); } while (0)
; #define PG8_MMA(ai, bj, At, Bt) do { __builtin_amdgcn_s_setprio(1); _Pragma("unroll") for (int m = 0; m < 4; ++m) _Pragma("unroll") for (int n = 0; n < 2; ++n) _Pragma("unroll") for (int k = 0; k < 2; ++k) \
;         acc[ai][bj][m][n] = __builtin_amdgcn_mfma_f32_16x16x32_bf16(Bt[n][k], At[m][k], acc[ai][bj][m][n], 0, 0, 0); __builtin_amdgcn_s_setprio(0); } while (0)
; #define PG8_WAIT_V(n) asm volatile("s_waitcnt vmcnt(" #n ")" ::: "memory")
; #define PG8_WAIT_L(n) asm volatile("s_waitcnt lgkmcnt(" #n ")" ::: "memory")
; #define PG8_BAR __builtin_amdgcn_s_barrier()
; #define PG8_SCHED __builtin_amdgcn_sched_barrier(0)
; template <class Epi, class Sched, bool ALIGN_EPI = false, bool SP2 = false>
; __device__ __forceinline__ void gemm_phase(PG8_LAS unsigned char* lds, const Gemm g, const Sched& S, const Epi& E, int wid0) {
;     ...
;             PG8_WAIT_V(8); PG8_WAIT_L(0); PG8_BAR; PG8_MMA(1, 0, At, B0); PG8_MMA(1, 1, At, B1); PG8_BAR; PG8_SCHED;
;             PG8_LDB(B0, 1, 0); PG8_LDB(B1, 1, 1); PG8_SCHED; PG8_LDA(At, 1, 0); PG8_STAGE(PG8_SA(0, 1), a2 + hstepA, vA_);
;             PG8_WAIT_V(8); PG8_WAIT_L(0); PG8_BAR; PG8_MMA(0, 0, At, B0); PG8_MMA(0, 1, At, B1); PG8_BAR; PG8_SCHED;
	s_setprio 1
	s_waitcnt lgkmcnt(0)
	v_mfma_f32_16x16x32_bf16 v[92:95], v[128:131], v[168:171], v[92:95]
	v_mfma_f32_16x16x32_bf16 v[88:91], v[136:139], v[168:171], v[88:91]
	v_mfma_f32_16x16x32_bf16 v[84:87], v[128:131], v[176:179], v[84:87]
	v_mfma_f32_16x16x32_bf16 v[80:83], v[136:139], v[176:179], v[80:83]
	v_mfma_f32_16x16x32_bf16 v[76:79], v[128:131], v[186:189], v[76:79]
	v_mfma_f32_16x16x32_bf16 v[72:75], v[136:139], v[186:189], v[72:75]
	v_mfma_f32_16x16x32_bf16 v[68:71], v[128:131], v[194:197], v[68:71]
	v_mfma_f32_16x16x32_bf16 v[64:67], v[136:139], v[194:197], v[64:67]
	v_mfma_f32_16x16x32_bf16 v[92:95], v[132:135], v[172:175], v[92:95]
	v_mfma_f32_16x16x32_bf16 v[88:91], v[140:143], v[172:175], v[88:91]
	v_mfma_f32_16x16x32_bf16 v[84:87], v[132:135], v[182:185], v[84:87]
	v_mfma_f32_16x16x32_bf16 v[80:83], v[140:143], v[182:185], v[80:83]
	v_mfma_f32_16x16x32_bf16 v[76:79], v[132:135], v[190:193], v[76:79]
	v_mfma_f32_16x16x32_bf16 v[72:75], v[140:143], v[190:193], v[72:75]
	v_mfma_f32_16x16x32_bf16 v[68:71], v[132:135], v[198:201], v[68:71]
	v_mfma_f32_16x16x32_bf16 v[64:67], v[140:143], v[198:201], v[64:67]
	s_setprio 0
	s_setprio 1
	v_mfma_f32_16x16x32_bf16 v[28:31], v[144:147], v[168:171], v[28:31]
	v_mfma_f32_16x16x32_bf16 v[24:27], v[152:155], v[168:171], v[24:27]
	v_mfma_f32_16x16x32_bf16 v[20:23], v[144:147], v[176:179], v[20:23]
	v_mfma_f32_16x16x32_bf16 v[16:19], v[152:155], v[176:179], v[16:19]
	v_mfma_f32_16x16x32_bf16 v[12:15], v[144:147], v[186:189], v[12:15]
	v_mfma_f32_16x16x32_bf16 v[8:11], v[152:155], v[186:189], v[8:11]
	v_mfma_f32_16x16x32_bf16 v[4:7], v[144:147], v[194:197], v[4:7]
	v_mfma_f32_16x16x32_bf16 v[0:3], v[152:155], v[194:197], v[0:3]
	v_mfma_f32_16x16x32_bf16 v[28:31], v[148:151], v[172:175], v[28:31]
	v_mfma_f32_16x16x32_bf16 v[24:27], v[164:167], v[172:175], v[24:27]
	v_mfma_f32_16x16x32_bf16 v[20:23], v[148:151], v[182:185], v[20:23]
	v_mfma_f32_16x16x32_bf16 v[16:19], v[164:167], v[182:185], v[16:19]
	v_mfma_f32_16x16x32_bf16 v[12:15], v[148:151], v[190:193], v[12:15]
	v_mfma_f32_16x16x32_bf16 v[8:11], v[164:167], v[190:193], v[8:11]
	v_mfma_f32_16x16x32_bf16 v[4:7], v[148:151], v[198:201], v[4:7]
	v_mfma_f32_16x16x32_bf16 v[0:3], v[164:167], v[198:201], v[0:3]
	s_setprio 0
	s_barrier
	s_add_i32 s61, 0, 0x18000
	s_add_i32 s62, 0, 0x1c000
	v_add_u32_e32 v140, s61, v157
	v_add_u32_e32 v164, s62, v157
	ds_read_b128 v[128:131], v140
	ds_read_b128 v[132:135], v140 offset:1024
	ds_read_b128 v[136:139], v140 offset:2048
	ds_read_b128 v[140:143], v140 offset:3072
	ds_read_b128 v[144:147], v164
	ds_read_b128 v[148:151], v164 offset:1024
	ds_read_b128 v[152:155], v164 offset:2048
	ds_read_b128 v[164:167], v164 offset:3072
	s_add_u32 s30, s40, 0x100000
	s_addc_u32 s31, s41, 0
	s_mov_b32 m0, s47
	ds_read_b128 v[168:171], v180 offset:32768
	ds_read_b128 v[172:175], v180 offset:33792
	ds_read_b128 v[176:179], v180 offset:34816
	ds_read_b128 v[182:185], v180 offset:35840
	ds_read_b128 v[186:189], v180 offset:36864
	ds_read_b128 v[190:193], v180 offset:37888
	ds_read_b128 v[194:197], v180 offset:38912
	ds_read_b128 v[198:201], v180 offset:39936
	s_nop 0
	global_load_lds_dwordx4 v202, s[30:31]
	s_mov_b32 m0, s48
	s_nop 0
	global_load_lds_dwordx4 v204, s[30:31]
	s_waitcnt vmcnt(8)
	s_waitcnt lgkmcnt(0)
	s_barrier
	s_setprio 1
	s_waitcnt lgkmcnt(0)
	v_mfma_f32_16x16x32_bf16 v[124:127], v[128:131], v[168:171], v[124:127]
	v_mfma_f32_16x16x32_bf16 v[120:123], v[136:139], v[168:171], v[120:123]
	v_mfma_f32_16x16x32_bf16 v[116:119], v[128:131], v[176:179], v[116:119]
	v_mfma_f32_16x16x32_bf16 v[112:115], v[136:139], v[176:179], v[112:115]
	v_mfma_f32_16x16x32_bf16 v[108:111], v[128:131], v[186:189], v[108:111]
	v_mfma_f32_16x16x32_bf16 v[104:107], v[136:139], v[186:189], v[104:107]
	v_mfma_f32_16x16x32_bf16 v[100:103], v[128:131], v[194:197], v[100:103]
	v_mfma_f32_16x16x32_bf16 v[96:99], v[136:139], v[194:197], v[96:99]
	v_mfma_f32_16x16x32_bf16 v[124:127], v[132:135], v[172:175], v[124:127]
	v_mfma_f32_16x16x32_bf16 v[120:123], v[140:143], v[172:175], v[120:123]
	v_mfma_f32_16x16x32_bf16 v[116:119], v[132:135], v[182:185], v[116:119]
	v_mfma_f32_16x16x32_bf16 v[112:115], v[140:143], v[182:185], v[112:115]
	v_mfma_f32_16x16x32_bf16 v[108:111], v[132:135], v[190:193], v[108:111]
	v_mfma_f32_16x16x32_bf16 v[104:107], v[140:143], v[190:193], v[104:107]
	v_mfma_f32_16x16x32_bf16 v[100:103], v[132:135], v[198:201], v[100:103]
	v_mfma_f32_16x16x32_bf16 v[96:99], v[140:143], v[198:201], v[96:99]
	s_setprio 0
	s_setprio 1
	v_mfma_f32_16x16x32_bf16 v[60:63], v[144:147], v[168:171], v[60:63]
	v_mfma_f32_16x16x32_bf16 v[56:59], v[152:155], v[168:171], v[56:59]
	v_mfma_f32_16x16x32_bf16 v[52:55], v[144:147], v[176:179], v[52:55]
	v_mfma_f32_16x16x32_bf16 v[48:51], v[152:155], v[176:179], v[48:51]
	v_mfma_f32_16x16x32_bf16 v[44:47], v[144:147], v[186:189], v[44:47]
	v_mfma_f32_16x16x32_bf16 v[40:43], v[152:155], v[186:189], v[40:43]
	v_mfma_f32_16x16x32_bf16 v[36:39], v[144:147], v[194:197], v[36:39]
	v_mfma_f32_16x16x32_bf16 v[32:35], v[152:155], v[194:197], v[32:35]
	v_mfma_f32_16x16x32_bf16 v[60:63], v[148:151], v[172:175], v[60:63]
	v_mfma_f32_16x16x32_bf16 v[56:59], v[164:167], v[172:175], v[56:59]
	v_mfma_f32_16x16x32_bf16 v[52:55], v[148:151], v[182:185], v[52:55]
	v_mfma_f32_16x16x32_bf16 v[48:51], v[164:167], v[182:185], v[48:51]
	v_mfma_f32_16x16x32_bf16 v[44:47], v[148:151], v[190:193], v[44:47]
	v_mfma_f32_16x16x32_bf16 v[40:43], v[164:167], v[190:193], v[40:43]
	v_mfma_f32_16x16x32_bf16 v[36:39], v[148:151], v[198:201], v[36:39]
	v_mfma_f32_16x16x32_bf16 v[32:35], v[164:167], v[198:201], v[32:35]
	s_setprio 0
	s_barrier
;     __device__ float mid(int row) const { return rg(row) / ra(row); }
; #define PG8_STAGE(bufoff, gbase, voff) do { const char* gb_ = (const char*)(gbase); asm volatile("" : "+s"(gb_));     \
;         _Pragma("unroll") for (int _i = 0; _i < 2; ++_i) \
;         __builtin_amdgcn_global_load_lds((const unsigned*)(gb_ + (voff)[_i]), (PG8_LAS unsigned*)(lds + (bufoff) + ldsw + _i * 8192), 16, 0, 0); } while (0)
; #define PG8_BAR __builtin_amdgcn_s_barrier()
; template <class Epi, class Sched, bool ALIGN_EPI = false, bool SP2 = false>
; __device__ __forceinline__ void gemm_phase(PG8_LAS unsigned char* lds, const Gemm g, const Sched& S, const Epi& E, int wid0) {
;     ...
;         for (int t = 0; t < nt; t += 2) {
;             const bool last = (t == nt - 2);
;             const char* a1 = cA + (size_t)(t + 1) * kstep;
;             const char* a2 = last ? nA : cA + (size_t)(t + 2) * kstep; const char* b2 = last ? nB : cB + (size_t)(t + 2) * kstep;
;             const char* a3 = a2 + kstep; const char* b3 = b2 + kstep;
;             if (last && has_next) S.a_ready(nxt);
;             if constexpr (Epi::HAS_MID) { if (t == Epi::MID_T) E.mid(acc, cur, wr, fr); }
;             unsigned vA_[2] = {voffA[0], voffA[1]}, vB_[2] = {voffB[0], voffB[1]};
;             asm volatile("" : "+v"(vA_[0]), "+v"(vA_[1]), "+v"(vB_[0]), "+v"(vB_[1]));
;             if constexpr (SP2) {
;             PG8_LDB(B0, 0, 0); PG8_LDB(B1, 0, 1); PG8_SCHED; PG8_LDA(At, 0, 0); PG8_STAGE(PG8_SA(1, 1), a1 + hstepA, vA_);
;             PG8_WAIT_V(8); PG8_WAIT_L(0); PG8_BAR; PG8_MMA(0, 0, At, B0); PG8_MMA(0, 1, At, B1); PG8_BAR; PG8_SCHED;
;             PG8_LDA(At, 0, 1); PG8_STAGE(PG8_SB(0, 0), b2, vB_); PG8_STAGE(PG8_SB(0, 1), b2 + hstep, vB_); PG8_STAGE(PG8_SA(0, 0), a2, vA_);
;             PG8_WAIT_V(8); PG8_WAIT_L(0); PG8_BAR; PG8_MMA(1, 0, At, B0); PG8_MMA(1, 1, At, B1); PG8_BAR; PG8_SCHED;
;             PG8_LDB(B0, 1, 0); PG8_LDB(B1, 1, 1); PG8_SCHED; PG8_LDA(At, 1, 0); PG8_STAGE(PG8_SA(0, 1), a2 + hstepA, vA_);
;             PG8_WAIT_V(8); PG8_WAIT_L(0); PG8_BAR; PG8_MMA(0, 0, At, B0); PG8_MMA(0, 1, At, B1); PG8_BAR; PG8_SCHED;
;             PG8_LDA(At, 1, 1); PG8_STAGE(PG8_SB(1, 0), b3, vB_); PG8_STAGE(PG8_SB(1, 1), b3 + hstep, vB_); PG8_STAGE(PG8_SA(1, 0), a3, vA_);
;             PG8_WAIT_V(8); PG8_WAIT_L(0); PG8_BAR; PG8_MMA(1, 0, At, B0); PG8_MMA(1, 1, At, B1); PG8_BAR; PG8_SCHED;
	s_add_u32 s30, s38, 0x80
	s_addc_u32 s31, s39, 0
	s_add_i32 s40, s61, s33
	s_mov_b32 m0, s40
	ds_read_b128 v[168:171], v180 offset:49152
	ds_read_b128 v[172:175], v180 offset:50176
	ds_read_b128 v[176:179], v180 offset:51200
	ds_read_b128 v[182:185], v180 offset:52224
	ds_read_b128 v[186:189], v180 offset:53248
	ds_read_b128 v[190:193], v180 offset:54272
	ds_read_b128 v[194:197], v180 offset:55296
	ds_read_b128 v[198:201], v180 offset:56320
	s_nop 0
	global_load_lds_dwordx4 v203, s[30:31]
	s_add_i32 m0, s40, 0x2000
	s_nop 0
	global_load_lds_dwordx4 v181, s[30:31]
	s_add_u32 s30, s38, 0x100080
	s_addc_u32 s31, s39, 0
	s_add_i32 s38, s62, s33
	s_mov_b32 m0, s38
	s_nop 0
	global_load_lds_dwordx4 v203, s[30:31]
	s_add_i32 m0, s38, 0x2000
	s_nop 0
	global_load_lds_dwordx4 v181, s[30:31]
	s_mov_b32 m0, s53
	s_nop 0
	global_load_lds_dwordx4 v202, s[36:37]
	s_mov_b32 m0, s54
	s_nop 0
	global_load_lds_dwordx4 v204, s[36:37]
	s_waitcnt vmcnt(8)
	s_waitcnt lgkmcnt(0)
	s_barrier
	s_setprio 1
	s_waitcnt lgkmcnt(0)
	v_mfma_f32_16x16x32_bf16 v[92:95], v[128:131], v[168:171], v[92:95]
	v_mfma_f32_16x16x32_bf16 v[88:91], v[136:139], v[168:171], v[88:91]
	v_mfma_f32_16x16x32_bf16 v[84:87], v[128:131], v[176:179], v[84:87]
	v_mfma_f32_16x16x32_bf16 v[80:83], v[136:139], v[176:179], v[80:83]
	v_mfma_f32_16x16x32_bf16 v[76:79], v[128:131], v[186:189], v[76:79]
	v_mfma_f32_16x16x32_bf16 v[72:75], v[136:139], v[186:189], v[72:75]
	v_mfma_f32_16x16x32_bf16 v[68:71], v[128:131], v[194:197], v[68:71]
	v_mfma_f32_16x16x32_bf16 v[64:67], v[136:139], v[194:197], v[64:67]
	v_mfma_f32_16x16x32_bf16 v[92:95], v[132:135], v[172:175], v[92:95]
	v_mfma_f32_16x16x32_bf16 v[88:91], v[140:143], v[172:175], v[88:91]
	v_mfma_f32_16x16x32_bf16 v[84:87], v[132:135], v[182:185], v[84:87]
	v_mfma_f32_16x16x32_bf16 v[80:83], v[140:143], v[182:185], v[80:83]
	v_mfma_f32_16x16x32_bf16 v[76:79], v[132:135], v[190:193], v[76:79]
	v_mfma_f32_16x16x32_bf16 v[72:75], v[140:143], v[190:193], v[72:75]
	v_mfma_f32_16x16x32_bf16 v[68:71], v[132:135], v[198:201], v[68:71]
	v_mfma_f32_16x16x32_bf16 v[64:67], v[140:143], v[198:201], v[64:67]
	s_setprio 0
	s_setprio 1
	v_mfma_f32_16x16x32_bf16 v[28:31], v[144:147], v[168:171], v[28:31]
	v_mfma_f32_16x16x32_bf16 v[24:27], v[152:155], v[168:171], v[24:27]
	v_mfma_f32_16x16x32_bf16 v[20:23], v[144:147], v[176:179], v[20:23]
	v_mfma_f32_16x16x32_bf16 v[16:19], v[152:155], v[176:179], v[16:19]
	v_mfma_f32_16x16x32_bf16 v[12:15], v[144:147], v[186:189], v[12:15]
	v_mfma_f32_16x16x32_bf16 v[8:11], v[152:155], v[186:189], v[8:11]
	v_mfma_f32_16x16x32_bf16 v[4:7], v[144:147], v[194:197], v[4:7]
	v_mfma_f32_16x16x32_bf16 v[0:3], v[152:155], v[194:197], v[0:3]
	s_add_i32 s60, s60, 2
	s_add_u32 s58, s58, 0x100
	s_addc_u32 s59, s59, 0
	s_cmp_gt_u32 s60, 61
	s_mov_b64 s[30:31], s[34:35]
	v_mfma_f32_16x16x32_bf16 v[28:31], v[148:151], v[172:175], v[28:31]
	v_mfma_f32_16x16x32_bf16 v[24:27], v[164:167], v[172:175], v[24:27]
	v_mfma_f32_16x16x32_bf16 v[20:23], v[148:151], v[182:185], v[20:23]
	v_mfma_f32_16x16x32_bf16 v[16:19], v[164:167], v[182:185], v[16:19]
	v_mfma_f32_16x16x32_bf16 v[12:15], v[148:151], v[190:193], v[12:15]
	v_mfma_f32_16x16x32_bf16 v[8:11], v[164:167], v[190:193], v[8:11]
	v_mfma_f32_16x16x32_bf16 v[4:7], v[148:151], v[198:201], v[4:7]
	v_mfma_f32_16x16x32_bf16 v[0:3], v[164:167], v[198:201], v[0:3]
	s_setprio 0
	s_barrier
	s_cbranch_scc0 .LBB13_1187
	s_and_b64 vcc, exec, s[14:15]
	s_cbranch_vccz .LBB13_1190
	s_barrier

;     __device__ float mid(int row) const { return rg(row) / ra(row); }
; #define PG8_STAGE(bufoff, gbase, voff) do { const char* gb_ = (const char*)(gbase); asm volatile("" : "+s"(gb_));     \
;         _Pragma("unroll") for (int _i = 0; _i < 2; ++_i) \
;         __builtin_amdgcn_global_load_lds((const unsigned*)(gb_ + (voff)[_i]), (PG8_LAS unsigned*)(lds + (bufoff) + ldsw + _i * 8192), 16, 0, 0); } while (0)
; #define PG8_LDA(dst, b, h) do { _Pragma("unroll") for (int m = 0; m < 4; ++m) _Pragma("unroll") for (int k = 0; k < 2; ++k) dst[m][k] = *(const PG8_LAS bf16x8*)(lds + PG8_SA(b, h) + aoff + m * 2048 + k * 1024); } while (0)
; #define PG8_LDB(dst, b, h) do { _Pragma("unroll") for (int n = 0; n < 2; ++n) _Pragma("unroll") for (int k = 0; k < 2; ++k) dst[n][k] = *(const PG8_LAS bf16x8*)(lds + PG8_SB(b, h) + boff + n * 2048 + k * 1024); } while (0)
; #define PG8_WAIT_V(n) asm volatile("s_waitcnt vmcnt(" #n ")" ::: "memory")
; template <class Epi, class Sched, bool ALIGN_EPI = false, bool SP2 = false>
; __device__ __forceinline__ void gemm_phase(PG8_LAS unsigned char* lds, const Gemm g, const Sched& S, const Epi& E, int wid0) {
;     ...
;         for (int t = 0; t < nt; t += 2) {
;             const bool last = (t == nt - 2);
;             const char* a1 = cA + (size_t)(t + 1) * kstep;
;             const char* a2 = last ? nA : cA + (size_t)(t + 2) * kstep; const char* b2 = last ? nB : cB + (size_t)(t + 2) * kstep;
;             const char* a3 = a2 + kstep; const char* b3 = b2 + kstep;
;             if (last && has_next) S.a_ready(nxt);
;             if constexpr (Epi::HAS_MID) { if (t == Epi::MID_T) E.mid(acc, cur, wr, fr); }
;             unsigned vA_[2] = {voffA[0], voffA[1]}, vB_[2] = {voffB[0], voffB[1]};
;             asm volatile("" : "+v"(vA_[0]), "+v"(vA_[1]), "+v"(vB_[0]), "+v"(vB_[1]));
;             if constexpr (SP2) {
;             PG8_LDB(B0, 0, 0); PG8_LDB(B1, 0, 1); PG8_SCHED; PG8_LDA(At, 0, 0); PG8_STAGE(PG8_SA(1, 1), a1 + hstepA, vA_);
;             PG8_WAIT_V(8); PG8_WAIT_L(0); PG8_BAR; PG8_MMA(0, 0, At, B0); PG8_MMA(0, 1, At, B1); PG8_BAR; PG8_SCHED;
;             PG8_LDA(At, 0, 1); PG8_STAGE(PG8_SB(0, 0), b2, vB_); PG8_STAGE(PG8_SB(0, 1), b2 + hstep, vB_); PG8_STAGE(PG8_SA(0, 0), a2, vA_);
;             PG8_WAIT_V(8); PG8_WAIT_L(0); PG8_BAR; PG8_MMA(1, 0, At, B0); PG8_MMA(1, 1, At, B1); PG8_BAR; PG8_SCHED;
.LBB13_1336:
	v_mov_b32_e32 v8, v178
	v_mov_b32_e32 v220, v174
	v_mov_b32_e32 v221, v200
	v_mov_b32_e32 v222, v176
	ds_read_b128 v[82:85], v201
	ds_read_b128 v[90:93], v201 offset:1024
	ds_read_b128 v[94:97], v201 offset:2048
	ds_read_b128 v[102:105], v201 offset:3072
	ds_read_b128 v[158:161], v202
	ds_read_b128 v[162:165], v202 offset:1024
	ds_read_b128 v[166:169], v202 offset:2048
	ds_read_b128 v[170:173], v202 offset:3072
	s_add_u32 s8, s2, 0x100
	s_addc_u32 s9, s3, 0
	s_cmp_eq_u32 s82, 12
	s_cselect_b32 s58, s78, s8
	s_cselect_b32 s59, s47, s9
	s_cselect_b32 s12, s79, s80
	s_cselect_b32 s13, s49, s81
	s_add_u32 s10, s58, 0x80
	s_addc_u32 s11, s59, 0
	s_add_u32 s2, s2, 0x40080
	s_addc_u32 s3, s3, 0
	s_add_i32 m0, s57, 0xc000
	ds_read_b128 v[180:183], v203
	ds_read_b128 v[184:187], v203 offset:1024
	ds_read_b128 v[188:191], v203 offset:2048
	ds_read_b128 v[192:195], v203 offset:3072
	ds_read_b128 v[204:207], v203 offset:4096
	ds_read_b128 v[208:211], v203 offset:5120
	ds_read_b128 v[212:215], v203 offset:6144
	ds_read_b128 v[216:219], v203 offset:7168
	s_nop 0
	global_load_lds_dwordx4 v220, s[2:3]
	s_add_i32 m0, s57, 0xe000
	s_nop 0
	global_load_lds_dwordx4 v222, s[2:3]
	s_waitcnt vmcnt(8)
	s_waitcnt lgkmcnt(0)
	s_barrier
	s_setprio 1
	s_waitcnt lgkmcnt(0)
	v_mfma_f32_16x16x32_bf16 v[154:157], v[82:85], v[180:183], v[154:157]
	v_mfma_f32_16x16x32_bf16 v[150:153], v[94:97], v[180:183], v[150:153]
	v_mfma_f32_16x16x32_bf16 v[138:141], v[82:85], v[188:191], v[138:141]
	v_mfma_f32_16x16x32_bf16 v[134:137], v[94:97], v[188:191], v[134:137]
	v_mfma_f32_16x16x32_bf16 v[122:125], v[82:85], v[204:207], v[122:125]
	v_mfma_f32_16x16x32_bf16 v[118:121], v[94:97], v[204:207], v[118:121]
	v_mfma_f32_16x16x32_bf16 v[106:109], v[82:85], v[212:215], v[106:109]
	v_mfma_f32_16x16x32_bf16 v[98:101], v[94:97], v[212:215], v[98:101]
	v_mfma_f32_16x16x32_bf16 v[154:157], v[90:93], v[184:187], v[154:157]
	v_mfma_f32_16x16x32_bf16 v[150:153], v[102:105], v[184:187], v[150:153]
	v_mfma_f32_16x16x32_bf16 v[138:141], v[90:93], v[192:195], v[138:141]
	v_mfma_f32_16x16x32_bf16 v[134:137], v[102:105], v[192:195], v[134:137]
	v_mfma_f32_16x16x32_bf16 v[122:125], v[90:93], v[208:211], v[122:125]
	v_mfma_f32_16x16x32_bf16 v[118:121], v[102:105], v[208:211], v[118:121]
	v_mfma_f32_16x16x32_bf16 v[106:109], v[90:93], v[216:219], v[106:109]
	v_mfma_f32_16x16x32_bf16 v[98:101], v[102:105], v[216:219], v[98:101]
	s_setprio 0
	s_setprio 1
	v_mfma_f32_16x16x32_bf16 v[146:149], v[158:161], v[180:183], v[146:149]
	v_mfma_f32_16x16x32_bf16 v[142:145], v[166:169], v[180:183], v[142:145]
	v_mfma_f32_16x16x32_bf16 v[130:133], v[158:161], v[188:191], v[130:133]
	v_mfma_f32_16x16x32_bf16 v[126:129], v[166:169], v[188:191], v[126:129]
	v_mfma_f32_16x16x32_bf16 v[114:117], v[158:161], v[204:207], v[114:117]
	v_mfma_f32_16x16x32_bf16 v[110:113], v[166:169], v[204:207], v[110:113]
	v_mfma_f32_16x16x32_bf16 v[86:89], v[158:161], v[212:215], v[86:89]
	v_mfma_f32_16x16x32_bf16 v[78:81], v[166:169], v[212:215], v[78:81]
	v_mfma_f32_16x16x32_bf16 v[146:149], v[162:165], v[184:187], v[146:149]
	v_mfma_f32_16x16x32_bf16 v[142:145], v[170:173], v[184:187], v[142:145]
	v_mfma_f32_16x16x32_bf16 v[130:133], v[162:165], v[192:195], v[130:133]
	v_mfma_f32_16x16x32_bf16 v[126:129], v[170:173], v[192:195], v[126:129]
	v_mfma_f32_16x16x32_bf16 v[114:117], v[162:165], v[208:211], v[114:117]
	v_mfma_f32_16x16x32_bf16 v[110:113], v[170:173], v[208:211], v[110:113]
	v_mfma_f32_16x16x32_bf16 v[86:89], v[162:165], v[216:219], v[86:89]
	v_mfma_f32_16x16x32_bf16 v[78:81], v[170:173], v[216:219], v[78:81]
	s_setprio 0
	s_barrier
	s_add_i32 s83, s75, s55
	s_mov_b64 s[2:3], s[12:13]
	s_mov_b32 m0, s83
	ds_read_b128 v[180:183], v203 offset:16384
	ds_read_b128 v[184:187], v203 offset:17408
	ds_read_b128 v[188:191], v203 offset:18432
	ds_read_b128 v[192:195], v203 offset:19456
	ds_read_b128 v[204:207], v203 offset:20480
	ds_read_b128 v[208:211], v203 offset:21504
	ds_read_b128 v[212:215], v203 offset:22528
	ds_read_b128 v[216:219], v203 offset:23552
	s_nop 0
	global_load_lds_dwordx4 v221, s[2:3]
	s_add_i32 m0, s83, 0x2000
	s_nop 0
	global_load_lds_dwordx4 v8, s[2:3]
	s_add_u32 s2, s12, 0x40000
	s_addc_u32 s3, s13, 0
	s_add_i32 s83, s76, s55
	s_mov_b32 m0, s83
	s_nop 0
	global_load_lds_dwordx4 v221, s[2:3]
	s_add_i32 m0, s83, 0x2000
	s_nop 0
	global_load_lds_dwordx4 v8, s[2:3]
	s_mov_b64 s[2:3], s[58:59]
	s_mov_b32 m0, s57
	s_nop 0
	global_load_lds_dwordx4 v220, s[2:3]
	s_mov_b32 m0, s64
	s_nop 0
	global_load_lds_dwordx4 v222, s[2:3]
	s_waitcnt vmcnt(8)
	s_waitcnt lgkmcnt(0)
	s_barrier
; #define PG8_STAGE(bufoff, gbase, voff) do { const char* gb_ = (const char*)(gbase); asm volatile("" : "+s"(gb_));     \
;         _Pragma("unroll") for (int _i = 0; _i < 2; ++_i) \
;         __builtin_amdgcn_global_load_lds((const unsigned*)(gb_ + (voff)[_i]), (PG8_LAS unsigned*)(lds + (bufoff) + ldsw + _i * 8192), 16, 0, 0); } while (0)
; #define PG8_LDA(dst, b, h) do { _Pragma("unroll") for (int m = 0; m < 4; ++m) _Pragma("unroll") for (int k = 0; k < 2; ++k) dst[m][k] = *(const PG8_LAS bf16x8*)(lds + PG8_SA(b, h) + aoff + m * 2048 + k * 1024); } while (0)
; #define PG8_LDB(dst, b, h) do { _Pragma("unroll") for (int n = 0; n < 2; ++n) _Pragma("unroll") for (int k = 0; k < 2; ++k) dst[n][k] = *(const PG8_LAS bf16x8*)(lds + PG8_SB(b, h) + boff + n * 2048 + k * 1024); } while (0)
; #define PG8_MMA(ai, bj, At, Bt) do { __builtin_amdgcn_s_setprio(1); _Pragma("unroll") for (int m = 0; m < 4; ++m) _Pragma("unroll") for (int n = 0; n < 2; ++n) _Pragma("unroll") for (int k = 0; k < 2; ++k) \
;         acc[ai][bj][m][n] = __builtin_amdgcn_mfma_f32_16x16x32_bf16(Bt[n][k], At[m][k], acc[ai][bj][m][n], 0, 0, 0); __builtin_amdgcn_s_setprio(0); } while (0)
; #define PG8_WAIT_V(n) asm volatile("s_waitcnt vmcnt(" #n ")" ::: "memory")
; #define PG8_WAIT_L(n) asm volatile("s_waitcnt lgkmcnt(" #n ")" ::: "memory")
; #define PG8_BAR __builtin_amdgcn_s_barrier()
; #define PG8_SCHED __builtin_amdgcn_sched_barrier(0)
; template <class Epi, class Sched, bool ALIGN_EPI = false, bool SP2 = false>
; __device__ __forceinline__ void gemm_phase(PG8_LAS unsigned char* lds, const Gemm g, const Sched& S, const Epi& E, int wid0) {
;     ...
;             PG8_WAIT_V(8); PG8_WAIT_L(0); PG8_BAR; PG8_MMA(1, 0, At, B0); PG8_MMA(1, 1, At, B1); PG8_BAR; PG8_SCHED;
;             PG8_LDB(B0, 1, 0); PG8_LDB(B1, 1, 1); PG8_SCHED; PG8_LDA(At, 1, 0); PG8_STAGE(PG8_SA(0, 1), a2 + hstepA, vA_);
;             PG8_WAIT_V(8); PG8_WAIT_L(0); PG8_BAR; PG8_MMA(0, 0, At, B0); PG8_MMA(0, 1, At, B1); PG8_BAR; PG8_SCHED;
	s_setprio 1
	s_waitcnt lgkmcnt(0)
	v_mfma_f32_16x16x32_bf16 v[74:77], v[82:85], v[180:183], v[74:77]
	v_mfma_f32_16x16x32_bf16 v[70:73], v[94:97], v[180:183], v[70:73]
	v_mfma_f32_16x16x32_bf16 v[58:61], v[82:85], v[188:191], v[58:61]
	v_mfma_f32_16x16x32_bf16 v[54:57], v[94:97], v[188:191], v[54:57]
	v_mfma_f32_16x16x32_bf16 v[42:45], v[82:85], v[204:207], v[42:45]
	v_mfma_f32_16x16x32_bf16 v[38:41], v[94:97], v[204:207], v[38:41]
	v_mfma_f32_16x16x32_bf16 v[26:29], v[82:85], v[212:215], v[26:29]
	v_mfma_f32_16x16x32_bf16 v[22:25], v[94:97], v[212:215], v[22:25]
	v_mfma_f32_16x16x32_bf16 v[74:77], v[90:93], v[184:187], v[74:77]
	v_mfma_f32_16x16x32_bf16 v[70:73], v[102:105], v[184:187], v[70:73]
	v_mfma_f32_16x16x32_bf16 v[58:61], v[90:93], v[192:195], v[58:61]
	v_mfma_f32_16x16x32_bf16 v[54:57], v[102:105], v[192:195], v[54:57]
	v_mfma_f32_16x16x32_bf16 v[42:45], v[90:93], v[208:211], v[42:45]
	v_mfma_f32_16x16x32_bf16 v[38:41], v[102:105], v[208:211], v[38:41]
	v_mfma_f32_16x16x32_bf16 v[26:29], v[90:93], v[216:219], v[26:29]
	v_mfma_f32_16x16x32_bf16 v[22:25], v[102:105], v[216:219], v[22:25]
	s_setprio 0
	s_setprio 1
	v_mfma_f32_16x16x32_bf16 v[66:69], v[158:161], v[180:183], v[66:69]
	v_mfma_f32_16x16x32_bf16 v[62:65], v[166:169], v[180:183], v[62:65]
	v_mfma_f32_16x16x32_bf16 v[50:53], v[158:161], v[188:191], v[50:53]
	v_mfma_f32_16x16x32_bf16 v[46:49], v[166:169], v[188:191], v[46:49]
	v_mfma_f32_16x16x32_bf16 v[34:37], v[158:161], v[204:207], v[34:37]
	v_mfma_f32_16x16x32_bf16 v[30:33], v[166:169], v[204:207], v[30:33]
	v_mfma_f32_16x16x32_bf16 v[18:21], v[158:161], v[212:215], v[18:21]
	v_mfma_f32_16x16x32_bf16 v[14:17], v[166:169], v[212:215], v[14:17]
	v_mfma_f32_16x16x32_bf16 v[66:69], v[162:165], v[184:187], v[66:69]
	v_mfma_f32_16x16x32_bf16 v[62:65], v[170:173], v[184:187], v[62:65]
	v_mfma_f32_16x16x32_bf16 v[50:53], v[162:165], v[192:195], v[50:53]
	v_mfma_f32_16x16x32_bf16 v[46:49], v[170:173], v[192:195], v[46:49]
	v_mfma_f32_16x16x32_bf16 v[34:37], v[162:165], v[208:211], v[34:37]
	v_mfma_f32_16x16x32_bf16 v[30:33], v[170:173], v[208:211], v[30:33]
	v_mfma_f32_16x16x32_bf16 v[18:21], v[162:165], v[216:219], v[18:21]
	v_mfma_f32_16x16x32_bf16 v[14:17], v[170:173], v[216:219], v[14:17]
	s_setprio 0
	s_barrier
	s_add_i32 s83, 0, 0x18000
	s_add_i32 s84, 0, 0x1c000
	v_add_u32_e32 v102, s83, v175
	v_add_u32_e32 v170, s84, v175
	ds_read_b128 v[82:85], v102
	ds_read_b128 v[90:93], v102 offset:1024
	ds_read_b128 v[94:97], v102 offset:2048
	ds_read_b128 v[102:105], v102 offset:3072
	ds_read_b128 v[158:161], v170
	ds_read_b128 v[162:165], v170 offset:1024
	ds_read_b128 v[166:169], v170 offset:2048
	ds_read_b128 v[170:173], v170 offset:3072
	s_add_u32 s2, s58, 0x40000
	s_addc_u32 s3, s59, 0
	s_mov_b32 m0, s65
	ds_read_b128 v[180:183], v203 offset:32768
	ds_read_b128 v[184:187], v203 offset:33792
	ds_read_b128 v[188:191], v203 offset:34816
	ds_read_b128 v[192:195], v203 offset:35840
	ds_read_b128 v[204:207], v203 offset:36864
	ds_read_b128 v[208:211], v203 offset:37888
	ds_read_b128 v[212:215], v203 offset:38912
	ds_read_b128 v[216:219], v203 offset:39936
	s_nop 0
	global_load_lds_dwordx4 v220, s[2:3]
	s_mov_b32 m0, s66
	s_nop 0
	global_load_lds_dwordx4 v222, s[2:3]
	s_waitcnt vmcnt(8)
	s_waitcnt lgkmcnt(0)
	s_barrier
	s_setprio 1
	s_waitcnt lgkmcnt(0)
	v_mfma_f32_16x16x32_bf16 v[154:157], v[82:85], v[180:183], v[154:157]
	v_mfma_f32_16x16x32_bf16 v[150:153], v[94:97], v[180:183], v[150:153]
	v_mfma_f32_16x16x32_bf16 v[138:141], v[82:85], v[188:191], v[138:141]
	v_mfma_f32_16x16x32_bf16 v[134:137], v[94:97], v[188:191], v[134:137]
	v_mfma_f32_16x16x32_bf16 v[122:125], v[82:85], v[204:207], v[122:125]
	v_mfma_f32_16x16x32_bf16 v[118:121], v[94:97], v[204:207], v[118:121]
	v_mfma_f32_16x16x32_bf16 v[106:109], v[82:85], v[212:215], v[106:109]
	v_mfma_f32_16x16x32_bf16 v[98:101], v[94:97], v[212:215], v[98:101]
	v_mfma_f32_16x16x32_bf16 v[154:157], v[90:93], v[184:187], v[154:157]
	v_mfma_f32_16x16x32_bf16 v[150:153], v[102:105], v[184:187], v[150:153]
	v_mfma_f32_16x16x32_bf16 v[138:141], v[90:93], v[192:195], v[138:141]
	v_mfma_f32_16x16x32_bf16 v[134:137], v[102:105], v[192:195], v[134:137]
	v_mfma_f32_16x16x32_bf16 v[122:125], v[90:93], v[208:211], v[122:125]
	v_mfma_f32_16x16x32_bf16 v[118:121], v[102:105], v[208:211], v[118:121]
	v_mfma_f32_16x16x32_bf16 v[106:109], v[90:93], v[216:219], v[106:109]
	v_mfma_f32_16x16x32_bf16 v[98:101], v[102:105], v[216:219], v[98:101]
	s_setprio 0
	s_setprio 1
	v_mfma_f32_16x16x32_bf16 v[146:149], v[158:161], v[180:183], v[146:149]
	v_mfma_f32_16x16x32_bf16 v[142:145], v[166:169], v[180:183], v[142:145]
	v_mfma_f32_16x16x32_bf16 v[130:133], v[158:161], v[188:191], v[130:133]
	v_mfma_f32_16x16x32_bf16 v[126:129], v[166:169], v[188:191], v[126:129]
	v_mfma_f32_16x16x32_bf16 v[114:117], v[158:161], v[204:207], v[114:117]
	v_mfma_f32_16x16x32_bf16 v[110:113], v[166:169], v[204:207], v[110:113]
	v_mfma_f32_16x16x32_bf16 v[86:89], v[158:161], v[212:215], v[86:89]
	v_mfma_f32_16x16x32_bf16 v[78:81], v[166:169], v[212:215], v[78:81]
	v_mfma_f32_16x16x32_bf16 v[146:149], v[162:165], v[184:187], v[146:149]
	v_mfma_f32_16x16x32_bf16 v[142:145], v[170:173], v[184:187], v[142:145]
	v_mfma_f32_16x16x32_bf16 v[130:133], v[162:165], v[192:195], v[130:133]
	v_mfma_f32_16x16x32_bf16 v[126:129], v[170:173], v[192:195], v[126:129]
	v_mfma_f32_16x16x32_bf16 v[114:117], v[162:165], v[208:211], v[114:117]
	v_mfma_f32_16x16x32_bf16 v[110:113], v[170:173], v[208:211], v[110:113]
	v_mfma_f32_16x16x32_bf16 v[86:89], v[162:165], v[216:219], v[86:89]
	v_mfma_f32_16x16x32_bf16 v[78:81], v[170:173], v[216:219], v[78:81]
	s_setprio 0
	s_barrier
;     __device__ float mid(int row) const { return rg(row) / ra(row); }
; #define PG8_STAGE(bufoff, gbase, voff) do { const char* gb_ = (const char*)(gbase); asm volatile("" : "+s"(gb_));     \
;         _Pragma("unroll") for (int _i = 0; _i < 2; ++_i) \
;         __builtin_amdgcn_global_load_lds((const unsigned*)(gb_ + (voff)[_i]), (PG8_LAS unsigned*)(lds + (bufoff) + ldsw + _i * 8192), 16, 0, 0); } while (0)
; #define PG8_BAR __builtin_amdgcn_s_barrier()
; template <class Epi, class Sched, bool ALIGN_EPI = false, bool SP2 = false>
; __device__ __forceinline__ void gemm_phase(PG8_LAS unsigned char* lds, const Gemm g, const Sched& S, const Epi& E, int wid0) {
;     ...
;         for (int t = 0; t < nt; t += 2) {
;             const bool last = (t == nt - 2);
;             const char* a1 = cA + (size_t)(t + 1) * kstep;
;             const char* a2 = last ? nA : cA + (size_t)(t + 2) * kstep; const char* b2 = last ? nB : cB + (size_t)(t + 2) * kstep;
;             const char* a3 = a2 + kstep; const char* b3 = b2 + kstep;
;             if (last && has_next) S.a_ready(nxt);
;             if constexpr (Epi::HAS_MID) { if (t == Epi::MID_T) E.mid(acc, cur, wr, fr); }
;             unsigned vA_[2] = {voffA[0], voffA[1]}, vB_[2] = {voffB[0], voffB[1]};
;             asm volatile("" : "+v"(vA_[0]), "+v"(vA_[1]), "+v"(vB_[0]), "+v"(vB_[1]));
;             if constexpr (SP2) {
;             PG8_LDB(B0, 0, 0); PG8_LDB(B1, 0, 1); PG8_SCHED; PG8_LDA(At, 0, 0); PG8_STAGE(PG8_SA(1, 1), a1 + hstepA, vA_);
;             PG8_WAIT_V(8); PG8_WAIT_L(0); PG8_BAR; PG8_MMA(0, 0, At, B0); PG8_MMA(0, 1, At, B1); PG8_BAR; PG8_SCHED;
;             PG8_LDA(At, 0, 1); PG8_STAGE(PG8_SB(0, 0), b2, vB_); PG8_STAGE(PG8_SB(0, 1), b2 + hstep, vB_); PG8_STAGE(PG8_SA(0, 0), a2, vA_);
;             PG8_WAIT_V(8); PG8_WAIT_L(0); PG8_BAR; PG8_MMA(1, 0, At, B0); PG8_MMA(1, 1, At, B1); PG8_BAR; PG8_SCHED;
;             PG8_LDB(B0, 1, 0); PG8_LDB(B1, 1, 1); PG8_SCHED; PG8_LDA(At, 1, 0); PG8_STAGE(PG8_SA(0, 1), a2 + hstepA, vA_);
;             PG8_WAIT_V(8); PG8_WAIT_L(0); PG8_BAR; PG8_MMA(0, 0, At, B0); PG8_MMA(0, 1, At, B1); PG8_BAR; PG8_SCHED;
;             PG8_LDA(At, 1, 1); PG8_STAGE(PG8_SB(1, 0), b3, vB_); PG8_STAGE(PG8_SB(1, 1), b3 + hstep, vB_); PG8_STAGE(PG8_SA(1, 0), a3, vA_);
;             PG8_WAIT_V(8); PG8_WAIT_L(0); PG8_BAR; PG8_MMA(1, 0, At, B0); PG8_MMA(1, 1, At, B1); PG8_BAR; PG8_SCHED;
	s_add_u32 s2, s12, 0x80
	s_addc_u32 s3, s13, 0
	s_add_i32 s58, s83, s55
	s_mov_b32 m0, s58
	ds_read_b128 v[180:183], v203 offset:49152
	ds_read_b128 v[184:187], v203 offset:50176
	ds_read_b128 v[188:191], v203 offset:51200
	ds_read_b128 v[192:195], v203 offset:52224
	ds_read_b128 v[204:207], v203 offset:53248
	ds_read_b128 v[208:211], v203 offset:54272
	ds_read_b128 v[212:215], v203 offset:55296
	ds_read_b128 v[216:219], v203 offset:56320
	s_nop 0
	global_load_lds_dwordx4 v221, s[2:3]
	s_add_i32 m0, s58, 0x2000
	s_nop 0
	global_load_lds_dwordx4 v8, s[2:3]
	s_add_u32 s2, s12, 0x40080
	s_addc_u32 s3, s13, 0
	s_add_i32 s12, s84, s55
	s_mov_b32 m0, s12
	s_nop 0
	global_load_lds_dwordx4 v221, s[2:3]
	s_add_i32 m0, s12, 0x2000
	s_nop 0
	global_load_lds_dwordx4 v8, s[2:3]
	s_mov_b32 m0, s69
	s_nop 0
	global_load_lds_dwordx4 v220, s[10:11]
	s_mov_b32 m0, s70
	s_nop 0
	global_load_lds_dwordx4 v222, s[10:11]
	s_waitcnt vmcnt(8)
	s_waitcnt lgkmcnt(0)
	s_barrier
	s_setprio 1
	s_waitcnt lgkmcnt(0)
	v_mfma_f32_16x16x32_bf16 v[74:77], v[82:85], v[180:183], v[74:77]
	v_mfma_f32_16x16x32_bf16 v[70:73], v[94:97], v[180:183], v[70:73]
	v_mfma_f32_16x16x32_bf16 v[58:61], v[82:85], v[188:191], v[58:61]
	v_mfma_f32_16x16x32_bf16 v[54:57], v[94:97], v[188:191], v[54:57]
	v_mfma_f32_16x16x32_bf16 v[42:45], v[82:85], v[204:207], v[42:45]
	v_mfma_f32_16x16x32_bf16 v[38:41], v[94:97], v[204:207], v[38:41]
	v_mfma_f32_16x16x32_bf16 v[26:29], v[82:85], v[212:215], v[26:29]
	v_mfma_f32_16x16x32_bf16 v[22:25], v[94:97], v[212:215], v[22:25]
	v_mfma_f32_16x16x32_bf16 v[74:77], v[90:93], v[184:187], v[74:77]
	v_mfma_f32_16x16x32_bf16 v[70:73], v[102:105], v[184:187], v[70:73]
	v_mfma_f32_16x16x32_bf16 v[58:61], v[90:93], v[192:195], v[58:61]
	v_mfma_f32_16x16x32_bf16 v[54:57], v[102:105], v[192:195], v[54:57]
	v_mfma_f32_16x16x32_bf16 v[42:45], v[90:93], v[208:211], v[42:45]
	v_mfma_f32_16x16x32_bf16 v[38:41], v[102:105], v[208:211], v[38:41]
	v_mfma_f32_16x16x32_bf16 v[26:29], v[90:93], v[216:219], v[26:29]
	v_mfma_f32_16x16x32_bf16 v[22:25], v[102:105], v[216:219], v[22:25]
	s_setprio 0
	s_setprio 1
	v_mfma_f32_16x16x32_bf16 v[66:69], v[158:161], v[180:183], v[66:69]
	v_mfma_f32_16x16x32_bf16 v[62:65], v[166:169], v[180:183], v[62:65]
	v_mfma_f32_16x16x32_bf16 v[50:53], v[158:161], v[188:191], v[50:53]
	v_mfma_f32_16x16x32_bf16 v[46:49], v[166:169], v[188:191], v[46:49]
	v_mfma_f32_16x16x32_bf16 v[34:37], v[158:161], v[204:207], v[34:37]
	v_mfma_f32_16x16x32_bf16 v[30:33], v[166:169], v[204:207], v[30:33]
	v_mfma_f32_16x16x32_bf16 v[18:21], v[158:161], v[212:215], v[18:21]
	v_mfma_f32_16x16x32_bf16 v[14:17], v[166:169], v[212:215], v[14:17]
	s_add_i32 s82, s82, 2
	s_add_u32 s80, s80, 0x100
	s_addc_u32 s81, s81, 0
	s_cmp_gt_u32 s82, 13
	s_mov_b64 s[2:3], s[8:9]
	v_mfma_f32_16x16x32_bf16 v[66:69], v[162:165], v[184:187], v[66:69]
	v_mfma_f32_16x16x32_bf16 v[62:65], v[170:173], v[184:187], v[62:65]
	v_mfma_f32_16x16x32_bf16 v[50:53], v[162:165], v[192:195], v[50:53]
	v_mfma_f32_16x16x32_bf16 v[46:49], v[170:173], v[192:195], v[46:49]
	v_mfma_f32_16x16x32_bf16 v[34:37], v[162:165], v[208:211], v[34:37]
	v_mfma_f32_16x16x32_bf16 v[30:33], v[170:173], v[208:211], v[30:33]
	v_mfma_f32_16x16x32_bf16 v[18:21], v[162:165], v[216:219], v[18:21]
	v_mfma_f32_16x16x32_bf16 v[14:17], v[170:173], v[216:219], v[14:17]
	s_setprio 0
	s_barrier
	s_cbranch_scc0 .LBB13_1336
	s_and_b64 vcc, exec, s[42:43]
	s_cbranch_vccz .LBB13_1339
	s_barrier

;     __device__ float mid(int row) const { return rg(row) / ra(row); }
; #define PG8_STAGE(bufoff, gbase, voff) do { const char* gb_ = (const char*)(gbase); asm volatile("" : "+s"(gb_));     \
;         _Pragma("unroll") for (int _i = 0; _i < 2; ++_i) \
;         __builtin_amdgcn_global_load_lds((const unsigned*)(gb_ + (voff)[_i]), (PG8_LAS unsigned*)(lds + (bufoff) + ldsw + _i * 8192), 16, 0, 0); } while (0)
; #define PG8_LDA(dst, b, h) do { _Pragma("unroll") for (int m = 0; m < 4; ++m) _Pragma("unroll") for (int k = 0; k < 2; ++k) dst[m][k] = *(const PG8_LAS bf16x8*)(lds + PG8_SA(b, h) + aoff + m * 2048 + k * 1024); } while (0)
; #define PG8_LDB(dst, b, h) do { _Pragma("unroll") for (int n = 0; n < 2; ++n) _Pragma("unroll") for (int k = 0; k < 2; ++k) dst[n][k] = *(const PG8_LAS bf16x8*)(lds + PG8_SB(b, h) + boff + n * 2048 + k * 1024); } while (0)
; #define PG8_WAIT_V(n) asm volatile("s_waitcnt vmcnt(" #n ")" ::: "memory")
; template <class Epi, class Sched, bool ALIGN_EPI = false, bool SP2 = false>
; __device__ __forceinline__ void gemm_phase(PG8_LAS unsigned char* lds, const Gemm g, const Sched& S, const Epi& E, int wid0) {
;     ...
;         for (int t = 0; t < nt; t += 2) {
;             const bool last = (t == nt - 2);
;             const char* a1 = cA + (size_t)(t + 1) * kstep;
;             const char* a2 = last ? nA : cA + (size_t)(t + 2) * kstep; const char* b2 = last ? nB : cB + (size_t)(t + 2) * kstep;
;             const char* a3 = a2 + kstep; const char* b3 = b2 + kstep;
;             if (last && has_next) S.a_ready(nxt);
;             if constexpr (Epi::HAS_MID) { if (t == Epi::MID_T) E.mid(acc, cur, wr, fr); }
;             unsigned vA_[2] = {voffA[0], voffA[1]}, vB_[2] = {voffB[0], voffB[1]};
;             asm volatile("" : "+v"(vA_[0]), "+v"(vA_[1]), "+v"(vB_[0]), "+v"(vB_[1]));
;             if constexpr (SP2) {
;             PG8_LDB(B0, 0, 0); PG8_LDB(B1, 0, 1); PG8_SCHED; PG8_LDA(At, 0, 0); PG8_STAGE(PG8_SA(1, 1), a1 + hstepA, vA_);
;             PG8_WAIT_V(8); PG8_WAIT_L(0); PG8_BAR; PG8_MMA(0, 0, At, B0); PG8_MMA(0, 1, At, B1); PG8_BAR; PG8_SCHED;
;             PG8_LDA(At, 0, 1); PG8_STAGE(PG8_SB(0, 0), b2, vB_); PG8_STAGE(PG8_SB(0, 1), b2 + hstep, vB_); PG8_STAGE(PG8_SA(0, 0), a2, vA_);
;             PG8_WAIT_V(8); PG8_WAIT_L(0); PG8_BAR; PG8_MMA(1, 0, At, B0); PG8_MMA(1, 1, At, B1); PG8_BAR; PG8_SCHED;
.LBB13_1920:
	v_mov_b32_e32 v9, v172
	v_mov_b32_e32 v170, v174
	v_mov_b32_e32 v171, v176
	v_mov_b32_e32 v182, v178
	v_add_u32_e32 v10, s62, v173
	ds_read_b128 v[142:145], v10
	ds_read_b128 v[146:149], v10 offset:1024
	ds_read_b128 v[150:153], v10 offset:2048
	ds_read_b128 v[154:157], v10 offset:3072
	v_add_u32_e32 v10, s63, v173
	s_add_u32 s6, s40, 0x100
	ds_read_b128 v[158:161], v10
	ds_read_b128 v[162:165], v10 offset:1024
	ds_read_b128 v[166:169], v10 offset:2048
	ds_read_b128 v[184:187], v10 offset:3072
	s_addc_u32 s7, s41, 0
	s_cmp_eq_u32 s68, 12
	s_cselect_b32 s48, s31, s6
	s_cselect_b32 s49, s27, s7
	s_cselect_b32 s43, s29, s67
	s_cselect_b32 s42, s65, s66
	s_add_u32 s44, s48, 0x80
	s_addc_u32 s45, s49, 0
	s_add_u32 s46, s42, 0x80
	s_addc_u32 s47, s43, 0
	s_add_u32 s40, s40, 0x80080
	s_addc_u32 s41, s41, 0
	s_add_i32 m0, s13, 0xc000
	ds_read_b128 v[188:191], v183
	ds_read_b128 v[192:195], v183 offset:1024
	ds_read_b128 v[196:199], v183 offset:2048
	ds_read_b128 v[200:203], v183 offset:3072
	ds_read_b128 v[204:207], v183 offset:4096
	ds_read_b128 v[208:211], v183 offset:5120
	ds_read_b128 v[212:215], v183 offset:6144
	ds_read_b128 v[216:219], v183 offset:7168
	s_nop 0
	global_load_lds_dwordx4 v9, s[40:41]
	s_add_i32 m0, s13, 0xe000
	s_nop 0
	global_load_lds_dwordx4 v171, s[40:41]
	s_waitcnt vmcnt(8)
	s_waitcnt lgkmcnt(0)
	s_barrier
	s_setprio 1
	s_waitcnt lgkmcnt(0)
	v_mfma_f32_16x16x32_bf16 v[136:139], v[142:145], v[188:191], v[136:139]
	v_mfma_f32_16x16x32_bf16 v[132:135], v[150:153], v[188:191], v[132:135]
	v_mfma_f32_16x16x32_bf16 v[128:131], v[142:145], v[196:199], v[128:131]
	v_mfma_f32_16x16x32_bf16 v[124:127], v[150:153], v[196:199], v[124:127]
	v_mfma_f32_16x16x32_bf16 v[120:123], v[142:145], v[204:207], v[120:123]
	v_mfma_f32_16x16x32_bf16 v[116:119], v[150:153], v[204:207], v[116:119]
	v_mfma_f32_16x16x32_bf16 v[112:115], v[142:145], v[212:215], v[112:115]
	v_mfma_f32_16x16x32_bf16 v[108:111], v[150:153], v[212:215], v[108:111]
	v_mfma_f32_16x16x32_bf16 v[136:139], v[146:149], v[192:195], v[136:139]
	v_mfma_f32_16x16x32_bf16 v[132:135], v[154:157], v[192:195], v[132:135]
	v_mfma_f32_16x16x32_bf16 v[128:131], v[146:149], v[200:203], v[128:131]
	v_mfma_f32_16x16x32_bf16 v[124:127], v[154:157], v[200:203], v[124:127]
	v_mfma_f32_16x16x32_bf16 v[120:123], v[146:149], v[208:211], v[120:123]
	v_mfma_f32_16x16x32_bf16 v[116:119], v[154:157], v[208:211], v[116:119]
	v_mfma_f32_16x16x32_bf16 v[112:115], v[146:149], v[216:219], v[112:115]
	v_mfma_f32_16x16x32_bf16 v[108:111], v[154:157], v[216:219], v[108:111]
	s_setprio 0
	s_setprio 1
	v_mfma_f32_16x16x32_bf16 v[72:75], v[158:161], v[188:191], v[72:75]
	v_mfma_f32_16x16x32_bf16 v[68:71], v[166:169], v[188:191], v[68:71]
	v_mfma_f32_16x16x32_bf16 v[64:67], v[158:161], v[196:199], v[64:67]
	v_mfma_f32_16x16x32_bf16 v[60:63], v[166:169], v[196:199], v[60:63]
	v_mfma_f32_16x16x32_bf16 v[56:59], v[158:161], v[204:207], v[56:59]
	v_mfma_f32_16x16x32_bf16 v[52:55], v[166:169], v[204:207], v[52:55]
	v_mfma_f32_16x16x32_bf16 v[48:51], v[158:161], v[212:215], v[48:51]
	v_mfma_f32_16x16x32_bf16 v[44:47], v[166:169], v[212:215], v[44:47]
	v_mfma_f32_16x16x32_bf16 v[72:75], v[162:165], v[192:195], v[72:75]
	v_mfma_f32_16x16x32_bf16 v[68:71], v[184:187], v[192:195], v[68:71]
	v_mfma_f32_16x16x32_bf16 v[64:67], v[162:165], v[200:203], v[64:67]
	v_mfma_f32_16x16x32_bf16 v[60:63], v[184:187], v[200:203], v[60:63]
	v_mfma_f32_16x16x32_bf16 v[56:59], v[162:165], v[208:211], v[56:59]
	v_mfma_f32_16x16x32_bf16 v[52:55], v[184:187], v[208:211], v[52:55]
	v_mfma_f32_16x16x32_bf16 v[48:51], v[162:165], v[216:219], v[48:51]
	v_mfma_f32_16x16x32_bf16 v[44:47], v[184:187], v[216:219], v[44:47]
	s_setprio 0
	s_barrier
	s_add_i32 s69, s62, s25
	s_mov_b64 s[40:41], s[42:43]
	s_mov_b32 m0, s69
	ds_read_b128 v[188:191], v183 offset:16384
	ds_read_b128 v[192:195], v183 offset:17408
	ds_read_b128 v[196:199], v183 offset:18432
	ds_read_b128 v[200:203], v183 offset:19456
	ds_read_b128 v[204:207], v183 offset:20480
	ds_read_b128 v[208:211], v183 offset:21504
	ds_read_b128 v[212:215], v183 offset:22528
	ds_read_b128 v[216:219], v183 offset:23552
	s_nop 0
	global_load_lds_dwordx4 v170, s[40:41]
	s_add_i32 m0, s69, 0x2000
	s_nop 0
	global_load_lds_dwordx4 v182, s[40:41]
	s_add_u32 s40, s42, 0x40000
	s_addc_u32 s41, s43, 0
	s_add_i32 s69, s63, s25
	s_mov_b32 m0, s69
	s_nop 0
	global_load_lds_dwordx4 v170, s[40:41]
	s_add_i32 m0, s69, 0x2000
	s_nop 0
	global_load_lds_dwordx4 v182, s[40:41]
	s_mov_b64 s[40:41], s[48:49]
	s_mov_b32 m0, s13
	s_nop 0
	global_load_lds_dwordx4 v9, s[40:41]
	s_mov_b32 m0, s51
	s_nop 0
	global_load_lds_dwordx4 v171, s[40:41]
	s_waitcnt vmcnt(8)
	s_waitcnt lgkmcnt(0)
	s_barrier
; #define PG8_STAGE(bufoff, gbase, voff) do { const char* gb_ = (const char*)(gbase); asm volatile("" : "+s"(gb_));     \
;         _Pragma("unroll") for (int _i = 0; _i < 2; ++_i) \
;         __builtin_amdgcn_global_load_lds((const unsigned*)(gb_ + (voff)[_i]), (PG8_LAS unsigned*)(lds + (bufoff) + ldsw + _i * 8192), 16, 0, 0); } while (0)
; #define PG8_LDA(dst, b, h) do { _Pragma("unroll") for (int m = 0; m < 4; ++m) _Pragma("unroll") for (int k = 0; k < 2; ++k) dst[m][k] = *(const PG8_LAS bf16x8*)(lds + PG8_SA(b, h) + aoff + m * 2048 + k * 1024); } while (0)
; #define PG8_LDB(dst, b, h) do { _Pragma("unroll") for (int n = 0; n < 2; ++n) _Pragma("unroll") for (int k = 0; k < 2; ++k) dst[n][k] = *(const PG8_LAS bf16x8*)(lds + PG8_SB(b, h) + boff + n * 2048 + k * 1024); } while (0)
; #define PG8_MMA(ai, bj, At, Bt) do { __builtin_amdgcn_s_setprio(1); _Pragma("unroll") for (int m = 0; m < 4; ++m) _Pragma("unroll") for (int n = 0; n < 2; ++n) _Pragma("unroll") for (int k = 0; k < 2; ++k) \
;         acc[ai][bj][m][n] = __builtin_amdgcn_mfma_f32_16x16x32_bf16(Bt[n][k], At[m][k], acc[ai][bj][m][n], 0, 0, 0); __builtin_amdgcn_s_setprio(0); } while (0)
; #define PG8_WAIT_V(n) asm volatile("s_waitcnt vmcnt(" #n ")" ::: "memory")
; #define PG8_WAIT_L(n) asm volatile("s_waitcnt lgkmcnt(" #n ")" ::: "memory")
; #define PG8_BAR __builtin_amdgcn_s_barrier()
; #define PG8_SCHED __builtin_amdgcn_sched_barrier(0)
; template <class Epi, class Sched, bool ALIGN_EPI = false, bool SP2 = false>
; __device__ __forceinline__ void gemm_phase(PG8_LAS unsigned char* lds, const Gemm g, const Sched& S, const Epi& E, int wid0) {
;     ...
;             PG8_WAIT_V(8); PG8_WAIT_L(0); PG8_BAR; PG8_MMA(1, 0, At, B0); PG8_MMA(1, 1, At, B1); PG8_BAR; PG8_SCHED;
;             PG8_LDB(B0, 1, 0); PG8_LDB(B1, 1, 1); PG8_SCHED; PG8_LDA(At, 1, 0); PG8_STAGE(PG8_SA(0, 1), a2 + hstepA, vA_);
;             PG8_WAIT_V(8); PG8_WAIT_L(0); PG8_BAR; PG8_MMA(0, 0, At, B0); PG8_MMA(0, 1, At, B1); PG8_BAR; PG8_SCHED;
	s_setprio 1
	s_waitcnt lgkmcnt(0)
	v_mfma_f32_16x16x32_bf16 v[104:107], v[142:145], v[188:191], v[104:107]
	v_mfma_f32_16x16x32_bf16 v[100:103], v[150:153], v[188:191], v[100:103]
	v_mfma_f32_16x16x32_bf16 v[96:99], v[142:145], v[196:199], v[96:99]
	v_mfma_f32_16x16x32_bf16 v[92:95], v[150:153], v[196:199], v[92:95]
	v_mfma_f32_16x16x32_bf16 v[88:91], v[142:145], v[204:207], v[88:91]
	v_mfma_f32_16x16x32_bf16 v[84:87], v[150:153], v[204:207], v[84:87]
	v_mfma_f32_16x16x32_bf16 v[80:83], v[142:145], v[212:215], v[80:83]
	v_mfma_f32_16x16x32_bf16 v[76:79], v[150:153], v[212:215], v[76:79]
	v_mfma_f32_16x16x32_bf16 v[104:107], v[146:149], v[192:195], v[104:107]
	v_mfma_f32_16x16x32_bf16 v[100:103], v[154:157], v[192:195], v[100:103]
	v_mfma_f32_16x16x32_bf16 v[96:99], v[146:149], v[200:203], v[96:99]
	v_mfma_f32_16x16x32_bf16 v[92:95], v[154:157], v[200:203], v[92:95]
	v_mfma_f32_16x16x32_bf16 v[88:91], v[146:149], v[208:211], v[88:91]
	v_mfma_f32_16x16x32_bf16 v[84:87], v[154:157], v[208:211], v[84:87]
	v_mfma_f32_16x16x32_bf16 v[80:83], v[146:149], v[216:219], v[80:83]
	v_mfma_f32_16x16x32_bf16 v[76:79], v[154:157], v[216:219], v[76:79]
	s_setprio 0
	s_setprio 1
	v_mfma_f32_16x16x32_bf16 v[40:43], v[158:161], v[188:191], v[40:43]
	v_mfma_f32_16x16x32_bf16 v[36:39], v[166:169], v[188:191], v[36:39]
	v_mfma_f32_16x16x32_bf16 v[32:35], v[158:161], v[196:199], v[32:35]
	v_mfma_f32_16x16x32_bf16 v[28:31], v[166:169], v[196:199], v[28:31]
	v_mfma_f32_16x16x32_bf16 v[24:27], v[158:161], v[204:207], v[24:27]
	v_mfma_f32_16x16x32_bf16 v[20:23], v[166:169], v[204:207], v[20:23]
	v_mfma_f32_16x16x32_bf16 v[16:19], v[158:161], v[212:215], v[16:19]
	v_mfma_f32_16x16x32_bf16 v[10:13], v[166:169], v[212:215], v[12:15]
	v_mfma_f32_16x16x32_bf16 v[40:43], v[162:165], v[192:195], v[40:43]
	v_mfma_f32_16x16x32_bf16 v[36:39], v[184:187], v[192:195], v[36:39]
	v_mfma_f32_16x16x32_bf16 v[32:35], v[162:165], v[200:203], v[32:35]
	v_mfma_f32_16x16x32_bf16 v[28:31], v[184:187], v[200:203], v[28:31]
	v_mfma_f32_16x16x32_bf16 v[24:27], v[162:165], v[208:211], v[24:27]
	v_mfma_f32_16x16x32_bf16 v[20:23], v[184:187], v[208:211], v[20:23]
	v_mfma_f32_16x16x32_bf16 v[16:19], v[162:165], v[216:219], v[16:19]
	v_mfma_f32_16x16x32_bf16 v[10:13], v[184:187], v[216:219], v[10:13]
	s_setprio 0
	s_barrier
	s_add_i32 s69, 0, 0x18000
	v_add_u32_e32 v14, s69, v173
	s_add_i32 s70, 0, 0x1c000
	ds_read_b128 v[142:145], v14
	ds_read_b128 v[146:149], v14 offset:1024
	ds_read_b128 v[150:153], v14 offset:2048
	ds_read_b128 v[154:157], v14 offset:3072
	v_add_u32_e32 v14, s70, v173
	ds_read_b128 v[158:161], v14
	ds_read_b128 v[162:165], v14 offset:1024
	ds_read_b128 v[166:169], v14 offset:2048
	ds_read_b128 v[184:187], v14 offset:3072
	s_add_u32 s40, s48, 0x80000
	s_addc_u32 s41, s49, 0
	s_mov_b32 m0, s52
	ds_read_b128 v[188:191], v183 offset:32768
	ds_read_b128 v[192:195], v183 offset:33792
	ds_read_b128 v[196:199], v183 offset:34816
	ds_read_b128 v[200:203], v183 offset:35840
	ds_read_b128 v[204:207], v183 offset:36864
	ds_read_b128 v[208:211], v183 offset:37888
	ds_read_b128 v[212:215], v183 offset:38912
	ds_read_b128 v[216:219], v183 offset:39936
	s_nop 0
	global_load_lds_dwordx4 v9, s[40:41]
	s_mov_b32 m0, s53
	s_nop 0
	global_load_lds_dwordx4 v171, s[40:41]
	s_waitcnt vmcnt(8)
	s_waitcnt lgkmcnt(0)
	s_barrier
	s_setprio 1
	s_waitcnt lgkmcnt(0)
	v_mfma_f32_16x16x32_bf16 v[136:139], v[142:145], v[188:191], v[136:139]
	v_mfma_f32_16x16x32_bf16 v[132:135], v[150:153], v[188:191], v[132:135]
	v_mfma_f32_16x16x32_bf16 v[128:131], v[142:145], v[196:199], v[128:131]
	v_mfma_f32_16x16x32_bf16 v[124:127], v[150:153], v[196:199], v[124:127]
	v_mfma_f32_16x16x32_bf16 v[120:123], v[142:145], v[204:207], v[120:123]
	v_mfma_f32_16x16x32_bf16 v[116:119], v[150:153], v[204:207], v[116:119]
	v_mfma_f32_16x16x32_bf16 v[112:115], v[142:145], v[212:215], v[112:115]
	v_mfma_f32_16x16x32_bf16 v[108:111], v[150:153], v[212:215], v[108:111]
	v_mfma_f32_16x16x32_bf16 v[136:139], v[146:149], v[192:195], v[136:139]
	v_mfma_f32_16x16x32_bf16 v[132:135], v[154:157], v[192:195], v[132:135]
	v_mfma_f32_16x16x32_bf16 v[128:131], v[146:149], v[200:203], v[128:131]
	v_mfma_f32_16x16x32_bf16 v[124:127], v[154:157], v[200:203], v[124:127]
	v_mfma_f32_16x16x32_bf16 v[120:123], v[146:149], v[208:211], v[120:123]
	v_mfma_f32_16x16x32_bf16 v[116:119], v[154:157], v[208:211], v[116:119]
	v_mfma_f32_16x16x32_bf16 v[112:115], v[146:149], v[216:219], v[112:115]
	v_mfma_f32_16x16x32_bf16 v[108:111], v[154:157], v[216:219], v[108:111]
	s_setprio 0
	s_setprio 1
	v_mfma_f32_16x16x32_bf16 v[72:75], v[158:161], v[188:191], v[72:75]
	v_mfma_f32_16x16x32_bf16 v[68:71], v[166:169], v[188:191], v[68:71]
	v_mfma_f32_16x16x32_bf16 v[64:67], v[158:161], v[196:199], v[64:67]
	v_mfma_f32_16x16x32_bf16 v[60:63], v[166:169], v[196:199], v[60:63]
	v_mfma_f32_16x16x32_bf16 v[56:59], v[158:161], v[204:207], v[56:59]
	v_mfma_f32_16x16x32_bf16 v[52:55], v[166:169], v[204:207], v[52:55]
	v_mfma_f32_16x16x32_bf16 v[48:51], v[158:161], v[212:215], v[48:51]
	v_mfma_f32_16x16x32_bf16 v[44:47], v[166:169], v[212:215], v[44:47]
	v_mfma_f32_16x16x32_bf16 v[72:75], v[162:165], v[192:195], v[72:75]
	v_mfma_f32_16x16x32_bf16 v[68:71], v[184:187], v[192:195], v[68:71]
	v_mfma_f32_16x16x32_bf16 v[64:67], v[162:165], v[200:203], v[64:67]
	v_mfma_f32_16x16x32_bf16 v[60:63], v[184:187], v[200:203], v[60:63]
	v_mfma_f32_16x16x32_bf16 v[56:59], v[162:165], v[208:211], v[56:59]
	v_mfma_f32_16x16x32_bf16 v[52:55], v[184:187], v[208:211], v[52:55]
	v_mfma_f32_16x16x32_bf16 v[48:51], v[162:165], v[216:219], v[48:51]
	v_mfma_f32_16x16x32_bf16 v[44:47], v[184:187], v[216:219], v[44:47]
	s_setprio 0
	s_barrier
;     __device__ float mid(int row) const { return rg(row) / ra(row); }
; #define PG8_STAGE(bufoff, gbase, voff) do { const char* gb_ = (const char*)(gbase); asm volatile("" : "+s"(gb_));     \
;         _Pragma("unroll") for (int _i = 0; _i < 2; ++_i) \
;         __builtin_amdgcn_global_load_lds((const unsigned*)(gb_ + (voff)[_i]), (PG8_LAS unsigned*)(lds + (bufoff) + ldsw + _i * 8192), 16, 0, 0); } while (0)
; #define PG8_BAR __builtin_amdgcn_s_barrier()
; template <class Epi, class Sched, bool ALIGN_EPI = false, bool SP2 = false>
; __device__ __forceinline__ void gemm_phase(PG8_LAS unsigned char* lds, const Gemm g, const Sched& S, const Epi& E, int wid0) {
;     ...
;         for (int t = 0; t < nt; t += 2) {
;             const bool last = (t == nt - 2);
;             const char* a1 = cA + (size_t)(t + 1) * kstep;
;             const char* a2 = last ? nA : cA + (size_t)(t + 2) * kstep; const char* b2 = last ? nB : cB + (size_t)(t + 2) * kstep;
;             const char* a3 = a2 + kstep; const char* b3 = b2 + kstep;
;             if (last && has_next) S.a_ready(nxt);
;             if constexpr (Epi::HAS_MID) { if (t == Epi::MID_T) E.mid(acc, cur, wr, fr); }
;             unsigned vA_[2] = {voffA[0], voffA[1]}, vB_[2] = {voffB[0], voffB[1]};
;             asm volatile("" : "+v"(vA_[0]), "+v"(vA_[1]), "+v"(vB_[0]), "+v"(vB_[1]));
;             if constexpr (SP2) {
;             PG8_LDB(B0, 0, 0); PG8_LDB(B1, 0, 1); PG8_SCHED; PG8_LDA(At, 0, 0); PG8_STAGE(PG8_SA(1, 1), a1 + hstepA, vA_);
;             PG8_WAIT_V(8); PG8_WAIT_L(0); PG8_BAR; PG8_MMA(0, 0, At, B0); PG8_MMA(0, 1, At, B1); PG8_BAR; PG8_SCHED;
;             PG8_LDA(At, 0, 1); PG8_STAGE(PG8_SB(0, 0), b2, vB_); PG8_STAGE(PG8_SB(0, 1), b2 + hstep, vB_); PG8_STAGE(PG8_SA(0, 0), a2, vA_);
;             PG8_WAIT_V(8); PG8_WAIT_L(0); PG8_BAR; PG8_MMA(1, 0, At, B0); PG8_MMA(1, 1, At, B1); PG8_BAR; PG8_SCHED;
;             PG8_LDB(B0, 1, 0); PG8_LDB(B1, 1, 1); PG8_SCHED; PG8_LDA(At, 1, 0); PG8_STAGE(PG8_SA(0, 1), a2 + hstepA, vA_);
;             PG8_WAIT_V(8); PG8_WAIT_L(0); PG8_BAR; PG8_MMA(0, 0, At, B0); PG8_MMA(0, 1, At, B1); PG8_BAR; PG8_SCHED;
;             PG8_LDA(At, 1, 1); PG8_STAGE(PG8_SB(1, 0), b3, vB_); PG8_STAGE(PG8_SB(1, 1), b3 + hstep, vB_); PG8_STAGE(PG8_SA(1, 0), a3, vA_);
;             PG8_WAIT_V(8); PG8_WAIT_L(0); PG8_BAR; PG8_MMA(1, 0, At, B0); PG8_MMA(1, 1, At, B1); PG8_BAR; PG8_SCHED;
	s_add_i32 s40, s69, s25
	s_mov_b32 m0, s40
	ds_read_b128 v[188:191], v183 offset:49152
	ds_read_b128 v[192:195], v183 offset:50176
	ds_read_b128 v[196:199], v183 offset:51200
	ds_read_b128 v[200:203], v183 offset:52224
	ds_read_b128 v[204:207], v183 offset:53248
	ds_read_b128 v[208:211], v183 offset:54272
	ds_read_b128 v[212:215], v183 offset:55296
	ds_read_b128 v[216:219], v183 offset:56320
	s_nop 0
	global_load_lds_dwordx4 v170, s[46:47]
	s_add_i32 m0, s40, 0x2000
	s_add_u32 s40, s42, 0x40080
	s_addc_u32 s41, s43, 0
	s_add_i32 s42, s70, s25
	global_load_lds_dwordx4 v182, s[46:47]
	s_mov_b32 m0, s42
	s_nop 0
	global_load_lds_dwordx4 v170, s[40:41]
	s_add_i32 m0, s42, 0x2000
	s_nop 0
	global_load_lds_dwordx4 v182, s[40:41]
	s_mov_b32 m0, s57
	s_nop 0
	global_load_lds_dwordx4 v9, s[44:45]
	s_mov_b32 m0, s58
	s_nop 0
	global_load_lds_dwordx4 v171, s[44:45]
	s_waitcnt vmcnt(8)
	s_waitcnt lgkmcnt(0)
	s_barrier
	s_setprio 1
	s_waitcnt lgkmcnt(0)
	v_mfma_f32_16x16x32_bf16 v[104:107], v[142:145], v[188:191], v[104:107]
	v_mfma_f32_16x16x32_bf16 v[100:103], v[150:153], v[188:191], v[100:103]
	v_mfma_f32_16x16x32_bf16 v[96:99], v[142:145], v[196:199], v[96:99]
	v_mfma_f32_16x16x32_bf16 v[92:95], v[150:153], v[196:199], v[92:95]
	v_mfma_f32_16x16x32_bf16 v[88:91], v[142:145], v[204:207], v[88:91]
	v_mfma_f32_16x16x32_bf16 v[84:87], v[150:153], v[204:207], v[84:87]
	v_mfma_f32_16x16x32_bf16 v[80:83], v[142:145], v[212:215], v[80:83]
	v_mfma_f32_16x16x32_bf16 v[76:79], v[150:153], v[212:215], v[76:79]
	v_mfma_f32_16x16x32_bf16 v[104:107], v[146:149], v[192:195], v[104:107]
	v_mfma_f32_16x16x32_bf16 v[100:103], v[154:157], v[192:195], v[100:103]
	v_mfma_f32_16x16x32_bf16 v[96:99], v[146:149], v[200:203], v[96:99]
	v_mfma_f32_16x16x32_bf16 v[92:95], v[154:157], v[200:203], v[92:95]
	v_mfma_f32_16x16x32_bf16 v[88:91], v[146:149], v[208:211], v[88:91]
	v_mfma_f32_16x16x32_bf16 v[84:87], v[154:157], v[208:211], v[84:87]
	v_mfma_f32_16x16x32_bf16 v[80:83], v[146:149], v[216:219], v[80:83]
	v_mfma_f32_16x16x32_bf16 v[76:79], v[154:157], v[216:219], v[76:79]
	s_setprio 0
	s_setprio 1
	v_mfma_f32_16x16x32_bf16 v[40:43], v[158:161], v[188:191], v[40:43]
	v_mfma_f32_16x16x32_bf16 v[36:39], v[166:169], v[188:191], v[36:39]
	v_mfma_f32_16x16x32_bf16 v[32:35], v[158:161], v[196:199], v[32:35]
	v_mfma_f32_16x16x32_bf16 v[28:31], v[166:169], v[196:199], v[28:31]
	v_mfma_f32_16x16x32_bf16 v[24:27], v[158:161], v[204:207], v[24:27]
	v_mfma_f32_16x16x32_bf16 v[20:23], v[166:169], v[204:207], v[20:23]
	v_mfma_f32_16x16x32_bf16 v[14:17], v[158:161], v[212:215], v[16:19]
	v_mfma_f32_16x16x32_bf16 v[10:13], v[166:169], v[212:215], v[10:13]
	s_add_i32 s68, s68, 2
	s_add_u32 s66, s66, 0x100
	s_addc_u32 s67, s67, 0
	s_cmp_gt_u32 s68, 13
	v_mfma_f32_16x16x32_bf16 v[40:43], v[162:165], v[192:195], v[40:43]
	v_mfma_f32_16x16x32_bf16 v[36:39], v[184:187], v[192:195], v[36:39]
	v_mfma_f32_16x16x32_bf16 v[32:35], v[162:165], v[200:203], v[32:35]
	v_mfma_f32_16x16x32_bf16 v[28:31], v[184:187], v[200:203], v[28:31]
	v_mfma_f32_16x16x32_bf16 v[24:27], v[162:165], v[208:211], v[24:27]
	v_mfma_f32_16x16x32_bf16 v[20:23], v[184:187], v[208:211], v[20:23]
	v_mfma_f32_16x16x32_bf16 v[16:19], v[162:165], v[216:219], v[14:17]
	v_mfma_f32_16x16x32_bf16 v[12:15], v[184:187], v[216:219], v[10:13]
	s_setprio 0
	s_barrier
	s_cbranch_scc1 .LBB13_1922
	s_mov_b64 s[40:41], s[6:7]
	s_cmp_lg_u32 s68, 6
	s_cbranch_scc0 .LBB13_1919
	s_branch .LBB13_1920

;     __device__ float mid(int row) const { return rg(row) / ra(row); }
; #define PG8_STAGE(bufoff, gbase, voff) do { const char* gb_ = (const char*)(gbase); asm volatile("" : "+s"(gb_));     \
;         _Pragma("unroll") for (int _i = 0; _i < 2; ++_i) \
;         __builtin_amdgcn_global_load_lds((const unsigned*)(gb_ + (voff)[_i]), (PG8_LAS unsigned*)(lds + (bufoff) + ldsw + _i * 8192), 16, 0, 0); } while (0)
; #define PG8_LDA(dst, b, h) do { _Pragma("unroll") for (int m = 0; m < 4; ++m) _Pragma("unroll") for (int k = 0; k < 2; ++k) dst[m][k] = *(const PG8_LAS bf16x8*)(lds + PG8_SA(b, h) + aoff + m * 2048 + k * 1024); } while (0)
; #define PG8_LDB(dst, b, h) do { _Pragma("unroll") for (int n = 0; n < 2; ++n) _Pragma("unroll") for (int k = 0; k < 2; ++k) dst[n][k] = *(const PG8_LAS bf16x8*)(lds + PG8_SB(b, h) + boff + n * 2048 + k * 1024); } while (0)
; #define PG8_WAIT_V(n) asm volatile("s_waitcnt vmcnt(" #n ")" ::: "memory")
; template <class Epi, class Sched, bool ALIGN_EPI = false, bool SP2 = false>
; __device__ __forceinline__ void gemm_phase(PG8_LAS unsigned char* lds, const Gemm g, const Sched& S, const Epi& E, int wid0) {
;     ...
;         for (int t = 0; t < nt; t += 2) {
;             const bool last = (t == nt - 2);
;             const char* a1 = cA + (size_t)(t + 1) * kstep;
;             const char* a2 = last ? nA : cA + (size_t)(t + 2) * kstep; const char* b2 = last ? nB : cB + (size_t)(t + 2) * kstep;
;             const char* a3 = a2 + kstep; const char* b3 = b2 + kstep;
;             if (last && has_next) S.a_ready(nxt);
;             if constexpr (Epi::HAS_MID) { if (t == Epi::MID_T) E.mid(acc, cur, wr, fr); }
;             unsigned vA_[2] = {voffA[0], voffA[1]}, vB_[2] = {voffB[0], voffB[1]};
;             asm volatile("" : "+v"(vA_[0]), "+v"(vA_[1]), "+v"(vB_[0]), "+v"(vB_[1]));
;             if constexpr (SP2) {
;             PG8_LDB(B0, 0, 0); PG8_LDB(B1, 0, 1); PG8_SCHED; PG8_LDA(At, 0, 0); PG8_STAGE(PG8_SA(1, 1), a1 + hstepA, vA_);
;             PG8_WAIT_V(8); PG8_WAIT_L(0); PG8_BAR; PG8_MMA(0, 0, At, B0); PG8_MMA(0, 1, At, B1); PG8_BAR; PG8_SCHED;
;             PG8_LDA(At, 0, 1); PG8_STAGE(PG8_SB(0, 0), b2, vB_); PG8_STAGE(PG8_SB(0, 1), b2 + hstep, vB_); PG8_STAGE(PG8_SA(0, 0), a2, vA_);
;             PG8_WAIT_V(8); PG8_WAIT_L(0); PG8_BAR; PG8_MMA(1, 0, At, B0); PG8_MMA(1, 1, At, B1); PG8_BAR; PG8_SCHED;
.LBB13_2163:
	v_mov_b32_e32 v202, v150
	v_mov_b32_e32 v203, v152
	v_mov_b32_e32 v204, v154
	v_mov_b32_e32 v205, v148
	ds_read_b128 v[128:131], v153
	ds_read_b128 v[132:135], v153 offset:1024
	ds_read_b128 v[136:139], v153 offset:2048
	ds_read_b128 v[140:143], v153 offset:3072
	ds_read_b128 v[144:147], v155
	ds_read_b128 v[158:161], v155 offset:1024
	ds_read_b128 v[162:165], v155 offset:2048
	ds_read_b128 v[166:169], v155 offset:3072
	s_add_u32 s26, s24, 0x100
	s_addc_u32 s27, s25, 0
	s_cmp_eq_u32 s53, 60
	s_cselect_b32 s34, s49, s26
	s_cselect_b32 s35, s11, s27
	s_cselect_b32 s30, s50, s51
	s_cselect_b32 s31, s13, s52
	s_add_u32 s28, s34, 0x80
	s_addc_u32 s29, s35, 0
	s_add_u32 s24, s24, 0x100080
	s_addc_u32 s25, s25, 0
	s_add_i32 m0, s21, 0xc000
	ds_read_b128 v[170:173], v156
	ds_read_b128 v[174:177], v156 offset:1024
	ds_read_b128 v[178:181], v156 offset:2048
	ds_read_b128 v[182:185], v156 offset:3072
	ds_read_b128 v[186:189], v156 offset:4096
	ds_read_b128 v[190:193], v156 offset:5120
	ds_read_b128 v[194:197], v156 offset:6144
	ds_read_b128 v[198:201], v156 offset:7168
	s_nop 0
	global_load_lds_dwordx4 v205, s[24:25]
	s_add_i32 m0, s21, 0xe000
	s_nop 0
	global_load_lds_dwordx4 v203, s[24:25]
	s_waitcnt vmcnt(8)
	s_waitcnt lgkmcnt(0)
	s_barrier
	s_setprio 1
	s_waitcnt lgkmcnt(0)
	v_mfma_f32_16x16x32_bf16 v[124:127], v[128:131], v[170:173], v[124:127]
	v_mfma_f32_16x16x32_bf16 v[120:123], v[136:139], v[170:173], v[120:123]
	v_mfma_f32_16x16x32_bf16 v[116:119], v[128:131], v[178:181], v[116:119]
	v_mfma_f32_16x16x32_bf16 v[112:115], v[136:139], v[178:181], v[112:115]
	v_mfma_f32_16x16x32_bf16 v[108:111], v[128:131], v[186:189], v[108:111]
	v_mfma_f32_16x16x32_bf16 v[104:107], v[136:139], v[186:189], v[104:107]
	v_mfma_f32_16x16x32_bf16 v[100:103], v[128:131], v[194:197], v[100:103]
	v_mfma_f32_16x16x32_bf16 v[96:99], v[136:139], v[194:197], v[96:99]
	v_mfma_f32_16x16x32_bf16 v[124:127], v[132:135], v[174:177], v[124:127]
	v_mfma_f32_16x16x32_bf16 v[120:123], v[140:143], v[174:177], v[120:123]
	v_mfma_f32_16x16x32_bf16 v[116:119], v[132:135], v[182:185], v[116:119]
	v_mfma_f32_16x16x32_bf16 v[112:115], v[140:143], v[182:185], v[112:115]
	v_mfma_f32_16x16x32_bf16 v[108:111], v[132:135], v[190:193], v[108:111]
	v_mfma_f32_16x16x32_bf16 v[104:107], v[140:143], v[190:193], v[104:107]
	v_mfma_f32_16x16x32_bf16 v[100:103], v[132:135], v[198:201], v[100:103]
	v_mfma_f32_16x16x32_bf16 v[96:99], v[140:143], v[198:201], v[96:99]
	s_setprio 0
	s_setprio 1
	v_mfma_f32_16x16x32_bf16 v[60:63], v[144:147], v[170:173], v[60:63]
	v_mfma_f32_16x16x32_bf16 v[56:59], v[162:165], v[170:173], v[56:59]
	v_mfma_f32_16x16x32_bf16 v[52:55], v[144:147], v[178:181], v[52:55]
	v_mfma_f32_16x16x32_bf16 v[48:51], v[162:165], v[178:181], v[48:51]
	v_mfma_f32_16x16x32_bf16 v[44:47], v[144:147], v[186:189], v[44:47]
	v_mfma_f32_16x16x32_bf16 v[40:43], v[162:165], v[186:189], v[40:43]
	v_mfma_f32_16x16x32_bf16 v[36:39], v[144:147], v[194:197], v[36:39]
	v_mfma_f32_16x16x32_bf16 v[32:35], v[162:165], v[194:197], v[32:35]
	v_mfma_f32_16x16x32_bf16 v[60:63], v[158:161], v[174:177], v[60:63]
	v_mfma_f32_16x16x32_bf16 v[56:59], v[166:169], v[174:177], v[56:59]
	v_mfma_f32_16x16x32_bf16 v[52:55], v[158:161], v[182:185], v[52:55]
	v_mfma_f32_16x16x32_bf16 v[48:51], v[166:169], v[182:185], v[48:51]
	v_mfma_f32_16x16x32_bf16 v[44:47], v[158:161], v[190:193], v[44:47]
	v_mfma_f32_16x16x32_bf16 v[40:43], v[166:169], v[190:193], v[40:43]
	v_mfma_f32_16x16x32_bf16 v[36:39], v[158:161], v[198:201], v[36:39]
	v_mfma_f32_16x16x32_bf16 v[32:35], v[166:169], v[198:201], v[32:35]
	s_setprio 0
	s_barrier
	s_add_i32 s54, s47, s33
	s_mov_b64 s[24:25], s[30:31]
	s_mov_b32 m0, s54
	ds_read_b128 v[170:173], v156 offset:16384
	ds_read_b128 v[174:177], v156 offset:17408
	ds_read_b128 v[178:181], v156 offset:18432
	ds_read_b128 v[182:185], v156 offset:19456
	ds_read_b128 v[186:189], v156 offset:20480
	ds_read_b128 v[190:193], v156 offset:21504
	ds_read_b128 v[194:197], v156 offset:22528
	ds_read_b128 v[198:201], v156 offset:23552
	s_nop 0
	global_load_lds_dwordx4 v202, s[24:25]
	s_add_i32 m0, s54, 0x2000
	s_nop 0
	global_load_lds_dwordx4 v204, s[24:25]
	s_add_u32 s24, s30, 0x100000
	s_addc_u32 s25, s31, 0
	s_add_i32 s54, s48, s33
	s_mov_b32 m0, s54
	s_nop 0
	global_load_lds_dwordx4 v202, s[24:25]
	s_add_i32 m0, s54, 0x2000
	s_nop 0
	global_load_lds_dwordx4 v204, s[24:25]
	s_mov_b64 s[24:25], s[34:35]
	s_mov_b32 m0, s21
	s_nop 0
	global_load_lds_dwordx4 v205, s[24:25]
	s_mov_b32 m0, s23
	s_nop 0
	global_load_lds_dwordx4 v203, s[24:25]
	s_waitcnt vmcnt(8)
	s_waitcnt lgkmcnt(0)
	s_barrier
; #define PG8_STAGE(bufoff, gbase, voff) do { const char* gb_ = (const char*)(gbase); asm volatile("" : "+s"(gb_));     \
;         _Pragma("unroll") for (int _i = 0; _i < 2; ++_i) \
;         __builtin_amdgcn_global_load_lds((const unsigned*)(gb_ + (voff)[_i]), (PG8_LAS unsigned*)(lds + (bufoff) + ldsw + _i * 8192), 16, 0, 0); } while (0)
; #define PG8_LDA(dst, b, h) do { _Pragma("unroll") for (int m = 0; m < 4; ++m) _Pragma("unroll") for (int k = 0; k < 2; ++k) dst[m][k] = *(const PG8_LAS bf16x8*)(lds + PG8_SA(b, h) + aoff + m * 2048 + k * 1024); } while (0)
; #define PG8_LDB(dst, b, h) do { _Pragma("unroll") for (int n = 0; n < 2; ++n) _Pragma("unroll") for (int k = 0; k < 2; ++k) dst[n][k] = *(const PG8_LAS bf16x8*)(lds + PG8_SB(b, h) + boff + n * 2048 + k * 1024); } while (0)
; #define PG8_MMA(ai, bj, At, Bt) do { __builtin_amdgcn_s_setprio(1); _Pragma("unroll") for (int m = 0; m < 4; ++m) _Pragma("unroll") for (int n = 0; n < 2; ++n) _Pragma("unroll") for (int k = 0; k < 2; ++k) \
;         acc[ai][bj][m][n] = __builtin_amdgcn_mfma_f32_16x16x32_bf16(Bt[n][k], At[m][k], acc[ai][bj][m][n], 0, 0, 0); __builtin_amdgcn_s_setprio(0); } while (0)
; #define PG8_WAIT_V(n) asm volatile("s_waitcnt vmcnt(" #n ")" ::: "memory")
; #define PG8_WAIT_L(n) asm volatile("s_waitcnt lgkmcnt(" #n ")" ::: "memory")
; #define PG8_BAR __builtin_amdgcn_s_barrier()
; #define PG8_SCHED __builtin_amdgcn_sched_barrier(0)
; template <class Epi, class Sched, bool ALIGN_EPI = false, bool SP2 = false>
; __device__ __forceinline__ void gemm_phase(PG8_LAS unsigned char* lds, const Gemm g, const Sched& S, const Epi& E, int wid0) {
;     ...
;             PG8_WAIT_V(8); PG8_WAIT_L(0); PG8_BAR; PG8_MMA(1, 0, At, B0); PG8_MMA(1, 1, At, B1); PG8_BAR; PG8_SCHED;
;             PG8_LDB(B0, 1, 0); PG8_LDB(B1, 1, 1); PG8_SCHED; PG8_LDA(At, 1, 0); PG8_STAGE(PG8_SA(0, 1), a2 + hstepA, vA_);
;             PG8_WAIT_V(8); PG8_WAIT_L(0); PG8_BAR; PG8_MMA(0, 0, At, B0); PG8_MMA(0, 1, At, B1); PG8_BAR; PG8_SCHED;
	s_setprio 1
	s_waitcnt lgkmcnt(0)
	v_mfma_f32_16x16x32_bf16 v[92:95], v[128:131], v[170:173], v[92:95]
	v_mfma_f32_16x16x32_bf16 v[88:91], v[136:139], v[170:173], v[88:91]
	v_mfma_f32_16x16x32_bf16 v[84:87], v[128:131], v[178:181], v[84:87]
	v_mfma_f32_16x16x32_bf16 v[80:83], v[136:139], v[178:181], v[80:83]
	v_mfma_f32_16x16x32_bf16 v[76:79], v[128:131], v[186:189], v[76:79]
	v_mfma_f32_16x16x32_bf16 v[72:75], v[136:139], v[186:189], v[72:75]
	v_mfma_f32_16x16x32_bf16 v[68:71], v[128:131], v[194:197], v[68:71]
	v_mfma_f32_16x16x32_bf16 v[64:67], v[136:139], v[194:197], v[64:67]
	v_mfma_f32_16x16x32_bf16 v[92:95], v[132:135], v[174:177], v[92:95]
	v_mfma_f32_16x16x32_bf16 v[88:91], v[140:143], v[174:177], v[88:91]
	v_mfma_f32_16x16x32_bf16 v[84:87], v[132:135], v[182:185], v[84:87]
	v_mfma_f32_16x16x32_bf16 v[80:83], v[140:143], v[182:185], v[80:83]
	v_mfma_f32_16x16x32_bf16 v[76:79], v[132:135], v[190:193], v[76:79]
	v_mfma_f32_16x16x32_bf16 v[72:75], v[140:143], v[190:193], v[72:75]
	v_mfma_f32_16x16x32_bf16 v[68:71], v[132:135], v[198:201], v[68:71]
	v_mfma_f32_16x16x32_bf16 v[64:67], v[140:143], v[198:201], v[64:67]
	s_setprio 0
	s_setprio 1
	v_mfma_f32_16x16x32_bf16 v[28:31], v[144:147], v[170:173], v[28:31]
	v_mfma_f32_16x16x32_bf16 v[24:27], v[162:165], v[170:173], v[24:27]
	v_mfma_f32_16x16x32_bf16 v[20:23], v[144:147], v[178:181], v[20:23]
	v_mfma_f32_16x16x32_bf16 v[16:19], v[162:165], v[178:181], v[16:19]
	v_mfma_f32_16x16x32_bf16 v[12:15], v[144:147], v[186:189], v[12:15]
	v_mfma_f32_16x16x32_bf16 v[8:11], v[162:165], v[186:189], v[8:11]
	v_mfma_f32_16x16x32_bf16 v[4:7], v[144:147], v[194:197], v[4:7]
	v_mfma_f32_16x16x32_bf16 v[0:3], v[162:165], v[194:197], v[0:3]
	v_mfma_f32_16x16x32_bf16 v[28:31], v[158:161], v[174:177], v[28:31]
	v_mfma_f32_16x16x32_bf16 v[24:27], v[166:169], v[174:177], v[24:27]
	v_mfma_f32_16x16x32_bf16 v[20:23], v[158:161], v[182:185], v[20:23]
	v_mfma_f32_16x16x32_bf16 v[16:19], v[166:169], v[182:185], v[16:19]
	v_mfma_f32_16x16x32_bf16 v[12:15], v[158:161], v[190:193], v[12:15]
	v_mfma_f32_16x16x32_bf16 v[8:11], v[166:169], v[190:193], v[8:11]
	v_mfma_f32_16x16x32_bf16 v[4:7], v[158:161], v[198:201], v[4:7]
	v_mfma_f32_16x16x32_bf16 v[0:3], v[166:169], v[198:201], v[0:3]
	s_setprio 0
	s_barrier
	s_add_i32 s54, 0, 0x18000
	s_add_i32 s55, 0, 0x1c000
	v_add_u32_e32 v140, s54, v149
	v_add_u32_e32 v166, s55, v149
	ds_read_b128 v[128:131], v140
	ds_read_b128 v[132:135], v140 offset:1024
	ds_read_b128 v[136:139], v140 offset:2048
	ds_read_b128 v[140:143], v140 offset:3072
	ds_read_b128 v[144:147], v166
	ds_read_b128 v[158:161], v166 offset:1024
	ds_read_b128 v[162:165], v166 offset:2048
	ds_read_b128 v[166:169], v166 offset:3072
	s_add_u32 s24, s34, 0x100000
	s_addc_u32 s25, s35, 0
	s_mov_b32 m0, s40
	ds_read_b128 v[170:173], v156 offset:32768
	ds_read_b128 v[174:177], v156 offset:33792
	ds_read_b128 v[178:181], v156 offset:34816
	ds_read_b128 v[182:185], v156 offset:35840
	ds_read_b128 v[186:189], v156 offset:36864
	ds_read_b128 v[190:193], v156 offset:37888
	ds_read_b128 v[194:197], v156 offset:38912
	ds_read_b128 v[198:201], v156 offset:39936
	s_nop 0
	global_load_lds_dwordx4 v205, s[24:25]
	s_mov_b32 m0, s41
	s_nop 0
	global_load_lds_dwordx4 v203, s[24:25]
	s_waitcnt vmcnt(8)
	s_waitcnt lgkmcnt(0)
	s_barrier
	s_setprio 1
	s_waitcnt lgkmcnt(0)
	v_mfma_f32_16x16x32_bf16 v[124:127], v[128:131], v[170:173], v[124:127]
	v_mfma_f32_16x16x32_bf16 v[120:123], v[136:139], v[170:173], v[120:123]
	v_mfma_f32_16x16x32_bf16 v[116:119], v[128:131], v[178:181], v[116:119]
	v_mfma_f32_16x16x32_bf16 v[112:115], v[136:139], v[178:181], v[112:115]
	v_mfma_f32_16x16x32_bf16 v[108:111], v[128:131], v[186:189], v[108:111]
	v_mfma_f32_16x16x32_bf16 v[104:107], v[136:139], v[186:189], v[104:107]
	v_mfma_f32_16x16x32_bf16 v[100:103], v[128:131], v[194:197], v[100:103]
	v_mfma_f32_16x16x32_bf16 v[96:99], v[136:139], v[194:197], v[96:99]
	v_mfma_f32_16x16x32_bf16 v[124:127], v[132:135], v[174:177], v[124:127]
	v_mfma_f32_16x16x32_bf16 v[120:123], v[140:143], v[174:177], v[120:123]
	v_mfma_f32_16x16x32_bf16 v[116:119], v[132:135], v[182:185], v[116:119]
	v_mfma_f32_16x16x32_bf16 v[112:115], v[140:143], v[182:185], v[112:115]
	v_mfma_f32_16x16x32_bf16 v[108:111], v[132:135], v[190:193], v[108:111]
	v_mfma_f32_16x16x32_bf16 v[104:107], v[140:143], v[190:193], v[104:107]
	v_mfma_f32_16x16x32_bf16 v[100:103], v[132:135], v[198:201], v[100:103]
	v_mfma_f32_16x16x32_bf16 v[96:99], v[140:143], v[198:201], v[96:99]
	s_setprio 0
	s_setprio 1
	v_mfma_f32_16x16x32_bf16 v[60:63], v[144:147], v[170:173], v[60:63]
	v_mfma_f32_16x16x32_bf16 v[56:59], v[162:165], v[170:173], v[56:59]
	v_mfma_f32_16x16x32_bf16 v[52:55], v[144:147], v[178:181], v[52:55]
	v_mfma_f32_16x16x32_bf16 v[48:51], v[162:165], v[178:181], v[48:51]
	v_mfma_f32_16x16x32_bf16 v[44:47], v[144:147], v[186:189], v[44:47]
	v_mfma_f32_16x16x32_bf16 v[40:43], v[162:165], v[186:189], v[40:43]
	v_mfma_f32_16x16x32_bf16 v[36:39], v[144:147], v[194:197], v[36:39]
	v_mfma_f32_16x16x32_bf16 v[32:35], v[162:165], v[194:197], v[32:35]
	v_mfma_f32_16x16x32_bf16 v[60:63], v[158:161], v[174:177], v[60:63]
	v_mfma_f32_16x16x32_bf16 v[56:59], v[166:169], v[174:177], v[56:59]
	v_mfma_f32_16x16x32_bf16 v[52:55], v[158:161], v[182:185], v[52:55]
	v_mfma_f32_16x16x32_bf16 v[48:51], v[166:169], v[182:185], v[48:51]
	v_mfma_f32_16x16x32_bf16 v[44:47], v[158:161], v[190:193], v[44:47]
	v_mfma_f32_16x16x32_bf16 v[40:43], v[166:169], v[190:193], v[40:43]
	v_mfma_f32_16x16x32_bf16 v[36:39], v[158:161], v[198:201], v[36:39]
	v_mfma_f32_16x16x32_bf16 v[32:35], v[166:169], v[198:201], v[32:35]
	s_setprio 0
	s_barrier
;     __device__ float mid(int row) const { return rg(row) / ra(row); }
; #define PG8_STAGE(bufoff, gbase, voff) do { const char* gb_ = (const char*)(gbase); asm volatile("" : "+s"(gb_));     \
;         _Pragma("unroll") for (int _i = 0; _i < 2; ++_i) \
;         __builtin_amdgcn_global_load_lds((const unsigned*)(gb_ + (voff)[_i]), (PG8_LAS unsigned*)(lds + (bufoff) + ldsw + _i * 8192), 16, 0, 0); } while (0)
; #define PG8_BAR __builtin_amdgcn_s_barrier()
; template <class Epi, class Sched, bool ALIGN_EPI = false, bool SP2 = false>
; __device__ __forceinline__ void gemm_phase(PG8_LAS unsigned char* lds, const Gemm g, const Sched& S, const Epi& E, int wid0) {
;     ...
;         for (int t = 0; t < nt; t += 2) {
;             const bool last = (t == nt - 2);
;             const char* a1 = cA + (size_t)(t + 1) * kstep;
;             const char* a2 = last ? nA : cA + (size_t)(t + 2) * kstep; const char* b2 = last ? nB : cB + (size_t)(t + 2) * kstep;
;             const char* a3 = a2 + kstep; const char* b3 = b2 + kstep;
;             if (last && has_next) S.a_ready(nxt);
;             if constexpr (Epi::HAS_MID) { if (t == Epi::MID_T) E.mid(acc, cur, wr, fr); }
;             unsigned vA_[2] = {voffA[0], voffA[1]}, vB_[2] = {voffB[0], voffB[1]};
;             asm volatile("" : "+v"(vA_[0]), "+v"(vA_[1]), "+v"(vB_[0]), "+v"(vB_[1]));
;             if constexpr (SP2) {
;             PG8_LDB(B0, 0, 0); PG8_LDB(B1, 0, 1); PG8_SCHED; PG8_LDA(At, 0, 0); PG8_STAGE(PG8_SA(1, 1), a1 + hstepA, vA_);
;             PG8_WAIT_V(8); PG8_WAIT_L(0); PG8_BAR; PG8_MMA(0, 0, At, B0); PG8_MMA(0, 1, At, B1); PG8_BAR; PG8_SCHED;
;             PG8_LDA(At, 0, 1); PG8_STAGE(PG8_SB(0, 0), b2, vB_); PG8_STAGE(PG8_SB(0, 1), b2 + hstep, vB_); PG8_STAGE(PG8_SA(0, 0), a2, vA_);
;             PG8_WAIT_V(8); PG8_WAIT_L(0); PG8_BAR; PG8_MMA(1, 0, At, B0); PG8_MMA(1, 1, At, B1); PG8_BAR; PG8_SCHED;
;             PG8_LDB(B0, 1, 0); PG8_LDB(B1, 1, 1); PG8_SCHED; PG8_LDA(At, 1, 0); PG8_STAGE(PG8_SA(0, 1), a2 + hstepA, vA_);
;             PG8_WAIT_V(8); PG8_WAIT_L(0); PG8_BAR; PG8_MMA(0, 0, At, B0); PG8_MMA(0, 1, At, B1); PG8_BAR; PG8_SCHED;
;             PG8_LDA(At, 1, 1); PG8_STAGE(PG8_SB(1, 0), b3, vB_); PG8_STAGE(PG8_SB(1, 1), b3 + hstep, vB_); PG8_STAGE(PG8_SA(1, 0), a3, vA_);
;             PG8_WAIT_V(8); PG8_WAIT_L(0); PG8_BAR; PG8_MMA(1, 0, At, B0); PG8_MMA(1, 1, At, B1); PG8_BAR; PG8_SCHED;
	s_add_u32 s24, s30, 0x80
	s_addc_u32 s25, s31, 0
	s_add_i32 s34, s54, s33
	s_mov_b32 m0, s34
	ds_read_b128 v[170:173], v156 offset:49152
	ds_read_b128 v[174:177], v156 offset:50176
	ds_read_b128 v[178:181], v156 offset:51200
	ds_read_b128 v[182:185], v156 offset:52224
	ds_read_b128 v[186:189], v156 offset:53248
	ds_read_b128 v[190:193], v156 offset:54272
	ds_read_b128 v[194:197], v156 offset:55296
	ds_read_b128 v[198:201], v156 offset:56320
	s_nop 0
	global_load_lds_dwordx4 v202, s[24:25]
	s_add_i32 m0, s34, 0x2000
	s_nop 0
	global_load_lds_dwordx4 v204, s[24:25]
	s_add_u32 s24, s30, 0x100080
	s_addc_u32 s25, s31, 0
	s_add_i32 s30, s55, s33
	s_mov_b32 m0, s30
	s_nop 0
	global_load_lds_dwordx4 v202, s[24:25]
	s_add_i32 m0, s30, 0x2000
	s_nop 0
	global_load_lds_dwordx4 v204, s[24:25]
	s_mov_b32 m0, s45
	s_nop 0
	global_load_lds_dwordx4 v205, s[28:29]
	s_mov_b32 m0, s46
	s_nop 0
	global_load_lds_dwordx4 v203, s[28:29]
	s_waitcnt vmcnt(8)
	s_waitcnt lgkmcnt(0)
	s_barrier
	s_setprio 1
	s_waitcnt lgkmcnt(0)
	v_mfma_f32_16x16x32_bf16 v[92:95], v[128:131], v[170:173], v[92:95]
	v_mfma_f32_16x16x32_bf16 v[88:91], v[136:139], v[170:173], v[88:91]
	v_mfma_f32_16x16x32_bf16 v[84:87], v[128:131], v[178:181], v[84:87]
	v_mfma_f32_16x16x32_bf16 v[80:83], v[136:139], v[178:181], v[80:83]
	v_mfma_f32_16x16x32_bf16 v[76:79], v[128:131], v[186:189], v[76:79]
	v_mfma_f32_16x16x32_bf16 v[72:75], v[136:139], v[186:189], v[72:75]
	v_mfma_f32_16x16x32_bf16 v[68:71], v[128:131], v[194:197], v[68:71]
	v_mfma_f32_16x16x32_bf16 v[64:67], v[136:139], v[194:197], v[64:67]
	v_mfma_f32_16x16x32_bf16 v[92:95], v[132:135], v[174:177], v[92:95]
	v_mfma_f32_16x16x32_bf16 v[88:91], v[140:143], v[174:177], v[88:91]
	v_mfma_f32_16x16x32_bf16 v[84:87], v[132:135], v[182:185], v[84:87]
	v_mfma_f32_16x16x32_bf16 v[80:83], v[140:143], v[182:185], v[80:83]
	v_mfma_f32_16x16x32_bf16 v[76:79], v[132:135], v[190:193], v[76:79]
	v_mfma_f32_16x16x32_bf16 v[72:75], v[140:143], v[190:193], v[72:75]
	v_mfma_f32_16x16x32_bf16 v[68:71], v[132:135], v[198:201], v[68:71]
	v_mfma_f32_16x16x32_bf16 v[64:67], v[140:143], v[198:201], v[64:67]
	s_setprio 0
	s_setprio 1
	v_mfma_f32_16x16x32_bf16 v[28:31], v[144:147], v[170:173], v[28:31]
	v_mfma_f32_16x16x32_bf16 v[24:27], v[162:165], v[170:173], v[24:27]
	v_mfma_f32_16x16x32_bf16 v[20:23], v[144:147], v[178:181], v[20:23]
	v_mfma_f32_16x16x32_bf16 v[16:19], v[162:165], v[178:181], v[16:19]
	v_mfma_f32_16x16x32_bf16 v[12:15], v[144:147], v[186:189], v[12:15]
	v_mfma_f32_16x16x32_bf16 v[8:11], v[162:165], v[186:189], v[8:11]
	v_mfma_f32_16x16x32_bf16 v[4:7], v[144:147], v[194:197], v[4:7]
	v_mfma_f32_16x16x32_bf16 v[0:3], v[162:165], v[194:197], v[0:3]
	s_add_i32 s53, s53, 2
	s_add_u32 s51, s51, 0x100
	s_addc_u32 s52, s52, 0
	s_cmp_gt_u32 s53, 61
	s_mov_b64 s[24:25], s[26:27]
	v_mfma_f32_16x16x32_bf16 v[28:31], v[158:161], v[174:177], v[28:31]
	v_mfma_f32_16x16x32_bf16 v[24:27], v[166:169], v[174:177], v[24:27]
	v_mfma_f32_16x16x32_bf16 v[20:23], v[158:161], v[182:185], v[20:23]
	v_mfma_f32_16x16x32_bf16 v[16:19], v[166:169], v[182:185], v[16:19]
	v_mfma_f32_16x16x32_bf16 v[12:15], v[158:161], v[190:193], v[12:15]
	v_mfma_f32_16x16x32_bf16 v[8:11], v[166:169], v[190:193], v[8:11]
	v_mfma_f32_16x16x32_bf16 v[4:7], v[158:161], v[198:201], v[4:7]
	v_mfma_f32_16x16x32_bf16 v[0:3], v[166:169], v[198:201], v[0:3]
	s_setprio 0
	s_barrier
	s_cbranch_scc0 .LBB13_2163
	s_and_b64 vcc, exec, s[8:9]
	s_cbranch_vccz .LBB13_2166
	s_barrier
